# MIX epilogue+weight-prep restructure (loads batched, counted waits) and counted vmcnt(6) instead of vmcnt(0) at GEMM epilogue start
# baseline (speedup 1.0000x reference)
.LBB0_135:
	s_waitcnt lgkmcnt(0)
	v_mov_b32_e32 v2, v0
	v_mov_b32_e32 v3, v0
	v_mov_b32_e32 v1, v0
	v_mov_b32_e32 v75, 0
	v_mov_b64_e32 v[130:131], v[2:3]
	v_mov_b64_e32 v[126:127], v[2:3]
	v_mov_b64_e32 v[114:115], v[2:3]
	v_mov_b64_e32 v[110:111], v[2:3]
	v_mov_b64_e32 v[98:99], v[2:3]
	v_mov_b64_e32 v[94:95], v[2:3]
	v_mov_b64_e32 v[82:83], v[2:3]
	v_mov_b64_e32 v[78:79], v[2:3]
	v_mov_b64_e32 v[122:123], v[2:3]
	v_mov_b64_e32 v[118:119], v[2:3]
	v_mov_b64_e32 v[106:107], v[2:3]
	v_mov_b64_e32 v[102:103], v[2:3]
	v_mov_b64_e32 v[90:91], v[2:3]
	v_mov_b64_e32 v[86:87], v[2:3]
	v_mov_b64_e32 v[14:15], v[2:3]
	v_mov_b64_e32 v[10:11], v[2:3]
	v_mov_b32_e32 v74, v75
	v_mov_b32_e32 v73, v75
	v_mov_b32_e32 v72, v75
	v_mov_b32_e32 v71, v75
	v_mov_b32_e32 v70, v75
	v_mov_b32_e32 v69, v75
	v_mov_b32_e32 v68, v75
	v_mov_b32_e32 v59, v75
	v_mov_b32_e32 v58, v75
	v_mov_b32_e32 v57, v75
	v_mov_b32_e32 v56, v75
	v_mov_b32_e32 v55, v75
	v_mov_b32_e32 v54, v75
	v_mov_b32_e32 v53, v75
	v_mov_b32_e32 v52, v75
	v_mov_b32_e32 v43, v75
	v_mov_b32_e32 v42, v75
	v_mov_b32_e32 v41, v75
	v_mov_b32_e32 v40, v75
	v_mov_b32_e32 v39, v75
	v_mov_b32_e32 v38, v75
	v_mov_b32_e32 v37, v75
	v_mov_b32_e32 v36, v75
	v_mov_b32_e32 v27, v75
	v_mov_b32_e32 v26, v75
	v_mov_b32_e32 v25, v75
	v_mov_b32_e32 v24, v75
	v_mov_b32_e32 v23, v75
	v_mov_b32_e32 v22, v75
	v_mov_b32_e32 v21, v75
	v_mov_b32_e32 v20, v75
	v_mov_b32_e32 v67, v75
	v_mov_b32_e32 v66, v75
	v_mov_b32_e32 v65, v75
	v_mov_b32_e32 v64, v75
	v_mov_b32_e32 v63, v75
	v_mov_b32_e32 v62, v75
	v_mov_b32_e32 v61, v75
	v_mov_b32_e32 v60, v75
	v_mov_b32_e32 v51, v75
	v_mov_b32_e32 v50, v75
	v_mov_b32_e32 v49, v75
	v_mov_b32_e32 v48, v75
	v_mov_b32_e32 v47, v75
	v_mov_b32_e32 v46, v75
	v_mov_b32_e32 v45, v75
	v_mov_b32_e32 v44, v75
	v_mov_b32_e32 v35, v75
	v_mov_b32_e32 v34, v75
	v_mov_b32_e32 v33, v75
	v_mov_b32_e32 v32, v75
	v_mov_b32_e32 v31, v75
	v_mov_b32_e32 v30, v75
	v_mov_b32_e32 v29, v75
	v_mov_b32_e32 v28, v75
	v_mov_b32_e32 v19, v75
	v_mov_b32_e32 v18, v75
	v_mov_b32_e32 v17, v75
	v_mov_b32_e32 v16, v75
	v_mov_b32_e32 v7, v75
	v_mov_b32_e32 v6, v75
	v_mov_b32_e32 v5, v75
	v_mov_b32_e32 v4, v75
	v_mov_b64_e32 v[128:129], v[0:1]
	v_mov_b64_e32 v[124:125], v[0:1]
	v_mov_b64_e32 v[112:113], v[0:1]
	v_mov_b64_e32 v[108:109], v[0:1]
	v_mov_b64_e32 v[96:97], v[0:1]
	v_mov_b64_e32 v[92:93], v[0:1]
	v_mov_b64_e32 v[80:81], v[0:1]
	v_mov_b64_e32 v[76:77], v[0:1]
	v_mov_b64_e32 v[120:121], v[0:1]
	v_mov_b64_e32 v[116:117], v[0:1]
	v_mov_b64_e32 v[104:105], v[0:1]
	v_mov_b64_e32 v[100:101], v[0:1]
	v_mov_b64_e32 v[88:89], v[0:1]
	v_mov_b64_e32 v[84:85], v[0:1]
	v_mov_b64_e32 v[12:13], v[0:1]
	v_mov_b64_e32 v[8:9], v[0:1]
	s_waitcnt vmcnt(0)
.LBB0_136:
	s_lshl_b32 s4, s18, 8
	s_cmp_lg_u32 s38, 64
	s_mov_b64 s[8:9], -1
	s_cbranch_scc0 .LBB0_170
	s_waitcnt vmcnt(6)
	v_fmamk_f32 v1, v244, 0x3a800000, v233
	v_mul_f32_e32 v3, 0x4b800000, v1
	v_cmp_gt_f32_e32 vcc, s61, v1
	s_add_i32 s1, s4, 0xfffff800
	s_cmp_gt_i32 s18, 7
	v_cndmask_b32_e32 v1, v1, v3, vcc
	v_rsq_f32_e32 v1, v1
	s_cselect_b64 s[40:41], -1, 0
	s_and_b64 s[8:9], s[40:41], exec
	s_cselect_b32 s2, s60, 0xdae7300
	s_cselect_b32 s1, s1, s4
	s_add_u32 s8, s82, s2
	v_or_b32_e32 v2, s1, v205
	v_lshl_add_u32 v132, s38, 8, v204
	v_mul_f32_e32 v133, 0x45800000, v1
	s_addc_u32 s9, s83, 0
	v_ashrrev_i32_e32 v3, 31, v2
	v_cndmask_b32_e32 v146, v1, v133, vcc
	v_ashrrev_i32_e32 v133, 31, v132
	v_lshl_add_u64 v[2:3], v[2:3], 1, s[8:9]
	v_lshlrev_b64 v[134:135], 12, v[132:133]
	v_lshl_add_u64 v[154:155], v[2:3], 0, v[134:135]
	v_pk_mul_f32 v[134:135], v[146:147], v[72:73] op_sel_hi:[0,1]
	v_pk_mul_f32 v[136:137], v[146:147], v[68:69] op_sel_hi:[0,1]
	v_mul_f32_e32 v1, 0x3d372713, v134
	v_mul_f32_e32 v138, 0x3d372713, v136
	v_mul_f32_e32 v139, 0x3d372713, v135
	v_fma_f32 v1, v134, v1, 1.0
	v_fma_f32 v138, v136, v138, 1.0
	v_fma_f32 v139, v135, v139, 1.0
	v_mul_f32_e32 v1, v134, v1
	v_mul_f32_e32 v138, v136, v138
	v_mul_f32_e32 v139, v135, v139
	v_mul_f32_e32 v1, 0xc0135761, v1
	v_mul_f32_e32 v138, 0xc0135761, v138
	v_mul_f32_e32 v139, 0xc0135761, v139
	v_exp_f32_e32 v1, v1
	v_exp_f32_e32 v138, v138
	v_exp_f32_e32 v139, v139
	v_mul_f32_e32 v144, 0x3d372713, v137
	v_add_f32_e32 v1, 1.0, v1
	v_add_f32_e32 v138, 1.0, v138
	v_add_f32_e32 v139, 1.0, v139
	v_rcp_f32_e32 v1, v1
	v_rcp_f32_e32 v138, v138
	v_rcp_f32_e32 v139, v139
	v_fma_f32 v144, v137, v144, 1.0
	v_mul_f32_e32 v144, v137, v144
	v_mul_f32_e32 v144, 0xc0135761, v144
	v_pk_mul_f32 v[140:141], v[146:147], v[74:75] op_sel_hi:[0,1]
	v_pk_mul_f32 v[142:143], v[146:147], v[70:71] op_sel_hi:[0,1]
	v_exp_f32_e32 v144, v144
	v_mul_f32_e32 v134, v134, v1
	v_mul_f32_e32 v1, v136, v138
	v_mul_f32_e32 v135, v135, v139
	v_mul_f32_e32 v138, 0x3d372713, v140
	v_mul_f32_e32 v139, 0x3d372713, v142
	v_fma_f32 v138, v140, v138, 1.0
	v_fma_f32 v139, v142, v139, 1.0
	v_mul_f32_e32 v138, v140, v138
	v_mul_f32_e32 v139, v142, v139
	v_add_f32_e32 v136, 1.0, v144
	v_mul_f32_e32 v138, 0xc0135761, v138
	v_mul_f32_e32 v139, 0xc0135761, v139
	v_rcp_f32_e32 v136, v136
	v_exp_f32_e32 v138, v138
	v_exp_f32_e32 v139, v139
	v_mul_f32_e32 v144, 0x3d372713, v143
	v_mul_f32_e32 v136, v137, v136
	v_add_f32_e32 v137, 1.0, v138
	v_add_f32_e32 v138, 1.0, v139
	v_mul_f32_e32 v139, 0x3d372713, v141
	v_fma_f32 v139, v141, v139, 1.0
	v_mul_f32_e32 v139, v141, v139
	v_fma_f32 v144, v143, v144, 1.0
	v_mul_f32_e32 v139, 0xc0135761, v139
	v_mul_f32_e32 v144, v143, v144
	v_exp_f32_e32 v139, v139
	v_mul_f32_e32 v144, 0xc0135761, v144
	v_exp_f32_e32 v144, v144
	v_rcp_f32_e32 v137, v137
	v_add_f32_e32 v139, 1.0, v139
	v_rcp_f32_e32 v145, v139
	v_add_f32_e32 v139, 1.0, v144
	v_rcp_f32_e32 v138, v138
	v_rcp_f32_e32 v144, v139
	v_mul_f32_e32 v139, v140, v137
	v_mul_f32_e32 v140, v141, v145
	v_mul_f32_e32 v137, v142, v138
	v_mul_f32_e32 v138, v143, v144
	v_cvt_pk_bf16_f32 v142, v134, v135
	v_cvt_pk_bf16_f32 v143, v139, v140
	v_cvt_pk_bf16_f32 v144, v1, v136
	v_cvt_pk_bf16_f32 v145, v137, v138
	global_store_dwordx4 v[154:155], v[142:145], off
	v_pk_mul_f32 v[148:149], v[146:147], v[66:67] op_sel_hi:[0,1]
	v_pk_mul_f32 v[150:151], v[146:147], v[62:63] op_sel_hi:[0,1]
	v_pk_mul_f32 v[142:143], v[146:147], v[64:65] op_sel_hi:[0,1]
	v_pk_mul_f32 v[144:145], v[146:147], v[60:61] op_sel_hi:[0,1]
	v_mul_f32_e32 v141, 0x3d372713, v142
	v_mul_f32_e32 v146, 0x3d372713, v144
	v_mul_f32_e32 v147, 0x3d372713, v143
	v_fma_f32 v141, v142, v141, 1.0
	v_fma_f32 v146, v144, v146, 1.0
	v_fma_f32 v147, v143, v147, 1.0
	v_mul_f32_e32 v141, v142, v141
	v_mul_f32_e32 v146, v144, v146
	v_mul_f32_e32 v147, v143, v147
	v_mul_f32_e32 v141, 0xc0135761, v141
	v_mul_f32_e32 v146, 0xc0135761, v146
	v_mul_f32_e32 v147, 0xc0135761, v147
	v_exp_f32_e32 v141, v141
	v_exp_f32_e32 v146, v146
	v_exp_f32_e32 v147, v147
	v_mul_f32_e32 v152, 0x3d372713, v145
	v_add_f32_e32 v141, 1.0, v141
	v_add_f32_e32 v146, 1.0, v146
	v_add_f32_e32 v147, 1.0, v147
	v_rcp_f32_e32 v141, v141
	v_rcp_f32_e32 v146, v146
	v_rcp_f32_e32 v147, v147
	v_fma_f32 v152, v145, v152, 1.0
	v_mul_f32_e32 v152, v145, v152
	v_mul_f32_e32 v152, 0xc0135761, v152
	v_exp_f32_e32 v152, v152
	v_mul_f32_e32 v142, v142, v141
	v_mul_f32_e32 v141, v144, v146
	v_mul_f32_e32 v143, v143, v147
	v_mul_f32_e32 v146, 0x3d372713, v148
	v_mul_f32_e32 v147, 0x3d372713, v150
	v_fma_f32 v146, v148, v146, 1.0
	v_fma_f32 v147, v150, v147, 1.0
	v_mul_f32_e32 v146, v148, v146
	v_mul_f32_e32 v147, v150, v147
	v_add_f32_e32 v144, 1.0, v152
	v_mul_f32_e32 v146, 0xc0135761, v146
	v_mul_f32_e32 v147, 0xc0135761, v147
	v_rcp_f32_e32 v144, v144
	v_exp_f32_e32 v146, v146
	v_exp_f32_e32 v147, v147
	v_mul_f32_e32 v152, 0x3d372713, v151
	v_mul_f32_e32 v144, v145, v144
	v_add_f32_e32 v145, 1.0, v146
	v_add_f32_e32 v146, 1.0, v147
	v_mul_f32_e32 v147, 0x3d372713, v149
	v_fma_f32 v147, v149, v147, 1.0
	v_mul_f32_e32 v147, v149, v147
	v_fma_f32 v152, v151, v152, 1.0
	v_mul_f32_e32 v147, 0xc0135761, v147
	v_mul_f32_e32 v152, v151, v152
	v_exp_f32_e32 v147, v147
	v_mul_f32_e32 v152, 0xc0135761, v152
	v_exp_f32_e32 v152, v152
	v_rcp_f32_e32 v145, v145
	v_add_f32_e32 v147, 1.0, v147
	v_rcp_f32_e32 v153, v147
	v_add_f32_e32 v147, 1.0, v152
	v_rcp_f32_e32 v146, v146
	v_rcp_f32_e32 v152, v147
	s_cmp_lt_i32 s18, 8
	v_mul_f32_e32 v147, v148, v145
	v_mul_f32_e32 v145, v150, v146
	v_mul_f32_e32 v148, v149, v153
	v_mul_f32_e32 v146, v151, v152
	v_cvt_pk_bf16_f32 v150, v142, v143
	v_cvt_pk_bf16_f32 v151, v147, v148
	v_cvt_pk_bf16_f32 v152, v141, v144
	v_cvt_pk_bf16_f32 v153, v145, v146
	global_store_dwordx4 v[154:155], v[150:153], off offset:256
	s_cbranch_scc1 .LBB0_141
	v_mul_f32_e32 v135, v135, v135
	v_fmac_f32_e32 v135, v134, v134
	v_mul_f32_e32 v134, v140, v140
	v_fmac_f32_e32 v134, v139, v139
	v_add_f32_e32 v134, v135, v134
	v_mul_f32_e32 v135, v136, v136
	v_fmac_f32_e32 v135, v1, v1
	v_mul_f32_e32 v1, v138, v138
	v_fmac_f32_e32 v1, v137, v137
	v_add_f32_e32 v1, v135, v1
	v_add_f32_e32 v1, v1, v134
	v_mul_f32_e32 v134, v143, v143
	v_mul_f32_e32 v135, v148, v148
	v_fmac_f32_e32 v134, v142, v142
	v_fmac_f32_e32 v135, v147, v147
	v_add_f32_e32 v134, v134, v135
	v_mul_f32_e32 v135, v144, v144
	v_mul_f32_e32 v136, v146, v146
	v_fmac_f32_e32 v135, v141, v141
	v_fmac_f32_e32 v136, v145, v145
	v_add_f32_e32 v135, v135, v136
	v_add_f32_e32 v134, v135, v134
	v_add_f32_e32 v1, v134, v1
	ds_bpermute_b32 v134, v231, v1
	s_waitcnt lgkmcnt(0)
	v_add_f32_e32 v1, v1, v134
	ds_bpermute_b32 v134, v232, v1
	s_and_saveexec_b64 s[8:9], s[6:7]
	s_cbranch_execz .LBB0_140
	s_lshl_b32 s1, s18, 2
	v_readlane_b32 s42, v255, 22
	s_waitcnt lgkmcnt(0)
	v_add_f32_e32 v1, v1, v134
	s_sub_i32 s38, s1, 32
	v_lshlrev_b64 v[134:135], 7, v[132:133]
	v_readlane_b32 s43, v255, 23
	s_ashr_i32 s39, s38, 31
	s_nop 0
	v_lshl_add_u64 v[134:135], s[42:43], 0, v[134:135]
	v_lshl_add_u64 v[134:135], s[38:39], 2, v[134:135]
	s_lshl_b32 s38, s52, 2
	s_mov_b32 s39, s21
	v_lshl_add_u64 v[134:135], v[134:135], 0, s[38:39]
	global_store_dword v[134:135], v1, off

.Lmy_mix0_wdone:
	s_waitcnt vmcnt(0)
	s_waitcnt lgkmcnt(0)
	s_barrier
	ds_read_b64_tr_b16 v[0:1], v116
	ds_read_b64_tr_b16 v[2:3], v116 offset:2048
	ds_read_b128 v[4:7], v117
	s_waitcnt lgkmcnt(0)
	v_mfma_f32_32x32x16_bf16 v[48:63], v[0:3], v[4:7], 0
	ds_read_b128 v[4:7], v117 offset:8192
	s_lshl_b32 s8, s1, 1
	s_mov_b32 s9, s5
	v_or_b32_e32 v94, s91, v65
	v_or_b32_e32 v79, s4, v65
	v_ashrrev_i32_e32 v95, 31, v94
	v_lshlrev_b32_e32 v79, 2, v79
	s_waitcnt lgkmcnt(0)
	v_mfma_f32_32x32x16_bf16 v[32:47], v[0:3], v[4:7], 0
	ds_read_b128 v[4:7], v117 offset:16384
	v_lshlrev_b64 v[94:95], 12, v[94:95]
	s_add_i32 s90, s90, s0
	s_add_i32 s85, s85, s92
	s_waitcnt lgkmcnt(0)
	v_mfma_f32_32x32x16_bf16 v[16:31], v[0:3], v[4:7], 0
	ds_read_b128 v[4:7], v117 offset:24576
	ds_read_b64_tr_b16 v[90:91], v116 offset:8192
	ds_read_b64_tr_b16 v[92:93], v116 offset:10240
	ds_read_b128 v[126:129], v118
	s_waitcnt lgkmcnt(0)
	v_mfma_f32_32x32x16_bf16 v[48:63], v[90:93], v[126:129], v[48:63]
	ds_read_b128 v[126:129], v118 offset:8192
	s_waitcnt lgkmcnt(0)
	v_mfma_f32_32x32x16_bf16 v[32:47], v[90:93], v[126:129], v[32:47]
	ds_read_b128 v[126:129], v118 offset:16384
	v_mfma_f32_32x32x16_bf16 v[0:15], v[0:3], v[4:7], 0
	s_waitcnt lgkmcnt(0)
	v_mfma_f32_32x32x16_bf16 v[16:31], v[90:93], v[126:129], v[16:31]
	ds_read_b128 v[126:129], v118 offset:24576
	s_waitcnt lgkmcnt(0)
	v_mfma_f32_32x32x16_bf16 v[0:15], v[90:93], v[126:129], v[0:15]
	ds_read_b64_tr_b16 v[90:91], v116 offset:16384
	ds_read_b64_tr_b16 v[92:93], v116 offset:18432
	ds_read_b128 v[126:129], v119 offset:8192
	s_waitcnt lgkmcnt(0)
	v_mfma_f32_32x32x16_bf16 v[32:47], v[90:93], v[126:129], v[32:47]
	ds_read_b128 v[126:129], v119 offset:16384
	s_waitcnt lgkmcnt(0)
	v_mfma_f32_32x32x16_bf16 v[16:31], v[90:93], v[126:129], v[16:31]
	ds_read_b128 v[126:129], v119 offset:24576
	s_waitcnt lgkmcnt(0)
	v_mfma_f32_32x32x16_bf16 v[0:15], v[90:93], v[126:129], v[0:15]
	ds_read_b64_tr_b16 v[90:91], v116 offset:24576
	ds_read_b64_tr_b16 v[92:93], v116 offset:26624
	ds_read_b128 v[126:129], v120 offset:8192
	s_waitcnt lgkmcnt(0)
	v_mfma_f32_32x32x16_bf16 v[32:47], v[90:93], v[126:129], v[32:47]
	ds_read_b128 v[126:129], v120 offset:16384
	s_waitcnt lgkmcnt(0)
	v_mfma_f32_32x32x16_bf16 v[16:31], v[90:93], v[126:129], v[16:31]
	ds_read_b128 v[126:129], v120 offset:24576
	s_waitcnt lgkmcnt(0)
	v_mfma_f32_32x32x16_bf16 v[0:15], v[90:93], v[126:129], v[0:15]
	ds_read_b64_tr_b16 v[90:91], v116 offset:32768
	ds_read_b64_tr_b16 v[92:93], v116 offset:34816
	ds_read_b128 v[126:129], v121 offset:16384
	s_waitcnt lgkmcnt(0)
	v_mfma_f32_32x32x16_bf16 v[16:31], v[90:93], v[126:129], v[16:31]
	ds_read_b128 v[126:129], v121 offset:24576
	s_waitcnt lgkmcnt(0)
	v_mfma_f32_32x32x16_bf16 v[0:15], v[90:93], v[126:129], v[0:15]
	ds_read_b64_tr_b16 v[90:91], v116 offset:40960
	ds_read_b64_tr_b16 v[92:93], v116 offset:43008
	ds_read_b128 v[126:129], v122 offset:16384
	s_waitcnt lgkmcnt(0)
	v_mfma_f32_32x32x16_bf16 v[16:31], v[90:93], v[126:129], v[16:31]
	ds_read_b128 v[126:129], v122 offset:24576
	s_waitcnt lgkmcnt(0)
	v_mfma_f32_32x32x16_bf16 v[0:15], v[90:93], v[126:129], v[0:15]
	ds_read_b64_tr_b16 v[90:91], v116 offset:49152
	ds_read_b64_tr_b16 v[92:93], v116 offset:51200
	ds_read_b128 v[126:129], v123 offset:24576
	s_waitcnt lgkmcnt(0)
	v_mfma_f32_32x32x16_bf16 v[0:15], v[90:93], v[126:129], v[0:15]
	ds_read_b64_tr_b16 v[90:91], v116 offset:57344
	ds_read_b64_tr_b16 v[92:93], v116 offset:59392
	ds_read_b128 v[126:129], v124 offset:24576
	global_load_dword v79, v79, s[96:97]
	s_waitcnt lgkmcnt(0)
	v_mfma_f32_32x32x16_bf16 v[0:15], v[90:93], v[126:129], v[0:15]
	v_lshl_add_u64 v[92:93], v[72:73], 0, s[8:9]
	s_lshl_b32 s8, s1, 2
	v_lshl_add_u64 v[90:91], v[74:75], 0, s[8:9]
	v_lshl_add_u64 v[94:95], v[92:93], 0, v[94:95]
	s_cmpk_gt_i32 s90, 0x3ff
	global_load_dwordx4 v[136:139], v[90:91], off
	global_load_dwordx4 v[140:143], v[90:91], off offset:32
	global_load_dwordx4 v[144:147], v[90:91], off offset:64
	global_load_dwordx4 v[148:151], v[90:91], off offset:96
	global_load_dwordx2 v[160:161], v[94:95], off
	global_load_dwordx2 v[162:163], v[94:95], off offset:16
	global_load_dwordx2 v[164:165], v[94:95], off offset:32
	global_load_dwordx2 v[166:167], v[94:95], off offset:48
	v_add_lshl_u32 v132, s4, v65, 2
	v_or_b32_e32 v152, s91, v108
	v_ashrrev_i32_e32 v153, 31, v152
	v_lshlrev_b64 v[152:153], 12, v[152:153]
	v_lshl_add_u64 v[152:153], v[92:93], 0, v[152:153]
	global_load_dword v133, v132, s[96:97] offset:128
	global_load_dwordx2 v[168:169], v[152:153], off
	global_load_dwordx2 v[170:171], v[152:153], off offset:16
	global_load_dwordx2 v[172:173], v[152:153], off offset:32
	global_load_dwordx2 v[174:175], v[152:153], off offset:48
	v_or_b32_e32 v154, s91, v109
	v_ashrrev_i32_e32 v155, 31, v154
	v_lshlrev_b64 v[154:155], 12, v[154:155]
	v_lshl_add_u64 v[154:155], v[92:93], 0, v[154:155]
	global_load_dword v134, v132, s[96:97] offset:256
	global_load_dwordx2 v[176:177], v[154:155], off
	global_load_dwordx2 v[178:179], v[154:155], off offset:16
	global_load_dwordx2 v[180:181], v[154:155], off offset:32
	global_load_dwordx2 v[182:183], v[154:155], off offset:48
	v_or_b32_e32 v156, s91, v110
	v_ashrrev_i32_e32 v157, 31, v156
	v_lshlrev_b64 v[156:157], 12, v[156:157]
	v_lshl_add_u64 v[156:157], v[92:93], 0, v[156:157]
	global_load_dword v135, v132, s[96:97] offset:384
	global_load_dwordx2 v[184:185], v[156:157], off
	global_load_dwordx2 v[186:187], v[156:157], off offset:16
	global_load_dwordx2 v[188:189], v[156:157], off offset:32
	global_load_dwordx2 v[190:191], v[156:157], off offset:48
	s_waitcnt vmcnt(15)
	v_fma_f32 v48, v48, v136, v79
	v_lshlrev_b32_e32 v192, 16, v160
	v_and_b32_e32 v193, 0xffff0000, v160
	v_fma_f32 v49, v49, v137, v79
	v_mul_f32_e32 v48, v48, v192
	v_mul_f32_e32 v49, v49, v193
	v_lshlrev_b32_e32 v194, 16, v161
	v_and_b32_e32 v195, 0xffff0000, v161
	v_fma_f32 v50, v50, v138, v79
	v_fma_f32 v51, v51, v139, v79
	v_mul_f32_e32 v50, v50, v194
	v_mul_f32_e32 v51, v51, v195
	v_cvt_pk_bf16_f32 v48, v48, v49
	v_cvt_pk_bf16_f32 v49, v50, v51
	global_store_dwordx2 v[94:95], v[48:49], off
	v_fma_f32 v52, v52, v140, v79
	v_lshlrev_b32_e32 v192, 16, v162
	v_and_b32_e32 v193, 0xffff0000, v162
	v_fma_f32 v53, v53, v141, v79
	v_mul_f32_e32 v52, v52, v192
	v_mul_f32_e32 v53, v53, v193
	v_lshlrev_b32_e32 v194, 16, v163
	v_and_b32_e32 v195, 0xffff0000, v163
	v_fma_f32 v54, v54, v142, v79
	v_fma_f32 v55, v55, v143, v79
	v_mul_f32_e32 v54, v54, v194
	v_mul_f32_e32 v55, v55, v195
	v_cvt_pk_bf16_f32 v52, v52, v53
	v_cvt_pk_bf16_f32 v53, v54, v55
	global_store_dwordx2 v[94:95], v[52:53], off offset:16
	v_fma_f32 v56, v56, v144, v79
	v_lshlrev_b32_e32 v192, 16, v164
	v_and_b32_e32 v193, 0xffff0000, v164
	v_fma_f32 v57, v57, v145, v79
	v_mul_f32_e32 v56, v56, v192
	v_mul_f32_e32 v57, v57, v193
	v_lshlrev_b32_e32 v194, 16, v165
	v_and_b32_e32 v195, 0xffff0000, v165
	v_fma_f32 v58, v58, v146, v79
	v_fma_f32 v59, v59, v147, v79
	v_mul_f32_e32 v58, v58, v194
	v_mul_f32_e32 v59, v59, v195
	v_cvt_pk_bf16_f32 v56, v56, v57
	v_cvt_pk_bf16_f32 v57, v58, v59
	global_store_dwordx2 v[94:95], v[56:57], off offset:32
	v_fma_f32 v60, v60, v148, v79
	v_lshlrev_b32_e32 v192, 16, v166
	v_and_b32_e32 v193, 0xffff0000, v166
	v_fma_f32 v61, v61, v149, v79
	v_mul_f32_e32 v60, v60, v192
	v_mul_f32_e32 v61, v61, v193
	v_lshlrev_b32_e32 v194, 16, v167
	v_and_b32_e32 v195, 0xffff0000, v167
	v_fma_f32 v62, v62, v150, v79
	v_fma_f32 v63, v63, v151, v79
	v_mul_f32_e32 v62, v62, v194
	v_mul_f32_e32 v63, v63, v195
	v_cvt_pk_bf16_f32 v60, v60, v61
	v_cvt_pk_bf16_f32 v61, v62, v63
	global_store_dwordx2 v[94:95], v[60:61], off offset:48
	s_waitcnt vmcnt(14)
	v_fma_f32 v32, v32, v136, v133
	v_lshlrev_b32_e32 v192, 16, v168
	v_and_b32_e32 v193, 0xffff0000, v168
	v_fma_f32 v33, v33, v137, v133
	v_mul_f32_e32 v32, v32, v192
	v_mul_f32_e32 v33, v33, v193
	v_lshlrev_b32_e32 v194, 16, v169
	v_and_b32_e32 v195, 0xffff0000, v169
	v_fma_f32 v34, v34, v138, v133
	v_fma_f32 v35, v35, v139, v133
	v_mul_f32_e32 v34, v34, v194
	v_mul_f32_e32 v35, v35, v195
	v_cvt_pk_bf16_f32 v32, v32, v33
	v_cvt_pk_bf16_f32 v33, v34, v35
	global_store_dwordx2 v[152:153], v[32:33], off
	v_fma_f32 v36, v36, v140, v133
	v_lshlrev_b32_e32 v192, 16, v170
	v_and_b32_e32 v193, 0xffff0000, v170
	v_fma_f32 v37, v37, v141, v133
	v_mul_f32_e32 v36, v36, v192
	v_mul_f32_e32 v37, v37, v193
	v_lshlrev_b32_e32 v194, 16, v171
	v_and_b32_e32 v195, 0xffff0000, v171
	v_fma_f32 v38, v38, v142, v133
	v_fma_f32 v39, v39, v143, v133
	v_mul_f32_e32 v38, v38, v194
	v_mul_f32_e32 v39, v39, v195
	v_cvt_pk_bf16_f32 v36, v36, v37
	v_cvt_pk_bf16_f32 v37, v38, v39
	global_store_dwordx2 v[152:153], v[36:37], off offset:16
	v_fma_f32 v40, v40, v144, v133
	v_lshlrev_b32_e32 v192, 16, v172
	v_and_b32_e32 v193, 0xffff0000, v172
	v_fma_f32 v41, v41, v145, v133
	v_mul_f32_e32 v40, v40, v192
	v_mul_f32_e32 v41, v41, v193
	v_lshlrev_b32_e32 v194, 16, v173
	v_and_b32_e32 v195, 0xffff0000, v173
	v_fma_f32 v42, v42, v146, v133
	v_fma_f32 v43, v43, v147, v133
	v_mul_f32_e32 v42, v42, v194
	v_mul_f32_e32 v43, v43, v195
	v_cvt_pk_bf16_f32 v40, v40, v41
	v_cvt_pk_bf16_f32 v41, v42, v43
	global_store_dwordx2 v[152:153], v[40:41], off offset:32
	v_fma_f32 v44, v44, v148, v133
	v_lshlrev_b32_e32 v192, 16, v174
	v_and_b32_e32 v193, 0xffff0000, v174
	v_fma_f32 v45, v45, v149, v133
	v_mul_f32_e32 v44, v44, v192
	v_mul_f32_e32 v45, v45, v193
	v_lshlrev_b32_e32 v194, 16, v175
	v_and_b32_e32 v195, 0xffff0000, v175
	v_fma_f32 v46, v46, v150, v133
	v_fma_f32 v47, v47, v151, v133
	v_mul_f32_e32 v46, v46, v194
	v_mul_f32_e32 v47, v47, v195
	v_cvt_pk_bf16_f32 v44, v44, v45
	v_cvt_pk_bf16_f32 v45, v46, v47
	global_store_dwordx2 v[152:153], v[44:45], off offset:48
	s_waitcnt vmcnt(13)
	v_fma_f32 v16, v16, v136, v134
	v_lshlrev_b32_e32 v192, 16, v176
	v_and_b32_e32 v193, 0xffff0000, v176
	v_fma_f32 v17, v17, v137, v134
	v_mul_f32_e32 v16, v16, v192
	v_mul_f32_e32 v17, v17, v193
	v_lshlrev_b32_e32 v194, 16, v177
	v_and_b32_e32 v195, 0xffff0000, v177
	v_fma_f32 v18, v18, v138, v134
	v_fma_f32 v19, v19, v139, v134
	v_mul_f32_e32 v18, v18, v194
	v_mul_f32_e32 v19, v19, v195
	v_cvt_pk_bf16_f32 v16, v16, v17
	v_cvt_pk_bf16_f32 v17, v18, v19
	global_store_dwordx2 v[154:155], v[16:17], off
	v_fma_f32 v20, v20, v140, v134
	v_lshlrev_b32_e32 v192, 16, v178
	v_and_b32_e32 v193, 0xffff0000, v178
	v_fma_f32 v21, v21, v141, v134
	v_mul_f32_e32 v20, v20, v192
	v_mul_f32_e32 v21, v21, v193
	v_lshlrev_b32_e32 v194, 16, v179
	v_and_b32_e32 v195, 0xffff0000, v179
	v_fma_f32 v22, v22, v142, v134
	v_fma_f32 v23, v23, v143, v134
	v_mul_f32_e32 v22, v22, v194
	v_mul_f32_e32 v23, v23, v195
	v_cvt_pk_bf16_f32 v20, v20, v21
	v_cvt_pk_bf16_f32 v21, v22, v23
	global_store_dwordx2 v[154:155], v[20:21], off offset:16
	v_fma_f32 v24, v24, v144, v134
	v_lshlrev_b32_e32 v192, 16, v180
	v_and_b32_e32 v193, 0xffff0000, v180
	v_fma_f32 v25, v25, v145, v134
	v_mul_f32_e32 v24, v24, v192
	v_mul_f32_e32 v25, v25, v193
	v_lshlrev_b32_e32 v194, 16, v181
	v_and_b32_e32 v195, 0xffff0000, v181
	v_fma_f32 v26, v26, v146, v134
	v_fma_f32 v27, v27, v147, v134
	v_mul_f32_e32 v26, v26, v194
	v_mul_f32_e32 v27, v27, v195
	v_cvt_pk_bf16_f32 v24, v24, v25
	v_cvt_pk_bf16_f32 v25, v26, v27
	global_store_dwordx2 v[154:155], v[24:25], off offset:32
	v_fma_f32 v28, v28, v148, v134
	v_lshlrev_b32_e32 v192, 16, v182
	v_and_b32_e32 v193, 0xffff0000, v182
	v_fma_f32 v29, v29, v149, v134
	v_mul_f32_e32 v28, v28, v192
	v_mul_f32_e32 v29, v29, v193
	v_lshlrev_b32_e32 v194, 16, v183
	v_and_b32_e32 v195, 0xffff0000, v183
	v_fma_f32 v30, v30, v150, v134
	v_fma_f32 v31, v31, v151, v134
	v_mul_f32_e32 v30, v30, v194
	v_mul_f32_e32 v31, v31, v195
	v_cvt_pk_bf16_f32 v28, v28, v29
	v_cvt_pk_bf16_f32 v29, v30, v31
	global_store_dwordx2 v[154:155], v[28:29], off offset:48
	s_waitcnt vmcnt(12)
	v_fma_f32 v0, v0, v136, v135
	v_lshlrev_b32_e32 v192, 16, v184
	v_and_b32_e32 v193, 0xffff0000, v184
	v_fma_f32 v1, v1, v137, v135
	v_mul_f32_e32 v0, v0, v192
	v_mul_f32_e32 v1, v1, v193
	v_lshlrev_b32_e32 v194, 16, v185
	v_and_b32_e32 v195, 0xffff0000, v185
	v_fma_f32 v2, v2, v138, v135
	v_fma_f32 v3, v3, v139, v135
	v_mul_f32_e32 v2, v2, v194
	v_mul_f32_e32 v3, v3, v195
	v_cvt_pk_bf16_f32 v0, v0, v1
	v_cvt_pk_bf16_f32 v1, v2, v3
	global_store_dwordx2 v[156:157], v[0:1], off
	v_fma_f32 v4, v4, v140, v135
	v_lshlrev_b32_e32 v192, 16, v186
	v_and_b32_e32 v193, 0xffff0000, v186
	v_fma_f32 v5, v5, v141, v135
	v_mul_f32_e32 v4, v4, v192
	v_mul_f32_e32 v5, v5, v193
	v_lshlrev_b32_e32 v194, 16, v187
	v_and_b32_e32 v195, 0xffff0000, v187
	v_fma_f32 v6, v6, v142, v135
	v_fma_f32 v7, v7, v143, v135
	v_mul_f32_e32 v6, v6, v194
	v_mul_f32_e32 v7, v7, v195
	v_cvt_pk_bf16_f32 v4, v4, v5
	v_cvt_pk_bf16_f32 v5, v6, v7
	global_store_dwordx2 v[156:157], v[4:5], off offset:16
	v_fma_f32 v8, v8, v144, v135
	v_lshlrev_b32_e32 v192, 16, v188
	v_and_b32_e32 v193, 0xffff0000, v188
	v_fma_f32 v9, v9, v145, v135
	v_mul_f32_e32 v8, v8, v192
	v_mul_f32_e32 v9, v9, v193
	v_lshlrev_b32_e32 v194, 16, v189
	v_and_b32_e32 v195, 0xffff0000, v189
	v_fma_f32 v10, v10, v146, v135
	v_fma_f32 v11, v11, v147, v135
	v_mul_f32_e32 v10, v10, v194
	v_mul_f32_e32 v11, v11, v195
	v_cvt_pk_bf16_f32 v8, v8, v9
	v_cvt_pk_bf16_f32 v9, v10, v11
	global_store_dwordx2 v[156:157], v[8:9], off offset:32
	v_fma_f32 v12, v12, v148, v135
	v_lshlrev_b32_e32 v192, 16, v190
	v_and_b32_e32 v193, 0xffff0000, v190
	v_fma_f32 v13, v13, v149, v135
	v_mul_f32_e32 v12, v12, v192
	v_mul_f32_e32 v13, v13, v193
	v_lshlrev_b32_e32 v194, 16, v191
	v_and_b32_e32 v195, 0xffff0000, v191
	v_fma_f32 v14, v14, v150, v135
	v_fma_f32 v15, v15, v151, v135
	v_mul_f32_e32 v14, v14, v194
	v_mul_f32_e32 v15, v15, v195
	v_cvt_pk_bf16_f32 v12, v12, v13
	v_cvt_pk_bf16_f32 v13, v14, v15
	global_store_dwordx2 v[156:157], v[12:13], off offset:48
	s_barrier
	s_cbranch_scc1 .LBB0_305

.LBB0_241:
	s_or_b64 exec, exec, s[8:9]
	s_lshl_b32 s4, s1, 7
	v_lshl_add_u64 v[0:1], s[4:5], 0, v[68:69]
	v_lshlrev_b64 v[0:1], 9, v[0:1]
	v_lshl_add_u64 v[8:9], v[70:71], 0, v[0:1]
	s_waitcnt vmcnt(0) lgkmcnt(0)
	s_barrier
	global_load_dwordx4 v[16:19], v[8:9], off
	global_load_dwordx4 v[20:23], v[8:9], off offset:16
	global_load_dwordx4 v[24:27], v[8:9], off offset:32
	global_load_dwordx4 v[28:31], v[8:9], off offset:48
	global_load_dwordx4 v[32:35], v[8:9], off offset:64
	global_load_dwordx4 v[36:39], v[8:9], off offset:80
	global_load_dwordx4 v[40:43], v[8:9], off offset:96
	global_load_dwordx4 v[44:47], v[8:9], off offset:112
	ds_read_b128 v[132:135], v99
	ds_read_b128 v[136:139], v99 offset:16
	ds_read_b128 v[140:143], v99 offset:32
	ds_read_b128 v[144:147], v99 offset:48
	ds_read_b128 v[148:151], v99 offset:64
	ds_read_b128 v[152:155], v99 offset:80
	ds_read_b128 v[156:159], v99 offset:96
	ds_read_b128 v[160:163], v99 offset:112
	s_lshl_b32 s1, s1, 8
	s_waitcnt vmcnt(0) lgkmcnt(0)
	v_mul_f32_e32 v16, v16, v132
	v_mul_f32_e32 v17, v17, v133
	v_mul_f32_e32 v18, v18, v134
	v_mul_f32_e32 v19, v19, v135
	v_mul_f32_e32 v20, v20, v136
	v_mul_f32_e32 v21, v21, v137
	v_mul_f32_e32 v22, v22, v138
	v_mul_f32_e32 v23, v23, v139
	v_mul_f32_e32 v24, v24, v140
	v_mul_f32_e32 v25, v25, v141
	v_mul_f32_e32 v26, v26, v142
	v_mul_f32_e32 v27, v27, v143
	v_mul_f32_e32 v28, v28, v144
	v_mul_f32_e32 v29, v29, v145
	v_mul_f32_e32 v30, v30, v146
	v_mul_f32_e32 v31, v31, v147
	v_mul_f32_e32 v32, v32, v148
	v_mul_f32_e32 v33, v33, v149
	v_mul_f32_e32 v34, v34, v150
	v_mul_f32_e32 v35, v35, v151
	v_mul_f32_e32 v36, v36, v152
	v_mul_f32_e32 v37, v37, v153
	v_mul_f32_e32 v38, v38, v154
	v_mul_f32_e32 v39, v39, v155
	v_mul_f32_e32 v40, v40, v156
	v_mul_f32_e32 v41, v41, v157
	v_mul_f32_e32 v42, v42, v158
	v_mul_f32_e32 v43, v43, v159
	v_mul_f32_e32 v44, v44, v160
	v_mul_f32_e32 v45, v45, v161
	v_mul_f32_e32 v46, v46, v162
	v_mul_f32_e32 v47, v47, v163
	v_cndmask_b32_e64 v16, 0, v16, s[6:7]
	v_cndmask_b32_e64 v17, 0, v17, s[10:11]
	v_cndmask_b32_e64 v18, 0, v18, s[12:13]
	v_cndmask_b32_e64 v19, 0, v19, s[14:15]
	v_cndmask_b32_e64 v20, 0, v20, s[16:17]
	v_cndmask_b32_e64 v21, 0, v21, s[18:19]
	v_cndmask_b32_e64 v22, 0, v22, s[20:21]
	v_cndmask_b32_e64 v23, 0, v23, s[22:23]
	v_cndmask_b32_e64 v24, 0, v24, s[24:25]
	v_cndmask_b32_e64 v25, 0, v25, s[26:27]
	v_cndmask_b32_e64 v26, 0, v26, s[28:29]
	v_cndmask_b32_e64 v27, 0, v27, s[30:31]
	v_cndmask_b32_e64 v28, 0, v28, s[34:35]
	v_cndmask_b32_e64 v29, 0, v29, s[36:37]
	v_cndmask_b32_e64 v30, 0, v30, s[38:39]
	v_cndmask_b32_e64 v31, 0, v31, s[40:41]
	v_cndmask_b32_e64 v32, 0, v32, s[42:43]
	v_cndmask_b32_e64 v33, 0, v33, s[44:45]
	v_cndmask_b32_e64 v34, 0, v34, s[46:47]
	v_cndmask_b32_e64 v35, 0, v35, s[48:49]
	v_cndmask_b32_e64 v36, 0, v36, s[50:51]
	v_cndmask_b32_e64 v37, 0, v37, s[52:53]
	v_cndmask_b32_e64 v38, 0, v38, s[54:55]
	v_cndmask_b32_e64 v39, 0, v39, s[56:57]
	v_cndmask_b32_e64 v40, 0, v40, s[58:59]
	v_cndmask_b32_e64 v41, 0, v41, s[60:61]
	v_cndmask_b32_e64 v42, 0, v42, s[62:63]
	v_cndmask_b32_e64 v43, 0, v43, s[64:65]
	v_cndmask_b32_e64 v44, 0, v44, s[66:67]
	v_cndmask_b32_e64 v45, 0, v45, s[68:69]
	v_cndmask_b32_e64 v46, 0, v46, s[70:71]
	v_cndmask_b32_e64 v47, 0, v47, s[72:73]
	v_cvt_pk_bf16_f32 v48, v16, v17
	v_cvt_pk_bf16_f32 v49, v18, v19
	v_cvt_pk_bf16_f32 v50, v20, v21
	v_cvt_pk_bf16_f32 v51, v22, v23
	ds_write_b128 v112, v[48:51]
	v_cvt_pk_bf16_f32 v52, v24, v25
	v_cvt_pk_bf16_f32 v53, v26, v27
	v_cvt_pk_bf16_f32 v54, v28, v29
	v_cvt_pk_bf16_f32 v55, v30, v31
	ds_write_b128 v113, v[52:55]
	v_cvt_pk_bf16_f32 v56, v32, v33
	v_cvt_pk_bf16_f32 v57, v34, v35
	v_cvt_pk_bf16_f32 v58, v36, v37
	v_cvt_pk_bf16_f32 v59, v38, v39
	ds_write_b128 v114, v[56:59]
	v_cvt_pk_bf16_f32 v60, v40, v41
	v_cvt_pk_bf16_f32 v61, v42, v43
	v_cvt_pk_bf16_f32 v62, v44, v45
	v_cvt_pk_bf16_f32 v63, v46, v47
	ds_write_b128 v115, v[60:63]
	s_branch .Lmy_mix0_wdone

.LBB0_581:
	v_mov_b32_e32 v2, v0
	v_mov_b32_e32 v3, v0
	v_mov_b32_e32 v1, v0
	v_mov_b32_e32 v127, 0
	v_mov_b64_e32 v[62:63], v[2:3]
	v_mov_b64_e32 v[54:55], v[2:3]
	v_mov_b64_e32 v[46:47], v[2:3]
	v_mov_b64_e32 v[38:39], v[2:3]
	v_mov_b64_e32 v[30:31], v[2:3]
	v_mov_b64_e32 v[22:23], v[2:3]
	v_mov_b64_e32 v[14:15], v[2:3]
	v_mov_b64_e32 v[6:7], v[2:3]
	v_mov_b64_e32 v[66:67], v[2:3]
	v_mov_b64_e32 v[58:59], v[2:3]
	v_mov_b64_e32 v[50:51], v[2:3]
	v_mov_b64_e32 v[42:43], v[2:3]
	v_mov_b64_e32 v[34:35], v[2:3]
	v_mov_b64_e32 v[26:27], v[2:3]
	v_mov_b64_e32 v[18:19], v[2:3]
	v_mov_b64_e32 v[10:11], v[2:3]
	v_mov_b32_e32 v126, v127
	v_mov_b32_e32 v125, v127
	v_mov_b32_e32 v124, v127
	v_mov_b32_e32 v119, v127
	v_mov_b32_e32 v118, v127
	v_mov_b32_e32 v117, v127
	v_mov_b32_e32 v116, v127
	v_mov_b32_e32 v111, v127
	v_mov_b32_e32 v110, v127
	v_mov_b32_e32 v109, v127
	v_mov_b32_e32 v108, v127
	v_mov_b32_e32 v103, v127
	v_mov_b32_e32 v102, v127
	v_mov_b32_e32 v101, v127
	v_mov_b32_e32 v100, v127
	v_mov_b32_e32 v95, v127
	v_mov_b32_e32 v94, v127
	v_mov_b32_e32 v93, v127
	v_mov_b32_e32 v92, v127
	v_mov_b32_e32 v87, v127
	v_mov_b32_e32 v86, v127
	v_mov_b32_e32 v85, v127
	v_mov_b32_e32 v84, v127
	v_mov_b32_e32 v79, v127
	v_mov_b32_e32 v78, v127
	v_mov_b32_e32 v77, v127
	v_mov_b32_e32 v76, v127
	v_mov_b32_e32 v75, v127
	v_mov_b32_e32 v74, v127
	v_mov_b32_e32 v73, v127
	v_mov_b32_e32 v72, v127
	v_mov_b32_e32 v131, v127
	v_mov_b32_e32 v130, v127
	v_mov_b32_e32 v129, v127
	v_mov_b32_e32 v128, v127
	v_mov_b32_e32 v123, v127
	v_mov_b32_e32 v122, v127
	v_mov_b32_e32 v121, v127
	v_mov_b32_e32 v120, v127
	v_mov_b32_e32 v115, v127
	v_mov_b32_e32 v114, v127
	v_mov_b32_e32 v113, v127
	v_mov_b32_e32 v112, v127
	v_mov_b32_e32 v107, v127
	v_mov_b32_e32 v106, v127
	v_mov_b32_e32 v105, v127
	v_mov_b32_e32 v104, v127
	v_mov_b32_e32 v99, v127
	v_mov_b32_e32 v98, v127
	v_mov_b32_e32 v97, v127
	v_mov_b32_e32 v96, v127
	v_mov_b32_e32 v91, v127
	v_mov_b32_e32 v90, v127
	v_mov_b32_e32 v89, v127
	v_mov_b32_e32 v88, v127
	v_mov_b32_e32 v83, v127
	v_mov_b32_e32 v82, v127
	v_mov_b32_e32 v81, v127
	v_mov_b32_e32 v80, v127
	v_mov_b32_e32 v71, v127
	v_mov_b32_e32 v70, v127
	v_mov_b32_e32 v69, v127
	v_mov_b32_e32 v68, v127
	v_mov_b64_e32 v[60:61], v[0:1]
	v_mov_b64_e32 v[52:53], v[0:1]
	v_mov_b64_e32 v[44:45], v[0:1]
	v_mov_b64_e32 v[36:37], v[0:1]
	v_mov_b64_e32 v[28:29], v[0:1]
	v_mov_b64_e32 v[20:21], v[0:1]
	v_mov_b64_e32 v[12:13], v[0:1]
	v_mov_b64_e32 v[4:5], v[0:1]
	v_mov_b64_e32 v[64:65], v[0:1]
	v_mov_b64_e32 v[56:57], v[0:1]
	v_mov_b64_e32 v[48:49], v[0:1]
	v_mov_b64_e32 v[40:41], v[0:1]
	v_mov_b64_e32 v[32:33], v[0:1]
	v_mov_b64_e32 v[24:25], v[0:1]
	v_mov_b64_e32 v[16:17], v[0:1]
	v_mov_b64_e32 v[8:9], v[0:1]
	s_waitcnt vmcnt(0)
.LBB0_582:
	s_waitcnt vmcnt(6)
	v_fmamk_f32 v1, v233, 0x3a800000, v226
	v_mul_f32_e32 v2, 0x4b800000, v1
	v_cmp_gt_f32_e32 vcc, s48, v1
	v_mov_b32_e32 v134, v128
	v_mov_b32_e32 v135, v124
	v_cndmask_b32_e32 v1, v1, v2, vcc
	v_rsq_f32_e32 v3, v1
	v_mov_b32_e32 v124, v129
	v_readlane_b32 s14, v255, 18
	v_lshl_or_b32 v2, s22, 7, v221
	v_mul_f32_e32 v132, 0x45800000, v3
	v_cndmask_b32_e32 v132, v3, v132, vcc
	v_pk_mul_f32 v[134:135], v[132:133], v[134:135] op_sel_hi:[0,1]
	v_mul_f32_e32 v3, 0xbfb8aa3b, v135
	v_pk_mul_f32 v[124:125], v[132:133], v[124:125] op_sel_hi:[0,1]
	v_exp_f32_e32 v3, v3
	v_mul_f32_e32 v128, 0xbfb8aa3b, v125
	v_exp_f32_e32 v128, v128
	v_readlane_b32 s15, v255, 19
	v_add_f32_e32 v3, 1.0, v3
	v_rcp_f32_e32 v129, v3
	v_add_f32_e32 v3, 1.0, v128
	v_rcp_f32_e32 v128, v3
	v_lshl_add_u32 v1, s20, 8, v219
	v_mul_f32_e32 v129, v135, v129
	v_mul_f32_e32 v133, v134, v129
	v_mul_f32_e32 v125, v125, v128
	v_mov_b32_e32 v128, v130
	v_mov_b32_e32 v129, v126
	v_pk_mul_f32 v[128:129], v[132:133], v[128:129] op_sel_hi:[0,1]
	v_mul_f32_e32 v126, 0xbfb8aa3b, v129
	v_exp_f32_e32 v130, v126
	v_mov_b32_e32 v126, v131
	v_pk_mul_f32 v[126:127], v[132:133], v[126:127] op_sel_hi:[0,1]
	v_mul_f32_e32 v131, 0xbfb8aa3b, v127
	v_exp_f32_e32 v131, v131
	v_mul_f32_e32 v134, v124, v125
	v_add_f32_e32 v124, 1.0, v130
	v_rcp_f32_e32 v130, v124
	v_add_f32_e32 v124, 1.0, v131
	v_rcp_f32_e32 v131, v124
	v_mov_b32_e32 v124, v120
	v_mov_b32_e32 v125, v116
	v_pk_mul_f32 v[124:125], v[132:133], v[124:125] op_sel_hi:[0,1]
	v_mul_f32_e32 v116, 0xbfb8aa3b, v125
	v_exp_f32_e32 v116, v116
	v_mul_f32_e32 v120, v129, v130
	v_mul_f32_e32 v128, v128, v120
	v_mul_f32_e32 v120, v127, v131
	v_add_f32_e32 v116, 1.0, v116
	v_rcp_f32_e32 v127, v116
	v_mov_b32_e32 v116, v121
	v_pk_mul_f32 v[116:117], v[132:133], v[116:117] op_sel_hi:[0,1]
	v_mul_f32_e32 v121, 0xbfb8aa3b, v117
	v_exp_f32_e32 v121, v121
	v_mul_f32_e32 v126, v126, v120
	v_mul_f32_e32 v120, v125, v127
	v_mul_f32_e32 v124, v124, v120
	v_add_f32_e32 v120, 1.0, v121
	v_rcp_f32_e32 v125, v120
	v_mov_b32_e32 v120, v122
	v_mov_b32_e32 v121, v118
	v_pk_mul_f32 v[120:121], v[132:133], v[120:121] op_sel_hi:[0,1]
	v_mul_f32_e32 v118, 0xbfb8aa3b, v121
	v_exp_f32_e32 v122, v118
	v_mov_b32_e32 v118, v123
	v_pk_mul_f32 v[118:119], v[132:133], v[118:119] op_sel_hi:[0,1]
	v_mul_f32_e32 v123, 0xbfb8aa3b, v119
	v_exp_f32_e32 v123, v123
	v_add_f32_e32 v122, 1.0, v122
	v_rcp_f32_e32 v122, v122
	v_mul_f32_e32 v117, v117, v125
	v_add_f32_e32 v123, 1.0, v123
	v_rcp_f32_e32 v123, v123
	v_mul_f32_e32 v116, v116, v117
	v_mul_f32_e32 v117, v121, v122
	v_fmamk_f32 v122, v232, 0x3a800000, v226
	v_mul_f32_e32 v119, v119, v123
	v_mul_f32_e32 v123, 0x4b800000, v122
	v_cmp_gt_f32_e32 vcc, s48, v122
	v_mul_f32_e32 v117, v120, v117
	v_mul_f32_e32 v121, v118, v119
	v_cndmask_b32_e32 v122, v122, v123, vcc
	v_cvt_pk_bf16_f32 v118, v133, v134
	v_cvt_pk_bf16_f32 v119, v128, v126
	v_cvt_pk_bf16_f32 v120, v124, v116
	v_rsq_f32_e32 v124, v122
	v_mov_b32_e32 v126, v112
	v_mov_b32_e32 v127, v108
	v_ashrrev_i32_e32 v3, 31, v2
	v_mul_f32_e32 v125, 0x45800000, v124
	v_cndmask_b32_e32 v124, v124, v125, vcc
	v_pk_mul_f32 v[126:127], v[124:125], v[126:127] op_sel_hi:[0,1]
	v_mul_f32_e32 v108, 0xbfb8aa3b, v127
	v_exp_f32_e32 v125, v108
	v_mov_b32_e32 v108, v113
	v_cvt_pk_bf16_f32 v121, v117, v121
	v_mov_b64_e32 v[116:117], s[14:15]
	v_pk_mul_f32 v[108:109], v[124:125], v[108:109] op_sel_hi:[0,1]
	v_mad_i64_i32 v[122:123], s[14:15], v1, s49, v[116:117]
	v_lshlrev_b64 v[2:3], 1, v[2:3]
	v_mul_f32_e32 v112, 0xbfb8aa3b, v109
	v_exp_f32_e32 v128, v112
	v_lshl_add_u64 v[112:113], v[122:123], 0, v[2:3]
	v_add_f32_e32 v122, 1.0, v125
	v_rcp_f32_e32 v122, v122
	global_store_dwordx4 v[112:113], v[118:121], off
	v_mov_b32_e32 v113, v110
	v_add_f32_e32 v123, 1.0, v128
	v_mul_f32_e32 v112, v127, v122
	v_mul_f32_e32 v118, v126, v112
	v_mov_b32_e32 v112, v114
	v_pk_mul_f32 v[112:113], v[124:125], v[112:113] op_sel_hi:[0,1]
	v_mul_f32_e32 v110, 0xbfb8aa3b, v113
	v_exp_f32_e32 v114, v110
	v_mov_b32_e32 v110, v115
	v_rcp_f32_e32 v123, v123
	v_pk_mul_f32 v[110:111], v[124:125], v[110:111] op_sel_hi:[0,1]
	v_mul_f32_e32 v115, 0xbfb8aa3b, v111
	v_exp_f32_e32 v115, v115
	v_mul_f32_e32 v109, v109, v123
	v_mul_f32_e32 v119, v108, v109
	v_add_f32_e32 v108, 1.0, v114
	v_rcp_f32_e32 v114, v108
	v_add_f32_e32 v108, 1.0, v115
	v_rcp_f32_e32 v115, v108
	v_mov_b32_e32 v108, v104
	v_mov_b32_e32 v109, v100
	v_pk_mul_f32 v[108:109], v[124:125], v[108:109] op_sel_hi:[0,1]
	v_mul_f32_e32 v100, 0xbfb8aa3b, v109
	v_exp_f32_e32 v100, v100
	v_mul_f32_e32 v104, v113, v114
	v_mul_f32_e32 v112, v112, v104
	v_mul_f32_e32 v104, v111, v115
	v_add_f32_e32 v100, 1.0, v100
	v_rcp_f32_e32 v111, v100
	v_mov_b32_e32 v100, v105
	v_pk_mul_f32 v[100:101], v[124:125], v[100:101] op_sel_hi:[0,1]
	v_mul_f32_e32 v105, 0xbfb8aa3b, v101
	v_exp_f32_e32 v105, v105
	v_mul_f32_e32 v110, v110, v104
	v_mul_f32_e32 v104, v109, v111
	v_mul_f32_e32 v108, v108, v104
	v_add_f32_e32 v104, 1.0, v105
	v_rcp_f32_e32 v109, v104
	v_mov_b32_e32 v104, v106
	v_mov_b32_e32 v105, v102
	v_pk_mul_f32 v[104:105], v[124:125], v[104:105] op_sel_hi:[0,1]
	v_mul_f32_e32 v102, 0xbfb8aa3b, v105
	v_exp_f32_e32 v106, v102
	v_mov_b32_e32 v102, v107
	v_pk_mul_f32 v[102:103], v[124:125], v[102:103] op_sel_hi:[0,1]
	v_mul_f32_e32 v107, 0xbfb8aa3b, v103
	v_exp_f32_e32 v107, v107
	v_add_f32_e32 v106, 1.0, v106
	v_rcp_f32_e32 v106, v106
	v_mul_f32_e32 v101, v101, v109
	v_add_f32_e32 v107, 1.0, v107
	v_rcp_f32_e32 v107, v107
	v_mul_f32_e32 v109, v100, v101
	v_mul_f32_e32 v100, v105, v106
	v_fmamk_f32 v106, v231, 0x3a800000, v226
	v_mul_f32_e32 v104, v104, v100
	v_mul_f32_e32 v100, v103, v107
	v_mul_f32_e32 v107, 0x4b800000, v106
	v_cmp_gt_f32_e32 vcc, s48, v106
	v_mul_f32_e32 v103, v102, v100
	v_cvt_pk_bf16_f32 v100, v118, v119
	v_cvt_pk_bf16_f32 v101, v112, v110
	v_cvt_pk_bf16_f32 v102, v108, v109
	v_mov_b32_e32 v108, v96
	v_cndmask_b32_e32 v106, v106, v107, vcc
	v_rsq_f32_e32 v106, v106
	v_mov_b32_e32 v109, v92
	v_or_b32_e32 v105, 16, v1
	v_cvt_pk_bf16_f32 v103, v104, v103
	v_mul_f32_e32 v107, 0x45800000, v106
	v_cndmask_b32_e32 v106, v106, v107, vcc
	v_pk_mul_f32 v[108:109], v[106:107], v[108:109] op_sel_hi:[0,1]
	v_mul_f32_e32 v92, 0xbfb8aa3b, v109
	v_exp_f32_e32 v107, v92
	v_mov_b32_e32 v92, v97
	v_mad_i64_i32 v[104:105], s[14:15], v105, s49, v[116:117]
	v_pk_mul_f32 v[92:93], v[106:107], v[92:93] op_sel_hi:[0,1]
	v_mul_f32_e32 v96, 0xbfb8aa3b, v93
	v_exp_f32_e32 v110, v96
	v_lshl_add_u64 v[96:97], v[104:105], 0, v[2:3]
	v_add_f32_e32 v104, 1.0, v107
	v_rcp_f32_e32 v104, v104
	global_store_dwordx4 v[96:97], v[100:103], off
	v_mov_b32_e32 v97, v94
	v_add_f32_e32 v105, 1.0, v110
	v_mul_f32_e32 v96, v109, v104
	v_mul_f32_e32 v100, v108, v96
	v_mov_b32_e32 v96, v98
	v_pk_mul_f32 v[96:97], v[106:107], v[96:97] op_sel_hi:[0,1]
	v_mul_f32_e32 v94, 0xbfb8aa3b, v97
	v_exp_f32_e32 v98, v94
	v_mov_b32_e32 v94, v99
	v_rcp_f32_e32 v105, v105
	v_pk_mul_f32 v[94:95], v[106:107], v[94:95] op_sel_hi:[0,1]
	v_mul_f32_e32 v99, 0xbfb8aa3b, v95
	v_exp_f32_e32 v99, v99
	v_mul_f32_e32 v93, v93, v105
	v_mul_f32_e32 v101, v92, v93
	v_add_f32_e32 v92, 1.0, v98
	v_rcp_f32_e32 v98, v92
	v_add_f32_e32 v92, 1.0, v99
	v_rcp_f32_e32 v99, v92
	v_mov_b32_e32 v92, v88
	v_mov_b32_e32 v93, v84
	v_pk_mul_f32 v[92:93], v[106:107], v[92:93] op_sel_hi:[0,1]
	v_mul_f32_e32 v84, 0xbfb8aa3b, v93
	v_exp_f32_e32 v84, v84
	v_mul_f32_e32 v88, v97, v98
	v_mul_f32_e32 v96, v96, v88
	v_mul_f32_e32 v88, v95, v99
	v_add_f32_e32 v84, 1.0, v84
	v_rcp_f32_e32 v95, v84
	v_mov_b32_e32 v84, v89
	v_pk_mul_f32 v[84:85], v[106:107], v[84:85] op_sel_hi:[0,1]
	v_mul_f32_e32 v89, 0xbfb8aa3b, v85
	v_exp_f32_e32 v89, v89
	v_mul_f32_e32 v94, v94, v88
	v_mul_f32_e32 v88, v93, v95
	v_mul_f32_e32 v92, v92, v88
	v_add_f32_e32 v88, 1.0, v89
	v_rcp_f32_e32 v93, v88
	v_mov_b32_e32 v88, v90
	v_mov_b32_e32 v89, v86
	v_pk_mul_f32 v[88:89], v[106:107], v[88:89] op_sel_hi:[0,1]
	v_mul_f32_e32 v86, 0xbfb8aa3b, v89
	v_exp_f32_e32 v90, v86
	v_mov_b32_e32 v86, v91
	v_pk_mul_f32 v[86:87], v[106:107], v[86:87] op_sel_hi:[0,1]
	v_mul_f32_e32 v91, 0xbfb8aa3b, v87
	v_exp_f32_e32 v91, v91
	v_add_f32_e32 v90, 1.0, v90
	v_rcp_f32_e32 v90, v90
	v_mul_f32_e32 v85, v85, v93
	v_add_f32_e32 v91, 1.0, v91
	v_rcp_f32_e32 v91, v91
	v_mul_f32_e32 v93, v84, v85
	v_mul_f32_e32 v84, v89, v90
	v_fmamk_f32 v90, v230, 0x3a800000, v226
	v_mul_f32_e32 v88, v88, v84
	v_mul_f32_e32 v84, v87, v91
	v_mul_f32_e32 v91, 0x4b800000, v90
	v_cmp_gt_f32_e32 vcc, s48, v90
	v_mul_f32_e32 v87, v86, v84
	v_cvt_pk_bf16_f32 v84, v100, v101
	v_cvt_pk_bf16_f32 v85, v96, v94
	v_cvt_pk_bf16_f32 v86, v92, v93
	v_mov_b32_e32 v92, v80
	v_cndmask_b32_e32 v90, v90, v91, vcc
	v_rsq_f32_e32 v90, v90
	v_mov_b32_e32 v93, v76
	v_or_b32_e32 v89, 32, v1
	v_cvt_pk_bf16_f32 v87, v88, v87
	v_mul_f32_e32 v91, 0x45800000, v90
	v_cndmask_b32_e32 v90, v90, v91, vcc
	v_pk_mul_f32 v[92:93], v[90:91], v[92:93] op_sel_hi:[0,1]
	v_mul_f32_e32 v76, 0xbfb8aa3b, v93
	v_exp_f32_e32 v91, v76
	v_mov_b32_e32 v76, v81
	v_mad_i64_i32 v[88:89], s[14:15], v89, s49, v[116:117]
	v_pk_mul_f32 v[76:77], v[90:91], v[76:77] op_sel_hi:[0,1]
	v_mul_f32_e32 v80, 0xbfb8aa3b, v77
	v_exp_f32_e32 v94, v80
	v_lshl_add_u64 v[80:81], v[88:89], 0, v[2:3]
	v_add_f32_e32 v88, 1.0, v91
	v_rcp_f32_e32 v88, v88
	global_store_dwordx4 v[80:81], v[84:87], off
	v_mov_b32_e32 v81, v78
	v_add_f32_e32 v89, 1.0, v94
	v_mul_f32_e32 v80, v93, v88
	v_mul_f32_e32 v84, v92, v80
	v_mov_b32_e32 v80, v82
	v_pk_mul_f32 v[80:81], v[90:91], v[80:81] op_sel_hi:[0,1]
	v_mul_f32_e32 v78, 0xbfb8aa3b, v81
	v_exp_f32_e32 v82, v78
	v_mov_b32_e32 v78, v83
	v_rcp_f32_e32 v89, v89
	v_pk_mul_f32 v[78:79], v[90:91], v[78:79] op_sel_hi:[0,1]
	v_mul_f32_e32 v83, 0xbfb8aa3b, v79
	v_exp_f32_e32 v83, v83
	v_mul_f32_e32 v77, v77, v89
	v_mul_f32_e32 v85, v76, v77
	v_add_f32_e32 v76, 1.0, v82
	v_rcp_f32_e32 v82, v76
	v_add_f32_e32 v76, 1.0, v83
	v_rcp_f32_e32 v83, v76
	v_mov_b32_e32 v76, v68
	v_mov_b32_e32 v77, v72
	v_pk_mul_f32 v[76:77], v[90:91], v[76:77] op_sel_hi:[0,1]
	v_mul_f32_e32 v68, 0xbfb8aa3b, v77
	v_exp_f32_e32 v68, v68
	v_mul_f32_e32 v72, v81, v82
	v_mul_f32_e32 v80, v80, v72
	v_mov_b32_e32 v72, v69
	v_add_f32_e32 v68, 1.0, v68
	v_rcp_f32_e32 v81, v68
	v_pk_mul_f32 v[68:69], v[90:91], v[72:73] op_sel_hi:[0,1]
	v_mul_f32_e32 v72, 0xbfb8aa3b, v69
	v_exp_f32_e32 v72, v72
	v_mul_f32_e32 v73, v77, v81
	v_mul_f32_e32 v76, v76, v73
	v_mov_b32_e32 v73, v74
	v_add_f32_e32 v72, 1.0, v72
	v_rcp_f32_e32 v77, v72
	v_mov_b32_e32 v72, v70
	v_pk_mul_f32 v[72:73], v[90:91], v[72:73] op_sel_hi:[0,1]
	v_mul_f32_e32 v79, v79, v83
	v_mul_f32_e32 v70, 0xbfb8aa3b, v73
	v_mov_b32_e32 v74, v71
	v_mul_f32_e32 v78, v78, v79
	v_exp_f32_e32 v79, v70
	v_pk_mul_f32 v[70:71], v[90:91], v[74:75] op_sel_hi:[0,1]
	v_mul_f32_e32 v74, 0xbfb8aa3b, v71
	v_exp_f32_e32 v74, v74
	v_add_f32_e32 v75, 1.0, v79
	v_rcp_f32_e32 v75, v75
	v_mul_f32_e32 v69, v69, v77
	v_add_f32_e32 v74, 1.0, v74
	v_rcp_f32_e32 v74, v74
	v_mul_f32_e32 v77, v68, v69
	v_mul_f32_e32 v68, v73, v75
	v_mul_f32_e32 v72, v72, v68
	v_mul_f32_e32 v68, v71, v74
	v_mul_f32_e32 v71, v70, v68
	v_or_b32_e32 v73, 48, v1
	v_cvt_pk_bf16_f32 v68, v84, v85
	v_cvt_pk_bf16_f32 v69, v80, v78
	v_cvt_pk_bf16_f32 v70, v76, v77
	v_cvt_pk_bf16_f32 v71, v72, v71
	v_mad_i64_i32 v[72:73], s[14:15], v73, s49, v[116:117]
	s_cmp_eq_u32 s20, 64
	v_lshl_add_u64 v[72:73], v[72:73], 0, v[2:3]
	global_store_dwordx4 v[72:73], v[68:71], off
	s_cbranch_scc1 .LBB0_584
	s_nop 0
	v_fmamk_f32 v68, v229, 0x3a800000, v226
	v_mul_f32_e32 v69, 0x4b800000, v68
	v_cmp_gt_f32_e32 vcc, s48, v68
	v_readlane_b32 s14, v255, 18
	v_readlane_b32 s15, v255, 19
	v_cndmask_b32_e32 v68, v68, v69, vcc
	v_rsq_f32_e32 v70, v68
	v_mov_b32_e32 v69, v60
	v_mov_b32_e32 v68, v64
	v_add_u32_e32 v71, 0x80, v1
	v_mul_f32_e32 v60, 0x45800000, v70
	v_cndmask_b32_e32 v64, v70, v60, vcc
	v_pk_mul_f32 v[68:69], v[64:65], v[68:69] op_sel_hi:[0,1]
	v_mul_f32_e32 v60, 0xbfb8aa3b, v69
	v_exp_f32_e32 v70, v60
	v_mov_b32_e32 v60, v65
	v_pk_mul_f32 v[60:61], v[64:65], v[60:61] op_sel_hi:[0,1]
	v_mul_f32_e32 v65, 0xbfb8aa3b, v61
	v_exp_f32_e32 v65, v65
	v_add_f32_e32 v70, 1.0, v70
	v_rcp_f32_e32 v70, v70
	v_add_f32_e32 v65, 1.0, v65
	v_rcp_f32_e32 v65, v65
	v_mul_f32_e32 v69, v69, v70
	v_mul_f32_e32 v70, v68, v69
	v_mov_b32_e32 v68, v66
	v_mov_b32_e32 v69, v62
	v_pk_mul_f32 v[68:69], v[64:65], v[68:69] op_sel_hi:[0,1]
	v_mul_f32_e32 v62, 0xbfb8aa3b, v69
	v_mul_f32_e32 v61, v61, v65
	v_exp_f32_e32 v65, v62
	v_mov_b32_e32 v62, v67
	v_mul_f32_e32 v67, v60, v61
	v_mov_b32_e32 v61, v52
	v_pk_mul_f32 v[62:63], v[64:65], v[62:63] op_sel_hi:[0,1]
	v_mul_f32_e32 v66, 0xbfb8aa3b, v63
	v_exp_f32_e32 v66, v66
	v_add_f32_e32 v60, 1.0, v65
	v_rcp_f32_e32 v65, v60
	v_add_f32_e32 v60, 1.0, v66
	v_rcp_f32_e32 v66, v60
	v_mov_b32_e32 v60, v56
	v_pk_mul_f32 v[60:61], v[64:65], v[60:61] op_sel_hi:[0,1]
	v_mul_f32_e32 v52, 0xbfb8aa3b, v61
	v_exp_f32_e32 v52, v52
	v_mul_f32_e32 v56, v69, v65
	v_mul_f32_e32 v65, v68, v56
	v_mul_f32_e32 v56, v63, v66
	v_add_f32_e32 v52, 1.0, v52
	v_rcp_f32_e32 v63, v52
	v_mov_b32_e32 v52, v57
	v_pk_mul_f32 v[52:53], v[64:65], v[52:53] op_sel_hi:[0,1]
	v_mul_f32_e32 v57, 0xbfb8aa3b, v53
	v_exp_f32_e32 v57, v57
	v_mul_f32_e32 v62, v62, v56
	v_mul_f32_e32 v56, v61, v63
	v_mul_f32_e32 v60, v60, v56
	v_add_f32_e32 v56, 1.0, v57
	v_rcp_f32_e32 v61, v56
	v_mov_b32_e32 v56, v58
	v_mov_b32_e32 v57, v54
	v_pk_mul_f32 v[56:57], v[64:65], v[56:57] op_sel_hi:[0,1]
	v_mul_f32_e32 v54, 0xbfb8aa3b, v57
	v_exp_f32_e32 v58, v54
	v_mov_b32_e32 v54, v59
	v_pk_mul_f32 v[54:55], v[64:65], v[54:55] op_sel_hi:[0,1]
	v_mul_f32_e32 v59, 0xbfb8aa3b, v55
	v_exp_f32_e32 v59, v59
	v_add_f32_e32 v58, 1.0, v58
	v_rcp_f32_e32 v58, v58
	v_mul_f32_e32 v53, v53, v61
	v_add_f32_e32 v59, 1.0, v59
	v_rcp_f32_e32 v59, v59
	v_mul_f32_e32 v52, v52, v53
	v_mul_f32_e32 v53, v57, v58
	v_mul_f32_e32 v53, v56, v53
	v_mul_f32_e32 v55, v55, v59
	v_mul_f32_e32 v57, v54, v55
	v_cvt_pk_bf16_f32 v54, v70, v67
	v_cvt_pk_bf16_f32 v55, v65, v62
	v_cvt_pk_bf16_f32 v56, v60, v52
	v_fmamk_f32 v52, v228, 0x3a800000, v226
	v_cvt_pk_bf16_f32 v57, v53, v57
	v_mul_f32_e32 v53, 0x4b800000, v52
	v_cmp_gt_f32_e32 vcc, s48, v52
	v_mov_b32_e32 v62, v48
	v_mov_b32_e32 v63, v44
	v_cndmask_b32_e32 v52, v52, v53, vcc
	v_rsq_f32_e32 v60, v52
	v_mov_b64_e32 v[52:53], s[14:15]
	v_mad_i64_i32 v[58:59], s[14:15], v71, s49, v[52:53]
	v_mul_f32_e32 v61, 0x45800000, v60
	v_cndmask_b32_e32 v60, v60, v61, vcc
	v_pk_mul_f32 v[62:63], v[60:61], v[62:63] op_sel_hi:[0,1]
	v_mul_f32_e32 v44, 0xbfb8aa3b, v63
	v_exp_f32_e32 v61, v44
	v_mov_b32_e32 v44, v49
	v_pk_mul_f32 v[44:45], v[60:61], v[44:45] op_sel_hi:[0,1]
	v_mul_f32_e32 v48, 0xbfb8aa3b, v45
	v_exp_f32_e32 v64, v48
	v_lshl_add_u64 v[48:49], v[58:59], 0, v[2:3]
	v_add_f32_e32 v58, 1.0, v61
	v_rcp_f32_e32 v58, v58
	global_store_dwordx4 v[48:49], v[54:57], off
	v_mov_b32_e32 v49, v46
	v_add_f32_e32 v59, 1.0, v64
	v_mul_f32_e32 v48, v63, v58
	v_mul_f32_e32 v54, v62, v48
	v_mov_b32_e32 v48, v50
	v_pk_mul_f32 v[48:49], v[60:61], v[48:49] op_sel_hi:[0,1]
	v_mul_f32_e32 v46, 0xbfb8aa3b, v49
	v_exp_f32_e32 v50, v46
	v_mov_b32_e32 v46, v51
	v_rcp_f32_e32 v59, v59
	v_pk_mul_f32 v[46:47], v[60:61], v[46:47] op_sel_hi:[0,1]
	v_mul_f32_e32 v51, 0xbfb8aa3b, v47
	v_exp_f32_e32 v51, v51
	v_mul_f32_e32 v45, v45, v59
	v_mul_f32_e32 v55, v44, v45
	v_add_f32_e32 v44, 1.0, v50
	v_rcp_f32_e32 v50, v44
	v_add_f32_e32 v44, 1.0, v51
	v_rcp_f32_e32 v51, v44
	v_mov_b32_e32 v44, v40
	v_mov_b32_e32 v45, v36
	v_pk_mul_f32 v[44:45], v[60:61], v[44:45] op_sel_hi:[0,1]
	v_mul_f32_e32 v36, 0xbfb8aa3b, v45
	v_exp_f32_e32 v36, v36
	v_mul_f32_e32 v40, v49, v50
	v_mul_f32_e32 v48, v48, v40
	v_mul_f32_e32 v40, v47, v51
	v_add_f32_e32 v36, 1.0, v36
	v_rcp_f32_e32 v47, v36
	v_mov_b32_e32 v36, v41
	v_pk_mul_f32 v[36:37], v[60:61], v[36:37] op_sel_hi:[0,1]
	v_mul_f32_e32 v41, 0xbfb8aa3b, v37
	v_exp_f32_e32 v41, v41
	v_mul_f32_e32 v46, v46, v40
	v_mul_f32_e32 v40, v45, v47
	v_mul_f32_e32 v44, v44, v40
	v_add_f32_e32 v40, 1.0, v41
	v_rcp_f32_e32 v45, v40
	v_mov_b32_e32 v40, v42
	v_mov_b32_e32 v41, v38
	v_pk_mul_f32 v[40:41], v[60:61], v[40:41] op_sel_hi:[0,1]
	v_mul_f32_e32 v38, 0xbfb8aa3b, v41
	v_exp_f32_e32 v42, v38
	v_mov_b32_e32 v38, v43
	v_pk_mul_f32 v[38:39], v[60:61], v[38:39] op_sel_hi:[0,1]
	v_mul_f32_e32 v43, 0xbfb8aa3b, v39
	v_exp_f32_e32 v43, v43
	v_add_f32_e32 v42, 1.0, v42
	v_rcp_f32_e32 v42, v42
	v_mul_f32_e32 v37, v37, v45
	v_add_f32_e32 v43, 1.0, v43
	v_rcp_f32_e32 v43, v43
	v_mul_f32_e32 v45, v36, v37
	v_mul_f32_e32 v36, v41, v42
	v_fmamk_f32 v42, v227, 0x3a800000, v226
	v_mul_f32_e32 v40, v40, v36
	v_mul_f32_e32 v36, v39, v43
	v_mul_f32_e32 v43, 0x4b800000, v42
	v_cmp_gt_f32_e32 vcc, s48, v42
	v_mul_f32_e32 v39, v38, v36
	v_cvt_pk_bf16_f32 v36, v54, v55
	v_cvt_pk_bf16_f32 v37, v48, v46
	v_cvt_pk_bf16_f32 v38, v44, v45
	v_mov_b32_e32 v44, v32
	v_cndmask_b32_e32 v42, v42, v43, vcc
	v_rsq_f32_e32 v42, v42
	v_mov_b32_e32 v45, v28
	v_add_u32_e32 v41, 0x90, v1
	v_cvt_pk_bf16_f32 v39, v40, v39
	v_mul_f32_e32 v43, 0x45800000, v42
	v_cndmask_b32_e32 v42, v42, v43, vcc
	v_pk_mul_f32 v[44:45], v[42:43], v[44:45] op_sel_hi:[0,1]
	v_mul_f32_e32 v28, 0xbfb8aa3b, v45
	v_exp_f32_e32 v43, v28
	v_mov_b32_e32 v28, v33
	v_mad_i64_i32 v[40:41], s[14:15], v41, s49, v[52:53]
	v_pk_mul_f32 v[28:29], v[42:43], v[28:29] op_sel_hi:[0,1]
	v_mul_f32_e32 v32, 0xbfb8aa3b, v29
	v_exp_f32_e32 v46, v32
	v_lshl_add_u64 v[32:33], v[40:41], 0, v[2:3]
	v_add_f32_e32 v40, 1.0, v43
	v_rcp_f32_e32 v40, v40
	global_store_dwordx4 v[32:33], v[36:39], off
	v_mov_b32_e32 v33, v30
	v_add_f32_e32 v41, 1.0, v46
	v_mul_f32_e32 v32, v45, v40
	v_mul_f32_e32 v36, v44, v32
	v_mov_b32_e32 v32, v34
	v_pk_mul_f32 v[32:33], v[42:43], v[32:33] op_sel_hi:[0,1]
	v_mul_f32_e32 v30, 0xbfb8aa3b, v33
	v_exp_f32_e32 v34, v30
	v_mov_b32_e32 v30, v35
	v_rcp_f32_e32 v41, v41
	v_pk_mul_f32 v[30:31], v[42:43], v[30:31] op_sel_hi:[0,1]
	v_mul_f32_e32 v35, 0xbfb8aa3b, v31
	v_exp_f32_e32 v35, v35
	v_mul_f32_e32 v29, v29, v41
	v_mul_f32_e32 v37, v28, v29
	v_add_f32_e32 v28, 1.0, v34
	v_rcp_f32_e32 v34, v28
	v_add_f32_e32 v28, 1.0, v35
	v_rcp_f32_e32 v35, v28
	v_mov_b32_e32 v28, v24
	v_mov_b32_e32 v29, v20
	v_pk_mul_f32 v[28:29], v[42:43], v[28:29] op_sel_hi:[0,1]
	v_mul_f32_e32 v20, 0xbfb8aa3b, v29
	v_exp_f32_e32 v20, v20
	v_mul_f32_e32 v24, v33, v34
	v_mul_f32_e32 v32, v32, v24
	v_mul_f32_e32 v24, v31, v35
	v_add_f32_e32 v20, 1.0, v20
	v_rcp_f32_e32 v31, v20
	v_mov_b32_e32 v20, v25
	v_pk_mul_f32 v[20:21], v[42:43], v[20:21] op_sel_hi:[0,1]
	v_mul_f32_e32 v25, 0xbfb8aa3b, v21
	v_exp_f32_e32 v25, v25
	v_mul_f32_e32 v30, v30, v24
	v_mul_f32_e32 v24, v29, v31
	v_mul_f32_e32 v28, v28, v24
	v_add_f32_e32 v24, 1.0, v25
	v_rcp_f32_e32 v29, v24
	v_mov_b32_e32 v24, v26
	v_mov_b32_e32 v25, v22
	v_pk_mul_f32 v[24:25], v[42:43], v[24:25] op_sel_hi:[0,1]
	v_mul_f32_e32 v22, 0xbfb8aa3b, v25
	v_exp_f32_e32 v26, v22
	v_mov_b32_e32 v22, v27
	v_pk_mul_f32 v[22:23], v[42:43], v[22:23] op_sel_hi:[0,1]
	v_mul_f32_e32 v27, 0xbfb8aa3b, v23
	v_exp_f32_e32 v27, v27
	v_add_f32_e32 v26, 1.0, v26
	v_rcp_f32_e32 v26, v26
	v_mul_f32_e32 v21, v21, v29
	v_add_f32_e32 v27, 1.0, v27
	v_rcp_f32_e32 v27, v27
	v_mul_f32_e32 v29, v20, v21
	v_mul_f32_e32 v20, v25, v26
	v_fmamk_f32 v26, v218, 0x3a800000, v226
	v_mul_f32_e32 v24, v24, v20
	v_mul_f32_e32 v20, v23, v27
	v_mul_f32_e32 v27, 0x4b800000, v26
	v_cmp_gt_f32_e32 vcc, s48, v26
	v_mul_f32_e32 v23, v22, v20
	v_cvt_pk_bf16_f32 v20, v36, v37
	v_cvt_pk_bf16_f32 v21, v32, v30
	v_cvt_pk_bf16_f32 v22, v28, v29
	v_mov_b32_e32 v28, v16
	v_cndmask_b32_e32 v26, v26, v27, vcc
	v_rsq_f32_e32 v26, v26
	v_mov_b32_e32 v29, v12
	v_add_u32_e32 v25, 0xa0, v1
	v_cvt_pk_bf16_f32 v23, v24, v23
	v_mul_f32_e32 v27, 0x45800000, v26
	v_cndmask_b32_e32 v26, v26, v27, vcc
	v_pk_mul_f32 v[28:29], v[26:27], v[28:29] op_sel_hi:[0,1]
	v_mul_f32_e32 v12, 0xbfb8aa3b, v29
	v_exp_f32_e32 v27, v12
	v_mov_b32_e32 v12, v17
	v_mad_i64_i32 v[24:25], s[14:15], v25, s49, v[52:53]
	v_pk_mul_f32 v[12:13], v[26:27], v[12:13] op_sel_hi:[0,1]
	v_mul_f32_e32 v16, 0xbfb8aa3b, v13
	v_exp_f32_e32 v30, v16
	v_lshl_add_u64 v[16:17], v[24:25], 0, v[2:3]
	v_add_f32_e32 v24, 1.0, v27
	v_rcp_f32_e32 v24, v24
	global_store_dwordx4 v[16:17], v[20:23], off
	v_mov_b32_e32 v17, v14
	v_add_f32_e32 v25, 1.0, v30
	v_mul_f32_e32 v16, v29, v24
	v_mul_f32_e32 v20, v28, v16
	v_mov_b32_e32 v16, v18
	v_pk_mul_f32 v[16:17], v[26:27], v[16:17] op_sel_hi:[0,1]
	v_mul_f32_e32 v14, 0xbfb8aa3b, v17
	v_exp_f32_e32 v18, v14
	v_mov_b32_e32 v14, v19
	v_rcp_f32_e32 v25, v25
	v_pk_mul_f32 v[14:15], v[26:27], v[14:15] op_sel_hi:[0,1]
	v_mul_f32_e32 v19, 0xbfb8aa3b, v15
	v_exp_f32_e32 v19, v19
	v_mul_f32_e32 v13, v13, v25
	v_mul_f32_e32 v21, v12, v13
	v_add_f32_e32 v12, 1.0, v18
	v_rcp_f32_e32 v18, v12
	v_add_f32_e32 v12, 1.0, v19
	v_rcp_f32_e32 v19, v12
	v_mov_b32_e32 v12, v8
	v_mov_b32_e32 v13, v4
	v_pk_mul_f32 v[12:13], v[26:27], v[12:13] op_sel_hi:[0,1]
	v_mul_f32_e32 v4, 0xbfb8aa3b, v13
	v_exp_f32_e32 v4, v4
	v_mul_f32_e32 v8, v17, v18
	v_mul_f32_e32 v16, v16, v8
	v_mul_f32_e32 v8, v15, v19
	v_add_f32_e32 v4, 1.0, v4
	v_rcp_f32_e32 v15, v4
	v_mov_b32_e32 v4, v9
	v_pk_mul_f32 v[4:5], v[26:27], v[4:5] op_sel_hi:[0,1]
	v_mul_f32_e32 v9, 0xbfb8aa3b, v5
	v_exp_f32_e32 v9, v9
	v_mul_f32_e32 v14, v14, v8
	v_mul_f32_e32 v8, v13, v15
	v_mul_f32_e32 v12, v12, v8
	v_add_f32_e32 v8, 1.0, v9
	v_rcp_f32_e32 v13, v8
	v_mov_b32_e32 v8, v10
	v_mov_b32_e32 v9, v6
	v_pk_mul_f32 v[8:9], v[26:27], v[8:9] op_sel_hi:[0,1]
	v_mul_f32_e32 v6, 0xbfb8aa3b, v9
	v_exp_f32_e32 v10, v6
	v_mov_b32_e32 v6, v11
	v_pk_mul_f32 v[6:7], v[26:27], v[6:7] op_sel_hi:[0,1]
	v_mul_f32_e32 v11, 0xbfb8aa3b, v7
	v_exp_f32_e32 v11, v11
	v_add_f32_e32 v10, 1.0, v10
	v_rcp_f32_e32 v10, v10
	v_mul_f32_e32 v5, v5, v13
	v_add_f32_e32 v11, 1.0, v11
	v_rcp_f32_e32 v11, v11
	v_mul_f32_e32 v13, v4, v5
	v_mul_f32_e32 v4, v9, v10
	v_mul_f32_e32 v8, v8, v4
	v_mul_f32_e32 v4, v7, v11
	v_mul_f32_e32 v7, v6, v4
	v_add_u32_e32 v1, 0xb0, v1
	v_cvt_pk_bf16_f32 v4, v20, v21
	v_cvt_pk_bf16_f32 v5, v16, v14
	v_cvt_pk_bf16_f32 v6, v12, v13
	v_cvt_pk_bf16_f32 v7, v8, v7
	v_mad_i64_i32 v[8:9], s[14:15], v1, s49, v[52:53]
	v_lshl_add_u64 v[2:3], v[8:9], 0, v[2:3]
	global_store_dwordx4 v[2:3], v[4:7], off

.LBB0_892:
	s_lshl_b32 s4, s20, 8
	s_cmp_lg_u32 s8, 64
	s_mov_b64 s[14:15], -1
	s_cbranch_scc0 .LBB0_926
	s_waitcnt vmcnt(6)
	v_fmamk_f32 v1, v244, 0x3a800000, v233
	v_mul_f32_e32 v3, 0x4b800000, v1
	v_cmp_gt_f32_e32 vcc, s58, v1
	s_add_i32 s1, s4, 0xfffff800
	s_cmp_gt_i32 s20, 7
	v_cndmask_b32_e32 v1, v1, v3, vcc
	v_rsq_f32_e32 v1, v1
	s_cselect_b64 s[36:37], -1, 0
	s_and_b64 s[14:15], s[36:37], exec
	s_mov_b32 s2, 0x11be7300
	s_cselect_b32 s2, s2, 0xdae7300
	s_cselect_b32 s1, s1, s4
	s_add_u32 s14, s82, s2
	v_or_b32_e32 v2, s1, v205
	v_lshl_add_u32 v132, s8, 8, v204
	v_mul_f32_e32 v133, 0x45800000, v1
	s_addc_u32 s15, s83, 0
	v_ashrrev_i32_e32 v3, 31, v2
	v_cndmask_b32_e32 v146, v1, v133, vcc
	v_ashrrev_i32_e32 v133, 31, v132
	v_lshl_add_u64 v[2:3], v[2:3], 1, s[14:15]
	v_lshlrev_b64 v[134:135], 12, v[132:133]
	v_lshl_add_u64 v[154:155], v[2:3], 0, v[134:135]
	v_pk_mul_f32 v[134:135], v[146:147], v[72:73] op_sel_hi:[0,1]
	v_pk_mul_f32 v[136:137], v[146:147], v[68:69] op_sel_hi:[0,1]
	v_mul_f32_e32 v1, 0x3d372713, v134
	v_mul_f32_e32 v138, 0x3d372713, v136
	v_mul_f32_e32 v139, 0x3d372713, v135
	v_fma_f32 v1, v134, v1, 1.0
	v_fma_f32 v138, v136, v138, 1.0
	v_fma_f32 v139, v135, v139, 1.0
	v_mul_f32_e32 v1, v134, v1
	v_mul_f32_e32 v138, v136, v138
	v_mul_f32_e32 v139, v135, v139
	v_mul_f32_e32 v1, 0xc0135761, v1
	v_mul_f32_e32 v138, 0xc0135761, v138
	v_mul_f32_e32 v139, 0xc0135761, v139
	v_exp_f32_e32 v1, v1
	v_exp_f32_e32 v138, v138
	v_exp_f32_e32 v139, v139
	v_mul_f32_e32 v144, 0x3d372713, v137
	v_add_f32_e32 v1, 1.0, v1
	v_add_f32_e32 v138, 1.0, v138
	v_add_f32_e32 v139, 1.0, v139
	v_rcp_f32_e32 v1, v1
	v_rcp_f32_e32 v138, v138
	v_rcp_f32_e32 v139, v139
	v_fma_f32 v144, v137, v144, 1.0
	v_mul_f32_e32 v144, v137, v144
	v_mul_f32_e32 v144, 0xc0135761, v144
	v_pk_mul_f32 v[140:141], v[146:147], v[74:75] op_sel_hi:[0,1]
	v_pk_mul_f32 v[142:143], v[146:147], v[70:71] op_sel_hi:[0,1]
	v_exp_f32_e32 v144, v144
	v_mul_f32_e32 v134, v134, v1
	v_mul_f32_e32 v1, v136, v138
	v_mul_f32_e32 v135, v135, v139
	v_mul_f32_e32 v138, 0x3d372713, v140
	v_mul_f32_e32 v139, 0x3d372713, v142
	v_fma_f32 v138, v140, v138, 1.0
	v_fma_f32 v139, v142, v139, 1.0
	v_mul_f32_e32 v138, v140, v138
	v_mul_f32_e32 v139, v142, v139
	v_add_f32_e32 v136, 1.0, v144
	v_mul_f32_e32 v138, 0xc0135761, v138
	v_mul_f32_e32 v139, 0xc0135761, v139
	v_rcp_f32_e32 v136, v136
	v_exp_f32_e32 v138, v138
	v_exp_f32_e32 v139, v139
	v_mul_f32_e32 v144, 0x3d372713, v143
	v_mul_f32_e32 v136, v137, v136
	v_add_f32_e32 v137, 1.0, v138
	v_add_f32_e32 v138, 1.0, v139
	v_mul_f32_e32 v139, 0x3d372713, v141
	v_fma_f32 v139, v141, v139, 1.0
	v_mul_f32_e32 v139, v141, v139
	v_fma_f32 v144, v143, v144, 1.0
	v_mul_f32_e32 v139, 0xc0135761, v139
	v_mul_f32_e32 v144, v143, v144
	v_exp_f32_e32 v139, v139
	v_mul_f32_e32 v144, 0xc0135761, v144
	v_exp_f32_e32 v144, v144
	v_rcp_f32_e32 v137, v137
	v_add_f32_e32 v139, 1.0, v139
	v_rcp_f32_e32 v145, v139
	v_add_f32_e32 v139, 1.0, v144
	v_rcp_f32_e32 v138, v138
	v_rcp_f32_e32 v144, v139
	v_mul_f32_e32 v139, v140, v137
	v_mul_f32_e32 v140, v141, v145
	v_mul_f32_e32 v137, v142, v138
	v_mul_f32_e32 v138, v143, v144
	v_cvt_pk_bf16_f32 v142, v134, v135
	v_cvt_pk_bf16_f32 v143, v139, v140
	v_cvt_pk_bf16_f32 v144, v1, v136
	v_cvt_pk_bf16_f32 v145, v137, v138
	global_store_dwordx4 v[154:155], v[142:145], off
	v_pk_mul_f32 v[148:149], v[146:147], v[66:67] op_sel_hi:[0,1]
	v_pk_mul_f32 v[150:151], v[146:147], v[62:63] op_sel_hi:[0,1]
	v_pk_mul_f32 v[142:143], v[146:147], v[64:65] op_sel_hi:[0,1]
	v_pk_mul_f32 v[144:145], v[146:147], v[60:61] op_sel_hi:[0,1]
	v_mul_f32_e32 v141, 0x3d372713, v142
	v_mul_f32_e32 v146, 0x3d372713, v144
	v_mul_f32_e32 v147, 0x3d372713, v143
	v_fma_f32 v141, v142, v141, 1.0
	v_fma_f32 v146, v144, v146, 1.0
	v_fma_f32 v147, v143, v147, 1.0
	v_mul_f32_e32 v141, v142, v141
	v_mul_f32_e32 v146, v144, v146
	v_mul_f32_e32 v147, v143, v147
	v_mul_f32_e32 v141, 0xc0135761, v141
	v_mul_f32_e32 v146, 0xc0135761, v146
	v_mul_f32_e32 v147, 0xc0135761, v147
	v_exp_f32_e32 v141, v141
	v_exp_f32_e32 v146, v146
	v_exp_f32_e32 v147, v147
	v_mul_f32_e32 v152, 0x3d372713, v145
	v_add_f32_e32 v141, 1.0, v141
	v_add_f32_e32 v146, 1.0, v146
	v_add_f32_e32 v147, 1.0, v147
	v_rcp_f32_e32 v141, v141
	v_rcp_f32_e32 v146, v146
	v_rcp_f32_e32 v147, v147
	v_fma_f32 v152, v145, v152, 1.0
	v_mul_f32_e32 v152, v145, v152
	v_mul_f32_e32 v152, 0xc0135761, v152
	v_exp_f32_e32 v152, v152
	v_mul_f32_e32 v142, v142, v141
	v_mul_f32_e32 v141, v144, v146
	v_mul_f32_e32 v143, v143, v147
	v_mul_f32_e32 v146, 0x3d372713, v148
	v_mul_f32_e32 v147, 0x3d372713, v150
	v_fma_f32 v146, v148, v146, 1.0
	v_fma_f32 v147, v150, v147, 1.0
	v_mul_f32_e32 v146, v148, v146
	v_mul_f32_e32 v147, v150, v147
	v_add_f32_e32 v144, 1.0, v152
	v_mul_f32_e32 v146, 0xc0135761, v146
	v_mul_f32_e32 v147, 0xc0135761, v147
	v_rcp_f32_e32 v144, v144
	v_exp_f32_e32 v146, v146
	v_exp_f32_e32 v147, v147
	v_mul_f32_e32 v152, 0x3d372713, v151
	v_mul_f32_e32 v144, v145, v144
	v_add_f32_e32 v145, 1.0, v146
	v_add_f32_e32 v146, 1.0, v147
	v_mul_f32_e32 v147, 0x3d372713, v149
	v_fma_f32 v147, v149, v147, 1.0
	v_mul_f32_e32 v147, v149, v147
	v_fma_f32 v152, v151, v152, 1.0
	v_mul_f32_e32 v147, 0xc0135761, v147
	v_mul_f32_e32 v152, v151, v152
	v_exp_f32_e32 v147, v147
	v_mul_f32_e32 v152, 0xc0135761, v152
	v_exp_f32_e32 v152, v152
	v_rcp_f32_e32 v145, v145
	v_add_f32_e32 v147, 1.0, v147
	v_rcp_f32_e32 v153, v147
	v_add_f32_e32 v147, 1.0, v152
	v_rcp_f32_e32 v146, v146
	v_rcp_f32_e32 v152, v147
	s_cmp_lt_i32 s20, 8
	v_mul_f32_e32 v147, v148, v145
	v_mul_f32_e32 v145, v150, v146
	v_mul_f32_e32 v148, v149, v153
	v_mul_f32_e32 v146, v151, v152
	v_cvt_pk_bf16_f32 v150, v142, v143
	v_cvt_pk_bf16_f32 v151, v147, v148
	v_cvt_pk_bf16_f32 v152, v141, v144
	v_cvt_pk_bf16_f32 v153, v145, v146
	global_store_dwordx4 v[154:155], v[150:153], off offset:256
	s_cbranch_scc1 .LBB0_897
	v_mul_f32_e32 v135, v135, v135
	v_fmac_f32_e32 v135, v134, v134
	v_mul_f32_e32 v134, v140, v140
	v_fmac_f32_e32 v134, v139, v139
	v_add_f32_e32 v134, v135, v134
	v_mul_f32_e32 v135, v136, v136
	v_fmac_f32_e32 v135, v1, v1
	v_mul_f32_e32 v1, v138, v138
	v_fmac_f32_e32 v1, v137, v137
	v_add_f32_e32 v1, v135, v1
	v_add_f32_e32 v1, v1, v134
	v_mul_f32_e32 v134, v143, v143
	v_mul_f32_e32 v135, v148, v148
	v_fmac_f32_e32 v134, v142, v142
	v_fmac_f32_e32 v135, v147, v147
	v_add_f32_e32 v134, v134, v135
	v_mul_f32_e32 v135, v144, v144
	v_mul_f32_e32 v136, v146, v146
	v_fmac_f32_e32 v135, v141, v141
	v_fmac_f32_e32 v136, v145, v145
	v_add_f32_e32 v135, v135, v136
	v_add_f32_e32 v134, v135, v134
	v_add_f32_e32 v1, v134, v1
	ds_bpermute_b32 v134, v231, v1
	s_waitcnt lgkmcnt(0)
	v_add_f32_e32 v1, v1, v134
	ds_bpermute_b32 v134, v232, v1
	s_and_saveexec_b64 s[8:9], s[12:13]
	s_cbranch_execz .LBB0_896
	s_lshl_b32 s1, s20, 2
	v_readlane_b32 s38, v255, 22
	s_waitcnt lgkmcnt(0)
	v_add_f32_e32 v1, v1, v134
	s_sub_i32 s14, s1, 32
	v_lshlrev_b64 v[134:135], 7, v[132:133]
	v_readlane_b32 s39, v255, 23
	s_ashr_i32 s15, s14, 31
	s_nop 0
	v_lshl_add_u64 v[134:135], s[38:39], 0, v[134:135]
	v_lshl_add_u64 v[134:135], s[14:15], 2, v[134:135]
	s_lshl_b32 s14, s50, 2
	s_mov_b32 s15, s23
	v_lshl_add_u64 v[134:135], v[134:135], 0, s[14:15]
	global_store_dword v[134:135], v1, off

.Lmy_mix1_wdone:
	s_waitcnt vmcnt(0)
	s_waitcnt lgkmcnt(0)
	s_barrier
	ds_read_b64_tr_b16 v[0:1], v116
	ds_read_b64_tr_b16 v[2:3], v116 offset:2048
	ds_read_b128 v[4:7], v117
	s_waitcnt lgkmcnt(0)
	v_mfma_f32_32x32x16_bf16 v[48:63], v[0:3], v[4:7], 0
	ds_read_b128 v[4:7], v117 offset:8192
	s_lshl_b32 s78, s1, 1
	s_mov_b32 s79, s5
	v_or_b32_e32 v94, s90, v65
	v_or_b32_e32 v79, s4, v65
	v_ashrrev_i32_e32 v95, 31, v94
	v_lshlrev_b32_e32 v79, 2, v79
	s_waitcnt lgkmcnt(0)
	v_mfma_f32_32x32x16_bf16 v[32:47], v[0:3], v[4:7], 0
	ds_read_b128 v[4:7], v117 offset:16384
	v_lshlrev_b64 v[94:95], 12, v[94:95]
	s_add_i32 s93, s93, s0
	s_add_i32 s85, s85, s94
	s_waitcnt lgkmcnt(0)
	v_mfma_f32_32x32x16_bf16 v[16:31], v[0:3], v[4:7], 0
	ds_read_b128 v[4:7], v117 offset:24576
	ds_read_b64_tr_b16 v[90:91], v116 offset:8192
	ds_read_b64_tr_b16 v[92:93], v116 offset:10240
	ds_read_b128 v[126:129], v118
	s_waitcnt lgkmcnt(0)
	v_mfma_f32_32x32x16_bf16 v[48:63], v[90:93], v[126:129], v[48:63]
	ds_read_b128 v[126:129], v118 offset:8192
	s_waitcnt lgkmcnt(0)
	v_mfma_f32_32x32x16_bf16 v[32:47], v[90:93], v[126:129], v[32:47]
	ds_read_b128 v[126:129], v118 offset:16384
	v_mfma_f32_32x32x16_bf16 v[0:15], v[0:3], v[4:7], 0
	s_waitcnt lgkmcnt(0)
	v_mfma_f32_32x32x16_bf16 v[16:31], v[90:93], v[126:129], v[16:31]
	ds_read_b128 v[126:129], v118 offset:24576
	s_waitcnt lgkmcnt(0)
	v_mfma_f32_32x32x16_bf16 v[0:15], v[90:93], v[126:129], v[0:15]
	ds_read_b64_tr_b16 v[90:91], v116 offset:16384
	ds_read_b64_tr_b16 v[92:93], v116 offset:18432
	ds_read_b128 v[126:129], v119 offset:8192
	s_waitcnt lgkmcnt(0)
	v_mfma_f32_32x32x16_bf16 v[32:47], v[90:93], v[126:129], v[32:47]
	ds_read_b128 v[126:129], v119 offset:16384
	s_waitcnt lgkmcnt(0)
	v_mfma_f32_32x32x16_bf16 v[16:31], v[90:93], v[126:129], v[16:31]
	ds_read_b128 v[126:129], v119 offset:24576
	s_waitcnt lgkmcnt(0)
	v_mfma_f32_32x32x16_bf16 v[0:15], v[90:93], v[126:129], v[0:15]
	ds_read_b64_tr_b16 v[90:91], v116 offset:24576
	ds_read_b64_tr_b16 v[92:93], v116 offset:26624
	ds_read_b128 v[126:129], v120 offset:8192
	s_waitcnt lgkmcnt(0)
	v_mfma_f32_32x32x16_bf16 v[32:47], v[90:93], v[126:129], v[32:47]
	ds_read_b128 v[126:129], v120 offset:16384
	s_waitcnt lgkmcnt(0)
	v_mfma_f32_32x32x16_bf16 v[16:31], v[90:93], v[126:129], v[16:31]
	ds_read_b128 v[126:129], v120 offset:24576
	s_waitcnt lgkmcnt(0)
	v_mfma_f32_32x32x16_bf16 v[0:15], v[90:93], v[126:129], v[0:15]
	ds_read_b64_tr_b16 v[90:91], v116 offset:32768
	ds_read_b64_tr_b16 v[92:93], v116 offset:34816
	ds_read_b128 v[126:129], v121 offset:16384
	s_waitcnt lgkmcnt(0)
	v_mfma_f32_32x32x16_bf16 v[16:31], v[90:93], v[126:129], v[16:31]
	ds_read_b128 v[126:129], v121 offset:24576
	s_waitcnt lgkmcnt(0)
	v_mfma_f32_32x32x16_bf16 v[0:15], v[90:93], v[126:129], v[0:15]
	ds_read_b64_tr_b16 v[90:91], v116 offset:40960
	ds_read_b64_tr_b16 v[92:93], v116 offset:43008
	ds_read_b128 v[126:129], v122 offset:16384
	s_waitcnt lgkmcnt(0)
	v_mfma_f32_32x32x16_bf16 v[16:31], v[90:93], v[126:129], v[16:31]
	ds_read_b128 v[126:129], v122 offset:24576
	s_waitcnt lgkmcnt(0)
	v_mfma_f32_32x32x16_bf16 v[0:15], v[90:93], v[126:129], v[0:15]
	ds_read_b64_tr_b16 v[90:91], v116 offset:49152
	ds_read_b64_tr_b16 v[92:93], v116 offset:51200
	ds_read_b128 v[126:129], v123 offset:24576
	s_waitcnt lgkmcnt(0)
	v_mfma_f32_32x32x16_bf16 v[0:15], v[90:93], v[126:129], v[0:15]
	ds_read_b64_tr_b16 v[90:91], v116 offset:57344
	ds_read_b64_tr_b16 v[92:93], v116 offset:59392
	ds_read_b128 v[126:129], v124 offset:24576
	global_load_dword v79, v79, s[8:9]
	s_waitcnt lgkmcnt(0)
	v_mfma_f32_32x32x16_bf16 v[0:15], v[90:93], v[126:129], v[0:15]
	v_lshl_add_u64 v[92:93], v[72:73], 0, s[78:79]
	s_lshl_b32 s78, s1, 2
	v_lshl_add_u64 v[90:91], v[74:75], 0, s[78:79]
	v_lshl_add_u64 v[94:95], v[92:93], 0, v[94:95]
	s_cmpk_gt_i32 s93, 0x3ff
	global_load_dwordx4 v[136:139], v[90:91], off
	global_load_dwordx4 v[140:143], v[90:91], off offset:32
	global_load_dwordx4 v[144:147], v[90:91], off offset:64
	global_load_dwordx4 v[148:151], v[90:91], off offset:96
	global_load_dwordx2 v[160:161], v[94:95], off
	global_load_dwordx2 v[162:163], v[94:95], off offset:16
	global_load_dwordx2 v[164:165], v[94:95], off offset:32
	global_load_dwordx2 v[166:167], v[94:95], off offset:48
	v_or_b32_e32 v152, s90, v108
	v_ashrrev_i32_e32 v153, 31, v152
	v_lshlrev_b64 v[152:153], 12, v[152:153]
	v_lshl_add_u64 v[152:153], v[92:93], 0, v[152:153]
	v_or_b32_e32 v132, s4, v108
	v_lshlrev_b32_e32 v132, 2, v132
	global_load_dword v133, v132, s[8:9]
	global_load_dwordx2 v[168:169], v[152:153], off
	global_load_dwordx2 v[170:171], v[152:153], off offset:16
	global_load_dwordx2 v[172:173], v[152:153], off offset:32
	global_load_dwordx2 v[174:175], v[152:153], off offset:48
	v_or_b32_e32 v154, s90, v109
	v_ashrrev_i32_e32 v155, 31, v154
	v_lshlrev_b64 v[154:155], 12, v[154:155]
	v_lshl_add_u64 v[154:155], v[92:93], 0, v[154:155]
	v_or_b32_e32 v132, s4, v109
	v_lshlrev_b32_e32 v132, 2, v132
	global_load_dword v134, v132, s[8:9]
	global_load_dwordx2 v[176:177], v[154:155], off
	global_load_dwordx2 v[178:179], v[154:155], off offset:16
	global_load_dwordx2 v[180:181], v[154:155], off offset:32
	global_load_dwordx2 v[182:183], v[154:155], off offset:48
	v_or_b32_e32 v156, s90, v110
	v_ashrrev_i32_e32 v157, 31, v156
	v_lshlrev_b64 v[156:157], 12, v[156:157]
	v_lshl_add_u64 v[156:157], v[92:93], 0, v[156:157]
	v_or_b32_e32 v132, s4, v110
	v_lshlrev_b32_e32 v132, 2, v132
	global_load_dword v135, v132, s[8:9]
	global_load_dwordx2 v[184:185], v[156:157], off
	global_load_dwordx2 v[186:187], v[156:157], off offset:16
	global_load_dwordx2 v[188:189], v[156:157], off offset:32
	global_load_dwordx2 v[190:191], v[156:157], off offset:48
	s_waitcnt vmcnt(15)
	v_fma_f32 v48, v48, v136, v79
	v_lshlrev_b32_e32 v192, 16, v160
	v_and_b32_e32 v193, 0xffff0000, v160
	v_fma_f32 v49, v49, v137, v79
	v_mul_f32_e32 v48, v48, v192
	v_mul_f32_e32 v49, v49, v193
	v_lshlrev_b32_e32 v194, 16, v161
	v_and_b32_e32 v195, 0xffff0000, v161
	v_fma_f32 v50, v50, v138, v79
	v_fma_f32 v51, v51, v139, v79
	v_mul_f32_e32 v50, v50, v194
	v_mul_f32_e32 v51, v51, v195
	v_cvt_pk_bf16_f32 v48, v48, v49
	v_cvt_pk_bf16_f32 v49, v50, v51
	global_store_dwordx2 v[94:95], v[48:49], off
	v_fma_f32 v52, v52, v140, v79
	v_lshlrev_b32_e32 v192, 16, v162
	v_and_b32_e32 v193, 0xffff0000, v162
	v_fma_f32 v53, v53, v141, v79
	v_mul_f32_e32 v52, v52, v192
	v_mul_f32_e32 v53, v53, v193
	v_lshlrev_b32_e32 v194, 16, v163
	v_and_b32_e32 v195, 0xffff0000, v163
	v_fma_f32 v54, v54, v142, v79
	v_fma_f32 v55, v55, v143, v79
	v_mul_f32_e32 v54, v54, v194
	v_mul_f32_e32 v55, v55, v195
	v_cvt_pk_bf16_f32 v52, v52, v53
	v_cvt_pk_bf16_f32 v53, v54, v55
	global_store_dwordx2 v[94:95], v[52:53], off offset:16
	v_fma_f32 v56, v56, v144, v79
	v_lshlrev_b32_e32 v192, 16, v164
	v_and_b32_e32 v193, 0xffff0000, v164
	v_fma_f32 v57, v57, v145, v79
	v_mul_f32_e32 v56, v56, v192
	v_mul_f32_e32 v57, v57, v193
	v_lshlrev_b32_e32 v194, 16, v165
	v_and_b32_e32 v195, 0xffff0000, v165
	v_fma_f32 v58, v58, v146, v79
	v_fma_f32 v59, v59, v147, v79
	v_mul_f32_e32 v58, v58, v194
	v_mul_f32_e32 v59, v59, v195
	v_cvt_pk_bf16_f32 v56, v56, v57
	v_cvt_pk_bf16_f32 v57, v58, v59
	global_store_dwordx2 v[94:95], v[56:57], off offset:32
	v_fma_f32 v60, v60, v148, v79
	v_lshlrev_b32_e32 v192, 16, v166
	v_and_b32_e32 v193, 0xffff0000, v166
	v_fma_f32 v61, v61, v149, v79
	v_mul_f32_e32 v60, v60, v192
	v_mul_f32_e32 v61, v61, v193
	v_lshlrev_b32_e32 v194, 16, v167
	v_and_b32_e32 v195, 0xffff0000, v167
	v_fma_f32 v62, v62, v150, v79
	v_fma_f32 v63, v63, v151, v79
	v_mul_f32_e32 v62, v62, v194
	v_mul_f32_e32 v63, v63, v195
	v_cvt_pk_bf16_f32 v60, v60, v61
	v_cvt_pk_bf16_f32 v61, v62, v63
	global_store_dwordx2 v[94:95], v[60:61], off offset:48
	s_waitcnt vmcnt(14)
	v_fma_f32 v32, v32, v136, v133
	v_lshlrev_b32_e32 v192, 16, v168
	v_and_b32_e32 v193, 0xffff0000, v168
	v_fma_f32 v33, v33, v137, v133
	v_mul_f32_e32 v32, v32, v192
	v_mul_f32_e32 v33, v33, v193
	v_lshlrev_b32_e32 v194, 16, v169
	v_and_b32_e32 v195, 0xffff0000, v169
	v_fma_f32 v34, v34, v138, v133
	v_fma_f32 v35, v35, v139, v133
	v_mul_f32_e32 v34, v34, v194
	v_mul_f32_e32 v35, v35, v195
	v_cvt_pk_bf16_f32 v32, v32, v33
	v_cvt_pk_bf16_f32 v33, v34, v35
	global_store_dwordx2 v[152:153], v[32:33], off
	v_fma_f32 v36, v36, v140, v133
	v_lshlrev_b32_e32 v192, 16, v170
	v_and_b32_e32 v193, 0xffff0000, v170
	v_fma_f32 v37, v37, v141, v133
	v_mul_f32_e32 v36, v36, v192
	v_mul_f32_e32 v37, v37, v193
	v_lshlrev_b32_e32 v194, 16, v171
	v_and_b32_e32 v195, 0xffff0000, v171
	v_fma_f32 v38, v38, v142, v133
	v_fma_f32 v39, v39, v143, v133
	v_mul_f32_e32 v38, v38, v194
	v_mul_f32_e32 v39, v39, v195
	v_cvt_pk_bf16_f32 v36, v36, v37
	v_cvt_pk_bf16_f32 v37, v38, v39
	global_store_dwordx2 v[152:153], v[36:37], off offset:16
	v_fma_f32 v40, v40, v144, v133
	v_lshlrev_b32_e32 v192, 16, v172
	v_and_b32_e32 v193, 0xffff0000, v172
	v_fma_f32 v41, v41, v145, v133
	v_mul_f32_e32 v40, v40, v192
	v_mul_f32_e32 v41, v41, v193
	v_lshlrev_b32_e32 v194, 16, v173
	v_and_b32_e32 v195, 0xffff0000, v173
	v_fma_f32 v42, v42, v146, v133
	v_fma_f32 v43, v43, v147, v133
	v_mul_f32_e32 v42, v42, v194
	v_mul_f32_e32 v43, v43, v195
	v_cvt_pk_bf16_f32 v40, v40, v41
	v_cvt_pk_bf16_f32 v41, v42, v43
	global_store_dwordx2 v[152:153], v[40:41], off offset:32
	v_fma_f32 v44, v44, v148, v133
	v_lshlrev_b32_e32 v192, 16, v174
	v_and_b32_e32 v193, 0xffff0000, v174
	v_fma_f32 v45, v45, v149, v133
	v_mul_f32_e32 v44, v44, v192
	v_mul_f32_e32 v45, v45, v193
	v_lshlrev_b32_e32 v194, 16, v175
	v_and_b32_e32 v195, 0xffff0000, v175
	v_fma_f32 v46, v46, v150, v133
	v_fma_f32 v47, v47, v151, v133
	v_mul_f32_e32 v46, v46, v194
	v_mul_f32_e32 v47, v47, v195
	v_cvt_pk_bf16_f32 v44, v44, v45
	v_cvt_pk_bf16_f32 v45, v46, v47
	global_store_dwordx2 v[152:153], v[44:45], off offset:48
	s_waitcnt vmcnt(13)
	v_fma_f32 v16, v16, v136, v134
	v_lshlrev_b32_e32 v192, 16, v176
	v_and_b32_e32 v193, 0xffff0000, v176
	v_fma_f32 v17, v17, v137, v134
	v_mul_f32_e32 v16, v16, v192
	v_mul_f32_e32 v17, v17, v193
	v_lshlrev_b32_e32 v194, 16, v177
	v_and_b32_e32 v195, 0xffff0000, v177
	v_fma_f32 v18, v18, v138, v134
	v_fma_f32 v19, v19, v139, v134
	v_mul_f32_e32 v18, v18, v194
	v_mul_f32_e32 v19, v19, v195
	v_cvt_pk_bf16_f32 v16, v16, v17
	v_cvt_pk_bf16_f32 v17, v18, v19
	global_store_dwordx2 v[154:155], v[16:17], off
	v_fma_f32 v20, v20, v140, v134
	v_lshlrev_b32_e32 v192, 16, v178
	v_and_b32_e32 v193, 0xffff0000, v178
	v_fma_f32 v21, v21, v141, v134
	v_mul_f32_e32 v20, v20, v192
	v_mul_f32_e32 v21, v21, v193
	v_lshlrev_b32_e32 v194, 16, v179
	v_and_b32_e32 v195, 0xffff0000, v179
	v_fma_f32 v22, v22, v142, v134
	v_fma_f32 v23, v23, v143, v134
	v_mul_f32_e32 v22, v22, v194
	v_mul_f32_e32 v23, v23, v195
	v_cvt_pk_bf16_f32 v20, v20, v21
	v_cvt_pk_bf16_f32 v21, v22, v23
	global_store_dwordx2 v[154:155], v[20:21], off offset:16
	v_fma_f32 v24, v24, v144, v134
	v_lshlrev_b32_e32 v192, 16, v180
	v_and_b32_e32 v193, 0xffff0000, v180
	v_fma_f32 v25, v25, v145, v134
	v_mul_f32_e32 v24, v24, v192
	v_mul_f32_e32 v25, v25, v193
	v_lshlrev_b32_e32 v194, 16, v181
	v_and_b32_e32 v195, 0xffff0000, v181
	v_fma_f32 v26, v26, v146, v134
	v_fma_f32 v27, v27, v147, v134
	v_mul_f32_e32 v26, v26, v194
	v_mul_f32_e32 v27, v27, v195
	v_cvt_pk_bf16_f32 v24, v24, v25
	v_cvt_pk_bf16_f32 v25, v26, v27
	global_store_dwordx2 v[154:155], v[24:25], off offset:32
	v_fma_f32 v28, v28, v148, v134
	v_lshlrev_b32_e32 v192, 16, v182
	v_and_b32_e32 v193, 0xffff0000, v182
	v_fma_f32 v29, v29, v149, v134
	v_mul_f32_e32 v28, v28, v192
	v_mul_f32_e32 v29, v29, v193
	v_lshlrev_b32_e32 v194, 16, v183
	v_and_b32_e32 v195, 0xffff0000, v183
	v_fma_f32 v30, v30, v150, v134
	v_fma_f32 v31, v31, v151, v134
	v_mul_f32_e32 v30, v30, v194
	v_mul_f32_e32 v31, v31, v195
	v_cvt_pk_bf16_f32 v28, v28, v29
	v_cvt_pk_bf16_f32 v29, v30, v31
	global_store_dwordx2 v[154:155], v[28:29], off offset:48
	s_waitcnt vmcnt(12)
	v_fma_f32 v0, v0, v136, v135
	v_lshlrev_b32_e32 v192, 16, v184
	v_and_b32_e32 v193, 0xffff0000, v184
	v_fma_f32 v1, v1, v137, v135
	v_mul_f32_e32 v0, v0, v192
	v_mul_f32_e32 v1, v1, v193
	v_lshlrev_b32_e32 v194, 16, v185
	v_and_b32_e32 v195, 0xffff0000, v185
	v_fma_f32 v2, v2, v138, v135
	v_fma_f32 v3, v3, v139, v135
	v_mul_f32_e32 v2, v2, v194
	v_mul_f32_e32 v3, v3, v195
	v_cvt_pk_bf16_f32 v0, v0, v1
	v_cvt_pk_bf16_f32 v1, v2, v3
	global_store_dwordx2 v[156:157], v[0:1], off
	v_fma_f32 v4, v4, v140, v135
	v_lshlrev_b32_e32 v192, 16, v186
	v_and_b32_e32 v193, 0xffff0000, v186
	v_fma_f32 v5, v5, v141, v135
	v_mul_f32_e32 v4, v4, v192
	v_mul_f32_e32 v5, v5, v193
	v_lshlrev_b32_e32 v194, 16, v187
	v_and_b32_e32 v195, 0xffff0000, v187
	v_fma_f32 v6, v6, v142, v135
	v_fma_f32 v7, v7, v143, v135
	v_mul_f32_e32 v6, v6, v194
	v_mul_f32_e32 v7, v7, v195
	v_cvt_pk_bf16_f32 v4, v4, v5
	v_cvt_pk_bf16_f32 v5, v6, v7
	global_store_dwordx2 v[156:157], v[4:5], off offset:16
	v_fma_f32 v8, v8, v144, v135
	v_lshlrev_b32_e32 v192, 16, v188
	v_and_b32_e32 v193, 0xffff0000, v188
	v_fma_f32 v9, v9, v145, v135
	v_mul_f32_e32 v8, v8, v192
	v_mul_f32_e32 v9, v9, v193
	v_lshlrev_b32_e32 v194, 16, v189
	v_and_b32_e32 v195, 0xffff0000, v189
	v_fma_f32 v10, v10, v146, v135
	v_fma_f32 v11, v11, v147, v135
	v_mul_f32_e32 v10, v10, v194
	v_mul_f32_e32 v11, v11, v195
	v_cvt_pk_bf16_f32 v8, v8, v9
	v_cvt_pk_bf16_f32 v9, v10, v11
	global_store_dwordx2 v[156:157], v[8:9], off offset:32
	v_fma_f32 v12, v12, v148, v135
	v_lshlrev_b32_e32 v192, 16, v190
	v_and_b32_e32 v193, 0xffff0000, v190
	v_fma_f32 v13, v13, v149, v135
	v_mul_f32_e32 v12, v12, v192
	v_mul_f32_e32 v13, v13, v193
	v_lshlrev_b32_e32 v194, 16, v191
	v_and_b32_e32 v195, 0xffff0000, v191
	v_fma_f32 v14, v14, v150, v135
	v_fma_f32 v15, v15, v151, v135
	v_mul_f32_e32 v14, v14, v194
	v_mul_f32_e32 v15, v15, v195
	v_cvt_pk_bf16_f32 v12, v12, v13
	v_cvt_pk_bf16_f32 v13, v14, v15
	global_store_dwordx2 v[156:157], v[12:13], off offset:48
	s_barrier
	s_cbranch_scc1 .LBB0_1061

.LBB0_997:
	s_or_b64 exec, exec, s[96:97]
	s_lshl_b32 s4, s1, 7
	v_lshl_add_u64 v[0:1], s[4:5], 0, v[68:69]
	v_lshlrev_b64 v[0:1], 9, v[0:1]
	v_lshl_add_u64 v[8:9], v[70:71], 0, v[0:1]
	s_waitcnt vmcnt(0) lgkmcnt(0)
	s_barrier
	global_load_dwordx4 v[16:19], v[8:9], off
	global_load_dwordx4 v[20:23], v[8:9], off offset:16
	global_load_dwordx4 v[24:27], v[8:9], off offset:32
	global_load_dwordx4 v[28:31], v[8:9], off offset:48
	global_load_dwordx4 v[32:35], v[8:9], off offset:64
	global_load_dwordx4 v[36:39], v[8:9], off offset:80
	global_load_dwordx4 v[40:43], v[8:9], off offset:96
	global_load_dwordx4 v[44:47], v[8:9], off offset:112
	ds_read_b128 v[132:135], v99
	ds_read_b128 v[136:139], v99 offset:16
	ds_read_b128 v[140:143], v99 offset:32
	ds_read_b128 v[144:147], v99 offset:48
	ds_read_b128 v[148:151], v99 offset:64
	ds_read_b128 v[152:155], v99 offset:80
	ds_read_b128 v[156:159], v99 offset:96
	ds_read_b128 v[160:163], v99 offset:112
	s_lshl_b32 s1, s1, 8
	s_waitcnt vmcnt(0) lgkmcnt(0)
	v_mul_f32_e32 v16, v16, v132
	v_mul_f32_e32 v17, v17, v133
	v_mul_f32_e32 v18, v18, v134
	v_mul_f32_e32 v19, v19, v135
	v_mul_f32_e32 v20, v20, v136
	v_mul_f32_e32 v21, v21, v137
	v_mul_f32_e32 v22, v22, v138
	v_mul_f32_e32 v23, v23, v139
	v_mul_f32_e32 v24, v24, v140
	v_mul_f32_e32 v25, v25, v141
	v_mul_f32_e32 v26, v26, v142
	v_mul_f32_e32 v27, v27, v143
	v_mul_f32_e32 v28, v28, v144
	v_mul_f32_e32 v29, v29, v145
	v_mul_f32_e32 v30, v30, v146
	v_mul_f32_e32 v31, v31, v147
	v_mul_f32_e32 v32, v32, v148
	v_mul_f32_e32 v33, v33, v149
	v_mul_f32_e32 v34, v34, v150
	v_mul_f32_e32 v35, v35, v151
	v_mul_f32_e32 v36, v36, v152
	v_mul_f32_e32 v37, v37, v153
	v_mul_f32_e32 v38, v38, v154
	v_mul_f32_e32 v39, v39, v155
	v_mul_f32_e32 v40, v40, v156
	v_mul_f32_e32 v41, v41, v157
	v_mul_f32_e32 v42, v42, v158
	v_mul_f32_e32 v43, v43, v159
	v_mul_f32_e32 v44, v44, v160
	v_mul_f32_e32 v45, v45, v161
	v_mul_f32_e32 v46, v46, v162
	v_mul_f32_e32 v47, v47, v163
	v_cndmask_b32_e64 v16, 0, v16, s[12:13]
	v_cndmask_b32_e64 v17, 0, v17, s[14:15]
	v_cndmask_b32_e64 v18, 0, v18, s[16:17]
	v_cndmask_b32_e64 v19, 0, v19, s[18:19]
	v_cndmask_b32_e64 v20, 0, v20, s[20:21]
	v_cndmask_b32_e64 v21, 0, v21, s[22:23]
	v_cndmask_b32_e64 v22, 0, v22, s[24:25]
	v_cndmask_b32_e64 v23, 0, v23, s[26:27]
	v_cndmask_b32_e64 v24, 0, v24, s[28:29]
	v_cndmask_b32_e64 v25, 0, v25, s[30:31]
	v_cndmask_b32_e64 v26, 0, v26, s[34:35]
	v_cndmask_b32_e64 v27, 0, v27, s[36:37]
	v_cndmask_b32_e64 v28, 0, v28, s[38:39]
	v_cndmask_b32_e64 v29, 0, v29, s[40:41]
	v_cndmask_b32_e64 v30, 0, v30, s[42:43]
	v_cndmask_b32_e64 v31, 0, v31, s[44:45]
	v_cndmask_b32_e64 v32, 0, v32, s[46:47]
	v_cndmask_b32_e64 v33, 0, v33, s[48:49]
	v_cndmask_b32_e64 v34, 0, v34, s[50:51]
	v_cndmask_b32_e64 v35, 0, v35, s[52:53]
	v_cndmask_b32_e64 v36, 0, v36, s[54:55]
	v_cndmask_b32_e64 v37, 0, v37, s[56:57]
	v_cndmask_b32_e64 v38, 0, v38, s[58:59]
	v_cndmask_b32_e64 v39, 0, v39, s[60:61]
	v_cndmask_b32_e64 v40, 0, v40, s[62:63]
	v_cndmask_b32_e64 v41, 0, v41, s[64:65]
	v_cndmask_b32_e64 v42, 0, v42, s[66:67]
	v_cndmask_b32_e64 v43, 0, v43, s[68:69]
	v_cndmask_b32_e64 v44, 0, v44, s[70:71]
	v_cndmask_b32_e64 v45, 0, v45, s[72:73]
	v_cndmask_b32_e64 v46, 0, v46, s[74:75]
	v_cndmask_b32_e64 v47, 0, v47, s[76:77]
	v_cvt_pk_bf16_f32 v48, v16, v17
	v_cvt_pk_bf16_f32 v49, v18, v19
	v_cvt_pk_bf16_f32 v50, v20, v21
	v_cvt_pk_bf16_f32 v51, v22, v23
	ds_write_b128 v112, v[48:51]
	v_cvt_pk_bf16_f32 v52, v24, v25
	v_cvt_pk_bf16_f32 v53, v26, v27
	v_cvt_pk_bf16_f32 v54, v28, v29
	v_cvt_pk_bf16_f32 v55, v30, v31
	ds_write_b128 v113, v[52:55]
	v_cvt_pk_bf16_f32 v56, v32, v33
	v_cvt_pk_bf16_f32 v57, v34, v35
	v_cvt_pk_bf16_f32 v58, v36, v37
	v_cvt_pk_bf16_f32 v59, v38, v39
	ds_write_b128 v114, v[56:59]
	v_cvt_pk_bf16_f32 v60, v40, v41
	v_cvt_pk_bf16_f32 v61, v42, v43
	v_cvt_pk_bf16_f32 v62, v44, v45
	v_cvt_pk_bf16_f32 v63, v46, v47
	ds_write_b128 v115, v[60:63]
	s_branch .Lmy_mix1_wdone

.LBB0_1355:
	s_waitcnt vmcnt(6)
	v_fmamk_f32 v1, v233, 0x3a800000, v226
	v_mul_f32_e32 v2, 0x4b800000, v1
	v_cmp_gt_f32_e32 vcc, s50, v1
	v_mov_b32_e32 v134, v128
	v_mov_b32_e32 v135, v124
	v_cndmask_b32_e32 v1, v1, v2, vcc
	v_rsq_f32_e32 v3, v1
	v_mov_b32_e32 v124, v129
	v_readlane_b32 s12, v255, 18
	v_lshl_or_b32 v2, s22, 7, v221
	v_mul_f32_e32 v132, 0x45800000, v3
	v_cndmask_b32_e32 v132, v3, v132, vcc
	v_pk_mul_f32 v[134:135], v[132:133], v[134:135] op_sel_hi:[0,1]
	v_mul_f32_e32 v3, 0xbfb8aa3b, v135
	v_pk_mul_f32 v[124:125], v[132:133], v[124:125] op_sel_hi:[0,1]
	v_exp_f32_e32 v3, v3
	v_mul_f32_e32 v128, 0xbfb8aa3b, v125
	v_exp_f32_e32 v128, v128
	v_readlane_b32 s13, v255, 19
	v_add_f32_e32 v3, 1.0, v3
	v_rcp_f32_e32 v129, v3
	v_add_f32_e32 v3, 1.0, v128
	v_rcp_f32_e32 v128, v3
	v_lshl_add_u32 v1, s20, 8, v219
	v_mul_f32_e32 v129, v135, v129
	v_mul_f32_e32 v133, v134, v129
	v_mul_f32_e32 v125, v125, v128
	v_mov_b32_e32 v128, v130
	v_mov_b32_e32 v129, v126
	v_pk_mul_f32 v[128:129], v[132:133], v[128:129] op_sel_hi:[0,1]
	v_mul_f32_e32 v126, 0xbfb8aa3b, v129
	v_exp_f32_e32 v130, v126
	v_mov_b32_e32 v126, v131
	v_pk_mul_f32 v[126:127], v[132:133], v[126:127] op_sel_hi:[0,1]
	v_mul_f32_e32 v131, 0xbfb8aa3b, v127
	v_exp_f32_e32 v131, v131
	v_mul_f32_e32 v134, v124, v125
	v_add_f32_e32 v124, 1.0, v130
	v_rcp_f32_e32 v130, v124
	v_add_f32_e32 v124, 1.0, v131
	v_rcp_f32_e32 v131, v124
	v_mov_b32_e32 v124, v120
	v_mov_b32_e32 v125, v116
	v_pk_mul_f32 v[124:125], v[132:133], v[124:125] op_sel_hi:[0,1]
	v_mul_f32_e32 v116, 0xbfb8aa3b, v125
	v_exp_f32_e32 v116, v116
	v_mul_f32_e32 v120, v129, v130
	v_mul_f32_e32 v128, v128, v120
	v_mul_f32_e32 v120, v127, v131
	v_add_f32_e32 v116, 1.0, v116
	v_rcp_f32_e32 v127, v116
	v_mov_b32_e32 v116, v121
	v_pk_mul_f32 v[116:117], v[132:133], v[116:117] op_sel_hi:[0,1]
	v_mul_f32_e32 v121, 0xbfb8aa3b, v117
	v_exp_f32_e32 v121, v121
	v_mul_f32_e32 v126, v126, v120
	v_mul_f32_e32 v120, v125, v127
	v_mul_f32_e32 v124, v124, v120
	v_add_f32_e32 v120, 1.0, v121
	v_rcp_f32_e32 v125, v120
	v_mov_b32_e32 v120, v122
	v_mov_b32_e32 v121, v118
	v_pk_mul_f32 v[120:121], v[132:133], v[120:121] op_sel_hi:[0,1]
	v_mul_f32_e32 v118, 0xbfb8aa3b, v121
	v_exp_f32_e32 v122, v118
	v_mov_b32_e32 v118, v123
	v_pk_mul_f32 v[118:119], v[132:133], v[118:119] op_sel_hi:[0,1]
	v_mul_f32_e32 v123, 0xbfb8aa3b, v119
	v_exp_f32_e32 v123, v123
	v_add_f32_e32 v122, 1.0, v122
	v_rcp_f32_e32 v122, v122
	v_mul_f32_e32 v117, v117, v125
	v_add_f32_e32 v123, 1.0, v123
	v_rcp_f32_e32 v123, v123
	v_mul_f32_e32 v116, v116, v117
	v_mul_f32_e32 v117, v121, v122
	v_fmamk_f32 v122, v232, 0x3a800000, v226
	v_mul_f32_e32 v119, v119, v123
	v_mul_f32_e32 v123, 0x4b800000, v122
	v_cmp_gt_f32_e32 vcc, s50, v122
	v_mul_f32_e32 v117, v120, v117
	v_mul_f32_e32 v121, v118, v119
	v_cndmask_b32_e32 v122, v122, v123, vcc
	v_cvt_pk_bf16_f32 v118, v133, v134
	v_cvt_pk_bf16_f32 v119, v128, v126
	v_cvt_pk_bf16_f32 v120, v124, v116
	v_rsq_f32_e32 v124, v122
	v_mov_b32_e32 v126, v112
	v_mov_b32_e32 v127, v108
	v_ashrrev_i32_e32 v3, 31, v2
	v_mul_f32_e32 v125, 0x45800000, v124
	v_cndmask_b32_e32 v124, v124, v125, vcc
	v_pk_mul_f32 v[126:127], v[124:125], v[126:127] op_sel_hi:[0,1]
	v_mul_f32_e32 v108, 0xbfb8aa3b, v127
	v_exp_f32_e32 v125, v108
	v_mov_b32_e32 v108, v113
	v_cvt_pk_bf16_f32 v121, v117, v121
	v_mov_b64_e32 v[116:117], s[12:13]
	v_pk_mul_f32 v[108:109], v[124:125], v[108:109] op_sel_hi:[0,1]
	v_mad_i64_i32 v[122:123], s[12:13], v1, s51, v[116:117]
	v_lshlrev_b64 v[2:3], 1, v[2:3]
	v_mul_f32_e32 v112, 0xbfb8aa3b, v109
	v_exp_f32_e32 v128, v112
	v_lshl_add_u64 v[112:113], v[122:123], 0, v[2:3]
	v_add_f32_e32 v122, 1.0, v125
	v_rcp_f32_e32 v122, v122
	global_store_dwordx4 v[112:113], v[118:121], off
	v_mov_b32_e32 v113, v110
	v_add_f32_e32 v123, 1.0, v128
	v_mul_f32_e32 v112, v127, v122
	v_mul_f32_e32 v118, v126, v112
	v_mov_b32_e32 v112, v114
	v_pk_mul_f32 v[112:113], v[124:125], v[112:113] op_sel_hi:[0,1]
	v_mul_f32_e32 v110, 0xbfb8aa3b, v113
	v_exp_f32_e32 v114, v110
	v_mov_b32_e32 v110, v115
	v_rcp_f32_e32 v123, v123
	v_pk_mul_f32 v[110:111], v[124:125], v[110:111] op_sel_hi:[0,1]
	v_mul_f32_e32 v115, 0xbfb8aa3b, v111
	v_exp_f32_e32 v115, v115
	v_mul_f32_e32 v109, v109, v123
	v_mul_f32_e32 v119, v108, v109
	v_add_f32_e32 v108, 1.0, v114
	v_rcp_f32_e32 v114, v108
	v_add_f32_e32 v108, 1.0, v115
	v_rcp_f32_e32 v115, v108
	v_mov_b32_e32 v108, v104
	v_mov_b32_e32 v109, v100
	v_pk_mul_f32 v[108:109], v[124:125], v[108:109] op_sel_hi:[0,1]
	v_mul_f32_e32 v100, 0xbfb8aa3b, v109
	v_exp_f32_e32 v100, v100
	v_mul_f32_e32 v104, v113, v114
	v_mul_f32_e32 v112, v112, v104
	v_mul_f32_e32 v104, v111, v115
	v_add_f32_e32 v100, 1.0, v100
	v_rcp_f32_e32 v111, v100
	v_mov_b32_e32 v100, v105
	v_pk_mul_f32 v[100:101], v[124:125], v[100:101] op_sel_hi:[0,1]
	v_mul_f32_e32 v105, 0xbfb8aa3b, v101
	v_exp_f32_e32 v105, v105
	v_mul_f32_e32 v110, v110, v104
	v_mul_f32_e32 v104, v109, v111
	v_mul_f32_e32 v108, v108, v104
	v_add_f32_e32 v104, 1.0, v105
	v_rcp_f32_e32 v109, v104
	v_mov_b32_e32 v104, v106
	v_mov_b32_e32 v105, v102
	v_pk_mul_f32 v[104:105], v[124:125], v[104:105] op_sel_hi:[0,1]
	v_mul_f32_e32 v102, 0xbfb8aa3b, v105
	v_exp_f32_e32 v106, v102
	v_mov_b32_e32 v102, v107
	v_pk_mul_f32 v[102:103], v[124:125], v[102:103] op_sel_hi:[0,1]
	v_mul_f32_e32 v107, 0xbfb8aa3b, v103
	v_exp_f32_e32 v107, v107
	v_add_f32_e32 v106, 1.0, v106
	v_rcp_f32_e32 v106, v106
	v_mul_f32_e32 v101, v101, v109
	v_add_f32_e32 v107, 1.0, v107
	v_rcp_f32_e32 v107, v107
	v_mul_f32_e32 v109, v100, v101
	v_mul_f32_e32 v100, v105, v106
	v_fmamk_f32 v106, v231, 0x3a800000, v226
	v_mul_f32_e32 v104, v104, v100
	v_mul_f32_e32 v100, v103, v107
	v_mul_f32_e32 v107, 0x4b800000, v106
	v_cmp_gt_f32_e32 vcc, s50, v106
	v_mul_f32_e32 v103, v102, v100
	v_cvt_pk_bf16_f32 v100, v118, v119
	v_cvt_pk_bf16_f32 v101, v112, v110
	v_cvt_pk_bf16_f32 v102, v108, v109
	v_mov_b32_e32 v108, v96
	v_cndmask_b32_e32 v106, v106, v107, vcc
	v_rsq_f32_e32 v106, v106
	v_mov_b32_e32 v109, v92
	v_or_b32_e32 v105, 16, v1
	v_cvt_pk_bf16_f32 v103, v104, v103
	v_mul_f32_e32 v107, 0x45800000, v106
	v_cndmask_b32_e32 v106, v106, v107, vcc
	v_pk_mul_f32 v[108:109], v[106:107], v[108:109] op_sel_hi:[0,1]
	v_mul_f32_e32 v92, 0xbfb8aa3b, v109
	v_exp_f32_e32 v107, v92
	v_mov_b32_e32 v92, v97
	v_mad_i64_i32 v[104:105], s[12:13], v105, s51, v[116:117]
	v_pk_mul_f32 v[92:93], v[106:107], v[92:93] op_sel_hi:[0,1]
	v_mul_f32_e32 v96, 0xbfb8aa3b, v93
	v_exp_f32_e32 v110, v96
	v_lshl_add_u64 v[96:97], v[104:105], 0, v[2:3]
	v_add_f32_e32 v104, 1.0, v107
	v_rcp_f32_e32 v104, v104
	global_store_dwordx4 v[96:97], v[100:103], off
	v_mov_b32_e32 v97, v94
	v_add_f32_e32 v105, 1.0, v110
	v_mul_f32_e32 v96, v109, v104
	v_mul_f32_e32 v100, v108, v96
	v_mov_b32_e32 v96, v98
	v_pk_mul_f32 v[96:97], v[106:107], v[96:97] op_sel_hi:[0,1]
	v_mul_f32_e32 v94, 0xbfb8aa3b, v97
	v_exp_f32_e32 v98, v94
	v_mov_b32_e32 v94, v99
	v_rcp_f32_e32 v105, v105
	v_pk_mul_f32 v[94:95], v[106:107], v[94:95] op_sel_hi:[0,1]
	v_mul_f32_e32 v99, 0xbfb8aa3b, v95
	v_exp_f32_e32 v99, v99
	v_mul_f32_e32 v93, v93, v105
	v_mul_f32_e32 v101, v92, v93
	v_add_f32_e32 v92, 1.0, v98
	v_rcp_f32_e32 v98, v92
	v_add_f32_e32 v92, 1.0, v99
	v_rcp_f32_e32 v99, v92
	v_mov_b32_e32 v92, v88
	v_mov_b32_e32 v93, v84
	v_pk_mul_f32 v[92:93], v[106:107], v[92:93] op_sel_hi:[0,1]
	v_mul_f32_e32 v84, 0xbfb8aa3b, v93
	v_exp_f32_e32 v84, v84
	v_mul_f32_e32 v88, v97, v98
	v_mul_f32_e32 v96, v96, v88
	v_mul_f32_e32 v88, v95, v99
	v_add_f32_e32 v84, 1.0, v84
	v_rcp_f32_e32 v95, v84
	v_mov_b32_e32 v84, v89
	v_pk_mul_f32 v[84:85], v[106:107], v[84:85] op_sel_hi:[0,1]
	v_mul_f32_e32 v89, 0xbfb8aa3b, v85
	v_exp_f32_e32 v89, v89
	v_mul_f32_e32 v94, v94, v88
	v_mul_f32_e32 v88, v93, v95
	v_mul_f32_e32 v92, v92, v88
	v_add_f32_e32 v88, 1.0, v89
	v_rcp_f32_e32 v93, v88
	v_mov_b32_e32 v88, v90
	v_mov_b32_e32 v89, v86
	v_pk_mul_f32 v[88:89], v[106:107], v[88:89] op_sel_hi:[0,1]
	v_mul_f32_e32 v86, 0xbfb8aa3b, v89
	v_exp_f32_e32 v90, v86
	v_mov_b32_e32 v86, v91
	v_pk_mul_f32 v[86:87], v[106:107], v[86:87] op_sel_hi:[0,1]
	v_mul_f32_e32 v91, 0xbfb8aa3b, v87
	v_exp_f32_e32 v91, v91
	v_add_f32_e32 v90, 1.0, v90
	v_rcp_f32_e32 v90, v90
	v_mul_f32_e32 v85, v85, v93
	v_add_f32_e32 v91, 1.0, v91
	v_rcp_f32_e32 v91, v91
	v_mul_f32_e32 v93, v84, v85
	v_mul_f32_e32 v84, v89, v90
	v_fmamk_f32 v90, v230, 0x3a800000, v226
	v_mul_f32_e32 v88, v88, v84
	v_mul_f32_e32 v84, v87, v91
	v_mul_f32_e32 v91, 0x4b800000, v90
	v_cmp_gt_f32_e32 vcc, s50, v90
	v_mul_f32_e32 v87, v86, v84
	v_cvt_pk_bf16_f32 v84, v100, v101
	v_cvt_pk_bf16_f32 v85, v96, v94
	v_cvt_pk_bf16_f32 v86, v92, v93
	v_mov_b32_e32 v92, v80
	v_cndmask_b32_e32 v90, v90, v91, vcc
	v_rsq_f32_e32 v90, v90
	v_mov_b32_e32 v93, v76
	v_or_b32_e32 v89, 32, v1
	v_cvt_pk_bf16_f32 v87, v88, v87
	v_mul_f32_e32 v91, 0x45800000, v90
	v_cndmask_b32_e32 v90, v90, v91, vcc
	v_pk_mul_f32 v[92:93], v[90:91], v[92:93] op_sel_hi:[0,1]
	v_mul_f32_e32 v76, 0xbfb8aa3b, v93
	v_exp_f32_e32 v91, v76
	v_mov_b32_e32 v76, v81
	v_mad_i64_i32 v[88:89], s[12:13], v89, s51, v[116:117]
	v_pk_mul_f32 v[76:77], v[90:91], v[76:77] op_sel_hi:[0,1]
	v_mul_f32_e32 v80, 0xbfb8aa3b, v77
	v_exp_f32_e32 v94, v80
	v_lshl_add_u64 v[80:81], v[88:89], 0, v[2:3]
	v_add_f32_e32 v88, 1.0, v91
	v_rcp_f32_e32 v88, v88
	global_store_dwordx4 v[80:81], v[84:87], off
	v_mov_b32_e32 v81, v78
	v_add_f32_e32 v89, 1.0, v94
	v_mul_f32_e32 v80, v93, v88
	v_mul_f32_e32 v84, v92, v80
	v_mov_b32_e32 v80, v82
	v_pk_mul_f32 v[80:81], v[90:91], v[80:81] op_sel_hi:[0,1]
	v_mul_f32_e32 v78, 0xbfb8aa3b, v81
	v_exp_f32_e32 v82, v78
	v_mov_b32_e32 v78, v83
	v_rcp_f32_e32 v89, v89
	v_pk_mul_f32 v[78:79], v[90:91], v[78:79] op_sel_hi:[0,1]
	v_mul_f32_e32 v83, 0xbfb8aa3b, v79
	v_exp_f32_e32 v83, v83
	v_mul_f32_e32 v77, v77, v89
	v_mul_f32_e32 v85, v76, v77
	v_add_f32_e32 v76, 1.0, v82
	v_rcp_f32_e32 v82, v76
	v_add_f32_e32 v76, 1.0, v83
	v_rcp_f32_e32 v83, v76
	v_mov_b32_e32 v76, v68
	v_mov_b32_e32 v77, v72
	v_pk_mul_f32 v[76:77], v[90:91], v[76:77] op_sel_hi:[0,1]
	v_mul_f32_e32 v68, 0xbfb8aa3b, v77
	v_exp_f32_e32 v68, v68
	v_mul_f32_e32 v72, v81, v82
	v_mul_f32_e32 v80, v80, v72
	v_mov_b32_e32 v72, v69
	v_add_f32_e32 v68, 1.0, v68
	v_rcp_f32_e32 v81, v68
	v_pk_mul_f32 v[68:69], v[90:91], v[72:73] op_sel_hi:[0,1]
	v_mul_f32_e32 v72, 0xbfb8aa3b, v69
	v_exp_f32_e32 v72, v72
	v_mul_f32_e32 v73, v77, v81
	v_mul_f32_e32 v76, v76, v73
	v_mov_b32_e32 v73, v74
	v_add_f32_e32 v72, 1.0, v72
	v_rcp_f32_e32 v77, v72
	v_mov_b32_e32 v72, v70
	v_pk_mul_f32 v[72:73], v[90:91], v[72:73] op_sel_hi:[0,1]
	v_mul_f32_e32 v79, v79, v83
	v_mul_f32_e32 v70, 0xbfb8aa3b, v73
	v_mov_b32_e32 v74, v71
	v_mul_f32_e32 v78, v78, v79
	v_exp_f32_e32 v79, v70
	v_pk_mul_f32 v[70:71], v[90:91], v[74:75] op_sel_hi:[0,1]
	v_mul_f32_e32 v74, 0xbfb8aa3b, v71
	v_exp_f32_e32 v74, v74
	v_add_f32_e32 v75, 1.0, v79
	v_rcp_f32_e32 v75, v75
	v_mul_f32_e32 v69, v69, v77
	v_add_f32_e32 v74, 1.0, v74
	v_rcp_f32_e32 v74, v74
	v_mul_f32_e32 v77, v68, v69
	v_mul_f32_e32 v68, v73, v75
	v_mul_f32_e32 v72, v72, v68
	v_mul_f32_e32 v68, v71, v74
	v_mul_f32_e32 v71, v70, v68
	v_or_b32_e32 v73, 48, v1
	v_cvt_pk_bf16_f32 v68, v84, v85
	v_cvt_pk_bf16_f32 v69, v80, v78
	v_cvt_pk_bf16_f32 v70, v76, v77
	v_cvt_pk_bf16_f32 v71, v72, v71
	v_mad_i64_i32 v[72:73], s[12:13], v73, s51, v[116:117]
	s_cmp_eq_u32 s20, 64
	v_lshl_add_u64 v[72:73], v[72:73], 0, v[2:3]
	global_store_dwordx4 v[72:73], v[68:71], off
	s_cbranch_scc1 .LBB0_1357
	s_nop 0
	v_fmamk_f32 v68, v229, 0x3a800000, v226
	v_mul_f32_e32 v69, 0x4b800000, v68
	v_cmp_gt_f32_e32 vcc, s50, v68
	v_readlane_b32 s12, v255, 18
	v_readlane_b32 s13, v255, 19
	v_cndmask_b32_e32 v68, v68, v69, vcc
	v_rsq_f32_e32 v70, v68
	v_mov_b32_e32 v69, v60
	v_mov_b32_e32 v68, v64
	v_add_u32_e32 v71, 0x80, v1
	v_mul_f32_e32 v60, 0x45800000, v70
	v_cndmask_b32_e32 v64, v70, v60, vcc
	v_pk_mul_f32 v[68:69], v[64:65], v[68:69] op_sel_hi:[0,1]
	v_mul_f32_e32 v60, 0xbfb8aa3b, v69
	v_exp_f32_e32 v70, v60
	v_mov_b32_e32 v60, v65
	v_pk_mul_f32 v[60:61], v[64:65], v[60:61] op_sel_hi:[0,1]
	v_mul_f32_e32 v65, 0xbfb8aa3b, v61
	v_exp_f32_e32 v65, v65
	v_add_f32_e32 v70, 1.0, v70
	v_rcp_f32_e32 v70, v70
	v_add_f32_e32 v65, 1.0, v65
	v_rcp_f32_e32 v65, v65
	v_mul_f32_e32 v69, v69, v70
	v_mul_f32_e32 v70, v68, v69
	v_mov_b32_e32 v68, v66
	v_mov_b32_e32 v69, v62
	v_pk_mul_f32 v[68:69], v[64:65], v[68:69] op_sel_hi:[0,1]
	v_mul_f32_e32 v62, 0xbfb8aa3b, v69
	v_mul_f32_e32 v61, v61, v65
	v_exp_f32_e32 v65, v62
	v_mov_b32_e32 v62, v67
	v_mul_f32_e32 v67, v60, v61
	v_mov_b32_e32 v61, v52
	v_pk_mul_f32 v[62:63], v[64:65], v[62:63] op_sel_hi:[0,1]
	v_mul_f32_e32 v66, 0xbfb8aa3b, v63
	v_exp_f32_e32 v66, v66
	v_add_f32_e32 v60, 1.0, v65
	v_rcp_f32_e32 v65, v60
	v_add_f32_e32 v60, 1.0, v66
	v_rcp_f32_e32 v66, v60
	v_mov_b32_e32 v60, v56
	v_pk_mul_f32 v[60:61], v[64:65], v[60:61] op_sel_hi:[0,1]
	v_mul_f32_e32 v52, 0xbfb8aa3b, v61
	v_exp_f32_e32 v52, v52
	v_mul_f32_e32 v56, v69, v65
	v_mul_f32_e32 v65, v68, v56
	v_mul_f32_e32 v56, v63, v66
	v_add_f32_e32 v52, 1.0, v52
	v_rcp_f32_e32 v63, v52
	v_mov_b32_e32 v52, v57
	v_pk_mul_f32 v[52:53], v[64:65], v[52:53] op_sel_hi:[0,1]
	v_mul_f32_e32 v57, 0xbfb8aa3b, v53
	v_exp_f32_e32 v57, v57
	v_mul_f32_e32 v62, v62, v56
	v_mul_f32_e32 v56, v61, v63
	v_mul_f32_e32 v60, v60, v56
	v_add_f32_e32 v56, 1.0, v57
	v_rcp_f32_e32 v61, v56
	v_mov_b32_e32 v56, v58
	v_mov_b32_e32 v57, v54
	v_pk_mul_f32 v[56:57], v[64:65], v[56:57] op_sel_hi:[0,1]
	v_mul_f32_e32 v54, 0xbfb8aa3b, v57
	v_exp_f32_e32 v58, v54
	v_mov_b32_e32 v54, v59
	v_pk_mul_f32 v[54:55], v[64:65], v[54:55] op_sel_hi:[0,1]
	v_mul_f32_e32 v59, 0xbfb8aa3b, v55
	v_exp_f32_e32 v59, v59
	v_add_f32_e32 v58, 1.0, v58
	v_rcp_f32_e32 v58, v58
	v_mul_f32_e32 v53, v53, v61
	v_add_f32_e32 v59, 1.0, v59
	v_rcp_f32_e32 v59, v59
	v_mul_f32_e32 v52, v52, v53
	v_mul_f32_e32 v53, v57, v58
	v_mul_f32_e32 v53, v56, v53
	v_mul_f32_e32 v55, v55, v59
	v_mul_f32_e32 v57, v54, v55
	v_cvt_pk_bf16_f32 v54, v70, v67
	v_cvt_pk_bf16_f32 v55, v65, v62
	v_cvt_pk_bf16_f32 v56, v60, v52
	v_fmamk_f32 v52, v228, 0x3a800000, v226
	v_cvt_pk_bf16_f32 v57, v53, v57
	v_mul_f32_e32 v53, 0x4b800000, v52
	v_cmp_gt_f32_e32 vcc, s50, v52
	v_mov_b32_e32 v62, v48
	v_mov_b32_e32 v63, v44
	v_cndmask_b32_e32 v52, v52, v53, vcc
	v_rsq_f32_e32 v60, v52
	v_mov_b64_e32 v[52:53], s[12:13]
	v_mad_i64_i32 v[58:59], s[12:13], v71, s51, v[52:53]
	v_mul_f32_e32 v61, 0x45800000, v60
	v_cndmask_b32_e32 v60, v60, v61, vcc
	v_pk_mul_f32 v[62:63], v[60:61], v[62:63] op_sel_hi:[0,1]
	v_mul_f32_e32 v44, 0xbfb8aa3b, v63
	v_exp_f32_e32 v61, v44
	v_mov_b32_e32 v44, v49
	v_pk_mul_f32 v[44:45], v[60:61], v[44:45] op_sel_hi:[0,1]
	v_mul_f32_e32 v48, 0xbfb8aa3b, v45
	v_exp_f32_e32 v64, v48
	v_lshl_add_u64 v[48:49], v[58:59], 0, v[2:3]
	v_add_f32_e32 v58, 1.0, v61
	v_rcp_f32_e32 v58, v58
	global_store_dwordx4 v[48:49], v[54:57], off
	v_mov_b32_e32 v49, v46
	v_add_f32_e32 v59, 1.0, v64
	v_mul_f32_e32 v48, v63, v58
	v_mul_f32_e32 v54, v62, v48
	v_mov_b32_e32 v48, v50
	v_pk_mul_f32 v[48:49], v[60:61], v[48:49] op_sel_hi:[0,1]
	v_mul_f32_e32 v46, 0xbfb8aa3b, v49
	v_exp_f32_e32 v50, v46
	v_mov_b32_e32 v46, v51
	v_rcp_f32_e32 v59, v59
	v_pk_mul_f32 v[46:47], v[60:61], v[46:47] op_sel_hi:[0,1]
	v_mul_f32_e32 v51, 0xbfb8aa3b, v47
	v_exp_f32_e32 v51, v51
	v_mul_f32_e32 v45, v45, v59
	v_mul_f32_e32 v55, v44, v45
	v_add_f32_e32 v44, 1.0, v50
	v_rcp_f32_e32 v50, v44
	v_add_f32_e32 v44, 1.0, v51
	v_rcp_f32_e32 v51, v44
	v_mov_b32_e32 v44, v40
	v_mov_b32_e32 v45, v36
	v_pk_mul_f32 v[44:45], v[60:61], v[44:45] op_sel_hi:[0,1]
	v_mul_f32_e32 v36, 0xbfb8aa3b, v45
	v_exp_f32_e32 v36, v36
	v_mul_f32_e32 v40, v49, v50
	v_mul_f32_e32 v48, v48, v40
	v_mul_f32_e32 v40, v47, v51
	v_add_f32_e32 v36, 1.0, v36
	v_rcp_f32_e32 v47, v36
	v_mov_b32_e32 v36, v41
	v_pk_mul_f32 v[36:37], v[60:61], v[36:37] op_sel_hi:[0,1]
	v_mul_f32_e32 v41, 0xbfb8aa3b, v37
	v_exp_f32_e32 v41, v41
	v_mul_f32_e32 v46, v46, v40
	v_mul_f32_e32 v40, v45, v47
	v_mul_f32_e32 v44, v44, v40
	v_add_f32_e32 v40, 1.0, v41
	v_rcp_f32_e32 v45, v40
	v_mov_b32_e32 v40, v42
	v_mov_b32_e32 v41, v38
	v_pk_mul_f32 v[40:41], v[60:61], v[40:41] op_sel_hi:[0,1]
	v_mul_f32_e32 v38, 0xbfb8aa3b, v41
	v_exp_f32_e32 v42, v38
	v_mov_b32_e32 v38, v43
	v_pk_mul_f32 v[38:39], v[60:61], v[38:39] op_sel_hi:[0,1]
	v_mul_f32_e32 v43, 0xbfb8aa3b, v39
	v_exp_f32_e32 v43, v43
	v_add_f32_e32 v42, 1.0, v42
	v_rcp_f32_e32 v42, v42
	v_mul_f32_e32 v37, v37, v45
	v_add_f32_e32 v43, 1.0, v43
	v_rcp_f32_e32 v43, v43
	v_mul_f32_e32 v45, v36, v37
	v_mul_f32_e32 v36, v41, v42
	v_fmamk_f32 v42, v227, 0x3a800000, v226
	v_mul_f32_e32 v40, v40, v36
	v_mul_f32_e32 v36, v39, v43
	v_mul_f32_e32 v43, 0x4b800000, v42
	v_cmp_gt_f32_e32 vcc, s50, v42
	v_mul_f32_e32 v39, v38, v36
	v_cvt_pk_bf16_f32 v36, v54, v55
	v_cvt_pk_bf16_f32 v37, v48, v46
	v_cvt_pk_bf16_f32 v38, v44, v45
	v_mov_b32_e32 v44, v32
	v_cndmask_b32_e32 v42, v42, v43, vcc
	v_rsq_f32_e32 v42, v42
	v_mov_b32_e32 v45, v28
	v_add_u32_e32 v41, 0x90, v1
	v_cvt_pk_bf16_f32 v39, v40, v39
	v_mul_f32_e32 v43, 0x45800000, v42
	v_cndmask_b32_e32 v42, v42, v43, vcc
	v_pk_mul_f32 v[44:45], v[42:43], v[44:45] op_sel_hi:[0,1]
	v_mul_f32_e32 v28, 0xbfb8aa3b, v45
	v_exp_f32_e32 v43, v28
	v_mov_b32_e32 v28, v33
	v_mad_i64_i32 v[40:41], s[12:13], v41, s51, v[52:53]
	v_pk_mul_f32 v[28:29], v[42:43], v[28:29] op_sel_hi:[0,1]
	v_mul_f32_e32 v32, 0xbfb8aa3b, v29
	v_exp_f32_e32 v46, v32
	v_lshl_add_u64 v[32:33], v[40:41], 0, v[2:3]
	v_add_f32_e32 v40, 1.0, v43
	v_rcp_f32_e32 v40, v40
	global_store_dwordx4 v[32:33], v[36:39], off
	v_mov_b32_e32 v33, v30
	v_add_f32_e32 v41, 1.0, v46
	v_mul_f32_e32 v32, v45, v40
	v_mul_f32_e32 v36, v44, v32
	v_mov_b32_e32 v32, v34
	v_pk_mul_f32 v[32:33], v[42:43], v[32:33] op_sel_hi:[0,1]
	v_mul_f32_e32 v30, 0xbfb8aa3b, v33
	v_exp_f32_e32 v34, v30
	v_mov_b32_e32 v30, v35
	v_rcp_f32_e32 v41, v41
	v_pk_mul_f32 v[30:31], v[42:43], v[30:31] op_sel_hi:[0,1]
	v_mul_f32_e32 v35, 0xbfb8aa3b, v31
	v_exp_f32_e32 v35, v35
	v_mul_f32_e32 v29, v29, v41
	v_mul_f32_e32 v37, v28, v29
	v_add_f32_e32 v28, 1.0, v34
	v_rcp_f32_e32 v34, v28
	v_add_f32_e32 v28, 1.0, v35
	v_rcp_f32_e32 v35, v28
	v_mov_b32_e32 v28, v24
	v_mov_b32_e32 v29, v20
	v_pk_mul_f32 v[28:29], v[42:43], v[28:29] op_sel_hi:[0,1]
	v_mul_f32_e32 v20, 0xbfb8aa3b, v29
	v_exp_f32_e32 v20, v20
	v_mul_f32_e32 v24, v33, v34
	v_mul_f32_e32 v32, v32, v24
	v_mul_f32_e32 v24, v31, v35
	v_add_f32_e32 v20, 1.0, v20
	v_rcp_f32_e32 v31, v20
	v_mov_b32_e32 v20, v25
	v_pk_mul_f32 v[20:21], v[42:43], v[20:21] op_sel_hi:[0,1]
	v_mul_f32_e32 v25, 0xbfb8aa3b, v21
	v_exp_f32_e32 v25, v25
	v_mul_f32_e32 v30, v30, v24
	v_mul_f32_e32 v24, v29, v31
	v_mul_f32_e32 v28, v28, v24
	v_add_f32_e32 v24, 1.0, v25
	v_rcp_f32_e32 v29, v24
	v_mov_b32_e32 v24, v26
	v_mov_b32_e32 v25, v22
	v_pk_mul_f32 v[24:25], v[42:43], v[24:25] op_sel_hi:[0,1]
	v_mul_f32_e32 v22, 0xbfb8aa3b, v25
	v_exp_f32_e32 v26, v22
	v_mov_b32_e32 v22, v27
	v_pk_mul_f32 v[22:23], v[42:43], v[22:23] op_sel_hi:[0,1]
	v_mul_f32_e32 v27, 0xbfb8aa3b, v23
	v_exp_f32_e32 v27, v27
	v_add_f32_e32 v26, 1.0, v26
	v_rcp_f32_e32 v26, v26
	v_mul_f32_e32 v21, v21, v29
	v_add_f32_e32 v27, 1.0, v27
	v_rcp_f32_e32 v27, v27
	v_mul_f32_e32 v29, v20, v21
	v_mul_f32_e32 v20, v25, v26
	v_fmamk_f32 v26, v218, 0x3a800000, v226
	v_mul_f32_e32 v24, v24, v20
	v_mul_f32_e32 v20, v23, v27
	v_mul_f32_e32 v27, 0x4b800000, v26
	v_cmp_gt_f32_e32 vcc, s50, v26
	v_mul_f32_e32 v23, v22, v20
	v_cvt_pk_bf16_f32 v20, v36, v37
	v_cvt_pk_bf16_f32 v21, v32, v30
	v_cvt_pk_bf16_f32 v22, v28, v29
	v_mov_b32_e32 v28, v16
	v_cndmask_b32_e32 v26, v26, v27, vcc
	v_rsq_f32_e32 v26, v26
	v_mov_b32_e32 v29, v12
	v_add_u32_e32 v25, 0xa0, v1
	v_cvt_pk_bf16_f32 v23, v24, v23
	v_mul_f32_e32 v27, 0x45800000, v26
	v_cndmask_b32_e32 v26, v26, v27, vcc
	v_pk_mul_f32 v[28:29], v[26:27], v[28:29] op_sel_hi:[0,1]
	v_mul_f32_e32 v12, 0xbfb8aa3b, v29
	v_exp_f32_e32 v27, v12
	v_mov_b32_e32 v12, v17
	v_mad_i64_i32 v[24:25], s[12:13], v25, s51, v[52:53]
	v_pk_mul_f32 v[12:13], v[26:27], v[12:13] op_sel_hi:[0,1]
	v_mul_f32_e32 v16, 0xbfb8aa3b, v13
	v_exp_f32_e32 v30, v16
	v_lshl_add_u64 v[16:17], v[24:25], 0, v[2:3]
	v_add_f32_e32 v24, 1.0, v27
	v_rcp_f32_e32 v24, v24
	global_store_dwordx4 v[16:17], v[20:23], off
	v_mov_b32_e32 v17, v14
	v_add_f32_e32 v25, 1.0, v30
	v_mul_f32_e32 v16, v29, v24
	v_mul_f32_e32 v20, v28, v16
	v_mov_b32_e32 v16, v18
	v_pk_mul_f32 v[16:17], v[26:27], v[16:17] op_sel_hi:[0,1]
	v_mul_f32_e32 v14, 0xbfb8aa3b, v17
	v_exp_f32_e32 v18, v14
	v_mov_b32_e32 v14, v19
	v_rcp_f32_e32 v25, v25
	v_pk_mul_f32 v[14:15], v[26:27], v[14:15] op_sel_hi:[0,1]
	v_mul_f32_e32 v19, 0xbfb8aa3b, v15
	v_exp_f32_e32 v19, v19
	v_mul_f32_e32 v13, v13, v25
	v_mul_f32_e32 v21, v12, v13
	v_add_f32_e32 v12, 1.0, v18
	v_rcp_f32_e32 v18, v12
	v_add_f32_e32 v12, 1.0, v19
	v_rcp_f32_e32 v19, v12
	v_mov_b32_e32 v12, v8
	v_mov_b32_e32 v13, v4
	v_pk_mul_f32 v[12:13], v[26:27], v[12:13] op_sel_hi:[0,1]
	v_mul_f32_e32 v4, 0xbfb8aa3b, v13
	v_exp_f32_e32 v4, v4
	v_mul_f32_e32 v8, v17, v18
	v_mul_f32_e32 v16, v16, v8
	v_mul_f32_e32 v8, v15, v19
	v_add_f32_e32 v4, 1.0, v4
	v_rcp_f32_e32 v15, v4
	v_mov_b32_e32 v4, v9
	v_pk_mul_f32 v[4:5], v[26:27], v[4:5] op_sel_hi:[0,1]
	v_mul_f32_e32 v9, 0xbfb8aa3b, v5
	v_exp_f32_e32 v9, v9
	v_mul_f32_e32 v14, v14, v8
	v_mul_f32_e32 v8, v13, v15
	v_mul_f32_e32 v12, v12, v8
	v_add_f32_e32 v8, 1.0, v9
	v_rcp_f32_e32 v13, v8
	v_mov_b32_e32 v8, v10
	v_mov_b32_e32 v9, v6
	v_pk_mul_f32 v[8:9], v[26:27], v[8:9] op_sel_hi:[0,1]
	v_mul_f32_e32 v6, 0xbfb8aa3b, v9
	v_exp_f32_e32 v10, v6
	v_mov_b32_e32 v6, v11
	v_pk_mul_f32 v[6:7], v[26:27], v[6:7] op_sel_hi:[0,1]
	v_mul_f32_e32 v11, 0xbfb8aa3b, v7
	v_exp_f32_e32 v11, v11
	v_add_f32_e32 v10, 1.0, v10
	v_rcp_f32_e32 v10, v10
	v_mul_f32_e32 v5, v5, v13
	v_add_f32_e32 v11, 1.0, v11
	v_rcp_f32_e32 v11, v11
	v_mul_f32_e32 v13, v4, v5
	v_mul_f32_e32 v4, v9, v10
	v_mul_f32_e32 v8, v8, v4
	v_mul_f32_e32 v4, v7, v11
	v_mul_f32_e32 v7, v6, v4
	v_add_u32_e32 v1, 0xb0, v1
	v_cvt_pk_bf16_f32 v4, v20, v21
	v_cvt_pk_bf16_f32 v5, v16, v14
	v_cvt_pk_bf16_f32 v6, v12, v13
	v_cvt_pk_bf16_f32 v7, v8, v7
	v_mad_i64_i32 v[8:9], s[12:13], v1, s51, v[52:53]
	v_lshl_add_u64 v[2:3], v[8:9], 0, v[2:3]
	global_store_dwordx4 v[2:3], v[4:7], off

.LBB0_1690:
	s_waitcnt lgkmcnt(0)
	v_mov_b32_e32 v2, v0
	v_mov_b32_e32 v3, v0
	v_mov_b32_e32 v1, v0
	v_mov_b32_e32 v131, 0
	v_mov_b64_e32 v[66:67], v[2:3]
	v_mov_b64_e32 v[62:63], v[2:3]
	v_mov_b64_e32 v[50:51], v[2:3]
	v_mov_b64_e32 v[46:47], v[2:3]
	v_mov_b64_e32 v[34:35], v[2:3]
	v_mov_b64_e32 v[30:31], v[2:3]
	v_mov_b64_e32 v[18:19], v[2:3]
	v_mov_b64_e32 v[14:15], v[2:3]
	v_mov_b64_e32 v[58:59], v[2:3]
	v_mov_b64_e32 v[54:55], v[2:3]
	v_mov_b64_e32 v[42:43], v[2:3]
	v_mov_b64_e32 v[38:39], v[2:3]
	v_mov_b64_e32 v[26:27], v[2:3]
	v_mov_b64_e32 v[22:23], v[2:3]
	v_mov_b64_e32 v[10:11], v[2:3]
	v_mov_b64_e32 v[6:7], v[2:3]
	v_mov_b32_e32 v130, v131
	v_mov_b32_e32 v129, v131
	v_mov_b32_e32 v128, v131
	v_mov_b32_e32 v127, v131
	v_mov_b32_e32 v126, v131
	v_mov_b32_e32 v125, v131
	v_mov_b32_e32 v124, v131
	v_mov_b32_e32 v115, v131
	v_mov_b32_e32 v114, v131
	v_mov_b32_e32 v113, v131
	v_mov_b32_e32 v112, v131
	v_mov_b32_e32 v111, v131
	v_mov_b32_e32 v110, v131
	v_mov_b32_e32 v109, v131
	v_mov_b32_e32 v108, v131
	v_mov_b32_e32 v99, v131
	v_mov_b32_e32 v98, v131
	v_mov_b32_e32 v97, v131
	v_mov_b32_e32 v96, v131
	v_mov_b32_e32 v95, v131
	v_mov_b32_e32 v94, v131
	v_mov_b32_e32 v93, v131
	v_mov_b32_e32 v92, v131
	v_mov_b32_e32 v83, v131
	v_mov_b32_e32 v82, v131
	v_mov_b32_e32 v81, v131
	v_mov_b32_e32 v80, v131
	v_mov_b32_e32 v79, v131
	v_mov_b32_e32 v78, v131
	v_mov_b32_e32 v77, v131
	v_mov_b32_e32 v76, v131
	v_mov_b32_e32 v123, v131
	v_mov_b32_e32 v122, v131
	v_mov_b32_e32 v121, v131
	v_mov_b32_e32 v120, v131
	v_mov_b32_e32 v119, v131
	v_mov_b32_e32 v118, v131
	v_mov_b32_e32 v117, v131
	v_mov_b32_e32 v116, v131
	v_mov_b32_e32 v107, v131
	v_mov_b32_e32 v106, v131
	v_mov_b32_e32 v105, v131
	v_mov_b32_e32 v104, v131
	v_mov_b32_e32 v103, v131
	v_mov_b32_e32 v102, v131
	v_mov_b32_e32 v101, v131
	v_mov_b32_e32 v100, v131
	v_mov_b32_e32 v91, v131
	v_mov_b32_e32 v90, v131
	v_mov_b32_e32 v89, v131
	v_mov_b32_e32 v88, v131
	v_mov_b32_e32 v87, v131
	v_mov_b32_e32 v86, v131
	v_mov_b32_e32 v85, v131
	v_mov_b32_e32 v84, v131
	v_mov_b32_e32 v75, v131
	v_mov_b32_e32 v74, v131
	v_mov_b32_e32 v73, v131
	v_mov_b32_e32 v72, v131
	v_mov_b32_e32 v71, v131
	v_mov_b32_e32 v70, v131
	v_mov_b32_e32 v69, v131
	v_mov_b32_e32 v68, v131
	v_mov_b64_e32 v[64:65], v[0:1]
	v_mov_b64_e32 v[60:61], v[0:1]
	v_mov_b64_e32 v[48:49], v[0:1]
	v_mov_b64_e32 v[44:45], v[0:1]
	v_mov_b64_e32 v[32:33], v[0:1]
	v_mov_b64_e32 v[28:29], v[0:1]
	v_mov_b64_e32 v[16:17], v[0:1]
	v_mov_b64_e32 v[12:13], v[0:1]
	v_mov_b64_e32 v[56:57], v[0:1]
	v_mov_b64_e32 v[52:53], v[0:1]
	v_mov_b64_e32 v[40:41], v[0:1]
	v_mov_b64_e32 v[36:37], v[0:1]
	v_mov_b64_e32 v[24:25], v[0:1]
	v_mov_b64_e32 v[20:21], v[0:1]
	v_mov_b64_e32 v[8:9], v[0:1]
	v_mov_b64_e32 v[4:5], v[0:1]
	s_waitcnt vmcnt(0)
.LBB0_1691:
	s_waitcnt vmcnt(6)
	v_fmamk_f32 v1, v235, 0x3a800000, v227
	v_mul_f32_e32 v2, 0x4b800000, v1
	v_cmp_gt_f32_e32 vcc, s62, v1
	v_lshl_add_u32 v132, s4, 8, v218
	v_mad_i64_i32 v[134:135], s[16:17], v132, s63, 0
	v_cndmask_b32_e32 v1, v1, v2, vcc
	v_rsq_f32_e32 v1, v1
	v_lshl_or_b32 v2, s8, 8, v220
	v_cmp_lt_i32_e64 s[16:17], s65, v2
	v_mul_f32_e32 v3, 0x45800000, v1
	v_cndmask_b32_e32 v136, v1, v3, vcc
	v_pk_mul_f32 v[130:131], v[136:137], v[130:131] op_sel_hi:[0,1]
	v_pk_mul_f32 v[128:129], v[136:137], v[128:129] op_sel_hi:[0,1]
	v_pk_mul_f32 v[126:127], v[136:137], v[126:127] op_sel_hi:[0,1]
	v_pk_mul_f32 v[124:125], v[136:137], v[124:125] op_sel_hi:[0,1]
	s_and_saveexec_b64 s[18:19], s[16:17]
	s_xor_b64 s[18:19], exec, s[18:19]
	s_cbranch_execz .LBB0_1695
	v_cmp_gt_u32_e32 vcc, s66, v2
	v_mov_b32_e32 v140, 0
	s_and_saveexec_b64 s[20:21], vcc
	s_cbranch_execz .LBB0_1694
	v_mov_b32_e32 v140, v125
	v_mov_b32_e32 v141, v129
	v_mov_b32_e32 v138, v124
	v_mov_b32_e32 v139, v128
	v_pk_mul_f32 v[140:141], v[140:141], v[140:141]
	v_mov_b32_e32 v142, v127
	v_mov_b32_e32 v143, v131
	v_pk_fma_f32 v[138:139], v[138:139], v[138:139], v[140:141]
	v_mov_b32_e32 v140, v126
	v_mov_b32_e32 v141, v130
	v_pk_mul_f32 v[142:143], v[142:143], v[142:143]
	v_cvt_pk_bf16_f32 v128, v128, v129
	v_cvt_pk_bf16_f32 v129, v130, v131
	v_cvt_pk_bf16_f32 v130, v124, v125
	v_lshl_add_u64 v[124:125], s[78:79], 0, v[134:135]
	v_pk_fma_f32 v[140:141], v[140:141], v[140:141], v[142:143]
	v_mov_b32_e32 v3, v0
	v_pk_add_f32 v[138:139], v[138:139], v[140:141]
	v_lshl_add_u64 v[124:125], v[2:3], 1, v[124:125]
	v_add_f32_e32 v140, v138, v139
	v_cvt_pk_bf16_f32 v131, v126, v127
	global_store_dwordx4 v[124:125], v[128:131], off offset:-640

.LBB0_2901:
	s_waitcnt vmcnt(6)
	v_fmamk_f32 v1, v233, 0x3a800000, v226
	v_mul_f32_e32 v2, 0x4b800000, v1
	v_cmp_gt_f32_e32 vcc, s47, v1
	v_mov_b32_e32 v134, v128
	v_mov_b32_e32 v135, v124
	v_cndmask_b32_e32 v1, v1, v2, vcc
	v_rsq_f32_e32 v3, v1
	v_mov_b32_e32 v124, v129
	v_readlane_b32 s12, v255, 18
	v_lshl_or_b32 v2, s24, 7, v221
	v_mul_f32_e32 v132, 0x45800000, v3
	v_cndmask_b32_e32 v132, v3, v132, vcc
	v_pk_mul_f32 v[134:135], v[132:133], v[134:135] op_sel_hi:[0,1]
	v_mul_f32_e32 v3, 0xbfb8aa3b, v135
	v_pk_mul_f32 v[124:125], v[132:133], v[124:125] op_sel_hi:[0,1]
	v_exp_f32_e32 v3, v3
	v_mul_f32_e32 v128, 0xbfb8aa3b, v125
	v_exp_f32_e32 v128, v128
	v_readlane_b32 s13, v255, 19
	v_add_f32_e32 v3, 1.0, v3
	v_rcp_f32_e32 v129, v3
	v_add_f32_e32 v3, 1.0, v128
	v_rcp_f32_e32 v128, v3
	v_lshl_add_u32 v1, s22, 8, v219
	v_mul_f32_e32 v129, v135, v129
	v_mul_f32_e32 v133, v134, v129
	v_mul_f32_e32 v125, v125, v128
	v_mov_b32_e32 v128, v130
	v_mov_b32_e32 v129, v126
	v_pk_mul_f32 v[128:129], v[132:133], v[128:129] op_sel_hi:[0,1]
	v_mul_f32_e32 v126, 0xbfb8aa3b, v129
	v_exp_f32_e32 v130, v126
	v_mov_b32_e32 v126, v131
	v_pk_mul_f32 v[126:127], v[132:133], v[126:127] op_sel_hi:[0,1]
	v_mul_f32_e32 v131, 0xbfb8aa3b, v127
	v_exp_f32_e32 v131, v131
	v_mul_f32_e32 v134, v124, v125
	v_add_f32_e32 v124, 1.0, v130
	v_rcp_f32_e32 v130, v124
	v_add_f32_e32 v124, 1.0, v131
	v_rcp_f32_e32 v131, v124
	v_mov_b32_e32 v124, v120
	v_mov_b32_e32 v125, v116
	v_pk_mul_f32 v[124:125], v[132:133], v[124:125] op_sel_hi:[0,1]
	v_mul_f32_e32 v116, 0xbfb8aa3b, v125
	v_exp_f32_e32 v116, v116
	v_mul_f32_e32 v120, v129, v130
	v_mul_f32_e32 v128, v128, v120
	v_mul_f32_e32 v120, v127, v131
	v_add_f32_e32 v116, 1.0, v116
	v_rcp_f32_e32 v127, v116
	v_mov_b32_e32 v116, v121
	v_pk_mul_f32 v[116:117], v[132:133], v[116:117] op_sel_hi:[0,1]
	v_mul_f32_e32 v121, 0xbfb8aa3b, v117
	v_exp_f32_e32 v121, v121
	v_mul_f32_e32 v126, v126, v120
	v_mul_f32_e32 v120, v125, v127
	v_mul_f32_e32 v124, v124, v120
	v_add_f32_e32 v120, 1.0, v121
	v_rcp_f32_e32 v125, v120
	v_mov_b32_e32 v120, v122
	v_mov_b32_e32 v121, v118
	v_pk_mul_f32 v[120:121], v[132:133], v[120:121] op_sel_hi:[0,1]
	v_mul_f32_e32 v118, 0xbfb8aa3b, v121
	v_exp_f32_e32 v122, v118
	v_mov_b32_e32 v118, v123
	v_pk_mul_f32 v[118:119], v[132:133], v[118:119] op_sel_hi:[0,1]
	v_mul_f32_e32 v123, 0xbfb8aa3b, v119
	v_exp_f32_e32 v123, v123
	v_add_f32_e32 v122, 1.0, v122
	v_rcp_f32_e32 v122, v122
	v_mul_f32_e32 v117, v117, v125
	v_add_f32_e32 v123, 1.0, v123
	v_rcp_f32_e32 v123, v123
	v_mul_f32_e32 v116, v116, v117
	v_mul_f32_e32 v117, v121, v122
	v_fmamk_f32 v122, v232, 0x3a800000, v226
	v_mul_f32_e32 v119, v119, v123
	v_mul_f32_e32 v123, 0x4b800000, v122
	v_cmp_gt_f32_e32 vcc, s47, v122
	v_mul_f32_e32 v117, v120, v117
	v_mul_f32_e32 v121, v118, v119
	v_cndmask_b32_e32 v122, v122, v123, vcc
	v_cvt_pk_bf16_f32 v118, v133, v134
	v_cvt_pk_bf16_f32 v119, v128, v126
	v_cvt_pk_bf16_f32 v120, v124, v116
	v_rsq_f32_e32 v124, v122
	v_mov_b32_e32 v126, v112
	v_mov_b32_e32 v127, v108
	v_ashrrev_i32_e32 v3, 31, v2
	v_mul_f32_e32 v125, 0x45800000, v124
	v_cndmask_b32_e32 v124, v124, v125, vcc
	v_pk_mul_f32 v[126:127], v[124:125], v[126:127] op_sel_hi:[0,1]
	v_mul_f32_e32 v108, 0xbfb8aa3b, v127
	v_exp_f32_e32 v125, v108
	v_mov_b32_e32 v108, v113
	v_cvt_pk_bf16_f32 v121, v117, v121
	v_mov_b64_e32 v[116:117], s[12:13]
	v_pk_mul_f32 v[108:109], v[124:125], v[108:109] op_sel_hi:[0,1]
	v_mad_i64_i32 v[122:123], s[12:13], v1, s55, v[116:117]
	v_lshlrev_b64 v[2:3], 1, v[2:3]
	v_mul_f32_e32 v112, 0xbfb8aa3b, v109
	v_exp_f32_e32 v128, v112
	v_lshl_add_u64 v[112:113], v[122:123], 0, v[2:3]
	v_add_f32_e32 v122, 1.0, v125
	v_rcp_f32_e32 v122, v122
	global_store_dwordx4 v[112:113], v[118:121], off
	v_mov_b32_e32 v113, v110
	v_add_f32_e32 v123, 1.0, v128
	v_mul_f32_e32 v112, v127, v122
	v_mul_f32_e32 v118, v126, v112
	v_mov_b32_e32 v112, v114
	v_pk_mul_f32 v[112:113], v[124:125], v[112:113] op_sel_hi:[0,1]
	v_mul_f32_e32 v110, 0xbfb8aa3b, v113
	v_exp_f32_e32 v114, v110
	v_mov_b32_e32 v110, v115
	v_rcp_f32_e32 v123, v123
	v_pk_mul_f32 v[110:111], v[124:125], v[110:111] op_sel_hi:[0,1]
	v_mul_f32_e32 v115, 0xbfb8aa3b, v111
	v_exp_f32_e32 v115, v115
	v_mul_f32_e32 v109, v109, v123
	v_mul_f32_e32 v119, v108, v109
	v_add_f32_e32 v108, 1.0, v114
	v_rcp_f32_e32 v114, v108
	v_add_f32_e32 v108, 1.0, v115
	v_rcp_f32_e32 v115, v108
	v_mov_b32_e32 v108, v104
	v_mov_b32_e32 v109, v100
	v_pk_mul_f32 v[108:109], v[124:125], v[108:109] op_sel_hi:[0,1]
	v_mul_f32_e32 v100, 0xbfb8aa3b, v109
	v_exp_f32_e32 v100, v100
	v_mul_f32_e32 v104, v113, v114
	v_mul_f32_e32 v112, v112, v104
	v_mul_f32_e32 v104, v111, v115
	v_add_f32_e32 v100, 1.0, v100
	v_rcp_f32_e32 v111, v100
	v_mov_b32_e32 v100, v105
	v_pk_mul_f32 v[100:101], v[124:125], v[100:101] op_sel_hi:[0,1]
	v_mul_f32_e32 v105, 0xbfb8aa3b, v101
	v_exp_f32_e32 v105, v105
	v_mul_f32_e32 v110, v110, v104
	v_mul_f32_e32 v104, v109, v111
	v_mul_f32_e32 v108, v108, v104
	v_add_f32_e32 v104, 1.0, v105
	v_rcp_f32_e32 v109, v104
	v_mov_b32_e32 v104, v106
	v_mov_b32_e32 v105, v102
	v_pk_mul_f32 v[104:105], v[124:125], v[104:105] op_sel_hi:[0,1]
	v_mul_f32_e32 v102, 0xbfb8aa3b, v105
	v_exp_f32_e32 v106, v102
	v_mov_b32_e32 v102, v107
	v_pk_mul_f32 v[102:103], v[124:125], v[102:103] op_sel_hi:[0,1]
	v_mul_f32_e32 v107, 0xbfb8aa3b, v103
	v_exp_f32_e32 v107, v107
	v_add_f32_e32 v106, 1.0, v106
	v_rcp_f32_e32 v106, v106
	v_mul_f32_e32 v101, v101, v109
	v_add_f32_e32 v107, 1.0, v107
	v_rcp_f32_e32 v107, v107
	v_mul_f32_e32 v109, v100, v101
	v_mul_f32_e32 v100, v105, v106
	v_fmamk_f32 v106, v231, 0x3a800000, v226
	v_mul_f32_e32 v104, v104, v100
	v_mul_f32_e32 v100, v103, v107
	v_mul_f32_e32 v107, 0x4b800000, v106
	v_cmp_gt_f32_e32 vcc, s47, v106
	v_mul_f32_e32 v103, v102, v100
	v_cvt_pk_bf16_f32 v100, v118, v119
	v_cvt_pk_bf16_f32 v101, v112, v110
	v_cvt_pk_bf16_f32 v102, v108, v109
	v_mov_b32_e32 v108, v96
	v_cndmask_b32_e32 v106, v106, v107, vcc
	v_rsq_f32_e32 v106, v106
	v_mov_b32_e32 v109, v92
	v_or_b32_e32 v105, 16, v1
	v_cvt_pk_bf16_f32 v103, v104, v103
	v_mul_f32_e32 v107, 0x45800000, v106
	v_cndmask_b32_e32 v106, v106, v107, vcc
	v_pk_mul_f32 v[108:109], v[106:107], v[108:109] op_sel_hi:[0,1]
	v_mul_f32_e32 v92, 0xbfb8aa3b, v109
	v_exp_f32_e32 v107, v92
	v_mov_b32_e32 v92, v97
	v_mad_i64_i32 v[104:105], s[12:13], v105, s55, v[116:117]
	v_pk_mul_f32 v[92:93], v[106:107], v[92:93] op_sel_hi:[0,1]
	v_mul_f32_e32 v96, 0xbfb8aa3b, v93
	v_exp_f32_e32 v110, v96
	v_lshl_add_u64 v[96:97], v[104:105], 0, v[2:3]
	v_add_f32_e32 v104, 1.0, v107
	v_rcp_f32_e32 v104, v104
	global_store_dwordx4 v[96:97], v[100:103], off
	v_mov_b32_e32 v97, v94
	v_add_f32_e32 v105, 1.0, v110
	v_mul_f32_e32 v96, v109, v104
	v_mul_f32_e32 v100, v108, v96
	v_mov_b32_e32 v96, v98
	v_pk_mul_f32 v[96:97], v[106:107], v[96:97] op_sel_hi:[0,1]
	v_mul_f32_e32 v94, 0xbfb8aa3b, v97
	v_exp_f32_e32 v98, v94
	v_mov_b32_e32 v94, v99
	v_rcp_f32_e32 v105, v105
	v_pk_mul_f32 v[94:95], v[106:107], v[94:95] op_sel_hi:[0,1]
	v_mul_f32_e32 v99, 0xbfb8aa3b, v95
	v_exp_f32_e32 v99, v99
	v_mul_f32_e32 v93, v93, v105
	v_mul_f32_e32 v101, v92, v93
	v_add_f32_e32 v92, 1.0, v98
	v_rcp_f32_e32 v98, v92
	v_add_f32_e32 v92, 1.0, v99
	v_rcp_f32_e32 v99, v92
	v_mov_b32_e32 v92, v88
	v_mov_b32_e32 v93, v84
	v_pk_mul_f32 v[92:93], v[106:107], v[92:93] op_sel_hi:[0,1]
	v_mul_f32_e32 v84, 0xbfb8aa3b, v93
	v_exp_f32_e32 v84, v84
	v_mul_f32_e32 v88, v97, v98
	v_mul_f32_e32 v96, v96, v88
	v_mul_f32_e32 v88, v95, v99
	v_add_f32_e32 v84, 1.0, v84
	v_rcp_f32_e32 v95, v84
	v_mov_b32_e32 v84, v89
	v_pk_mul_f32 v[84:85], v[106:107], v[84:85] op_sel_hi:[0,1]
	v_mul_f32_e32 v89, 0xbfb8aa3b, v85
	v_exp_f32_e32 v89, v89
	v_mul_f32_e32 v94, v94, v88
	v_mul_f32_e32 v88, v93, v95
	v_mul_f32_e32 v92, v92, v88
	v_add_f32_e32 v88, 1.0, v89
	v_rcp_f32_e32 v93, v88
	v_mov_b32_e32 v88, v90
	v_mov_b32_e32 v89, v86
	v_pk_mul_f32 v[88:89], v[106:107], v[88:89] op_sel_hi:[0,1]
	v_mul_f32_e32 v86, 0xbfb8aa3b, v89
	v_exp_f32_e32 v90, v86
	v_mov_b32_e32 v86, v91
	v_pk_mul_f32 v[86:87], v[106:107], v[86:87] op_sel_hi:[0,1]
	v_mul_f32_e32 v91, 0xbfb8aa3b, v87
	v_exp_f32_e32 v91, v91
	v_add_f32_e32 v90, 1.0, v90
	v_rcp_f32_e32 v90, v90
	v_mul_f32_e32 v85, v85, v93
	v_add_f32_e32 v91, 1.0, v91
	v_rcp_f32_e32 v91, v91
	v_mul_f32_e32 v93, v84, v85
	v_mul_f32_e32 v84, v89, v90
	v_fmamk_f32 v90, v230, 0x3a800000, v226
	v_mul_f32_e32 v88, v88, v84
	v_mul_f32_e32 v84, v87, v91
	v_mul_f32_e32 v91, 0x4b800000, v90
	v_cmp_gt_f32_e32 vcc, s47, v90
	v_mul_f32_e32 v87, v86, v84
	v_cvt_pk_bf16_f32 v84, v100, v101
	v_cvt_pk_bf16_f32 v85, v96, v94
	v_cvt_pk_bf16_f32 v86, v92, v93
	v_mov_b32_e32 v92, v80
	v_cndmask_b32_e32 v90, v90, v91, vcc
	v_rsq_f32_e32 v90, v90
	v_mov_b32_e32 v93, v76
	v_or_b32_e32 v89, 32, v1
	v_cvt_pk_bf16_f32 v87, v88, v87
	v_mul_f32_e32 v91, 0x45800000, v90
	v_cndmask_b32_e32 v90, v90, v91, vcc
	v_pk_mul_f32 v[92:93], v[90:91], v[92:93] op_sel_hi:[0,1]
	v_mul_f32_e32 v76, 0xbfb8aa3b, v93
	v_exp_f32_e32 v91, v76
	v_mov_b32_e32 v76, v81
	v_mad_i64_i32 v[88:89], s[12:13], v89, s55, v[116:117]
	v_pk_mul_f32 v[76:77], v[90:91], v[76:77] op_sel_hi:[0,1]
	v_mul_f32_e32 v80, 0xbfb8aa3b, v77
	v_exp_f32_e32 v94, v80
	v_lshl_add_u64 v[80:81], v[88:89], 0, v[2:3]
	v_add_f32_e32 v88, 1.0, v91
	v_rcp_f32_e32 v88, v88
	global_store_dwordx4 v[80:81], v[84:87], off
	v_mov_b32_e32 v81, v78
	v_add_f32_e32 v89, 1.0, v94
	v_mul_f32_e32 v80, v93, v88
	v_mul_f32_e32 v84, v92, v80
	v_mov_b32_e32 v80, v82
	v_pk_mul_f32 v[80:81], v[90:91], v[80:81] op_sel_hi:[0,1]
	v_mul_f32_e32 v78, 0xbfb8aa3b, v81
	v_exp_f32_e32 v82, v78
	v_mov_b32_e32 v78, v83
	v_rcp_f32_e32 v89, v89
	v_pk_mul_f32 v[78:79], v[90:91], v[78:79] op_sel_hi:[0,1]
	v_mul_f32_e32 v83, 0xbfb8aa3b, v79
	v_exp_f32_e32 v83, v83
	v_mul_f32_e32 v77, v77, v89
	v_mul_f32_e32 v85, v76, v77
	v_add_f32_e32 v76, 1.0, v82
	v_rcp_f32_e32 v82, v76
	v_add_f32_e32 v76, 1.0, v83
	v_rcp_f32_e32 v83, v76
	v_mov_b32_e32 v76, v68
	v_mov_b32_e32 v77, v72
	v_pk_mul_f32 v[76:77], v[90:91], v[76:77] op_sel_hi:[0,1]
	v_mul_f32_e32 v68, 0xbfb8aa3b, v77
	v_exp_f32_e32 v68, v68
	v_mul_f32_e32 v72, v81, v82
	v_mul_f32_e32 v80, v80, v72
	v_mov_b32_e32 v72, v69
	v_add_f32_e32 v68, 1.0, v68
	v_rcp_f32_e32 v81, v68
	v_pk_mul_f32 v[68:69], v[90:91], v[72:73] op_sel_hi:[0,1]
	v_mul_f32_e32 v72, 0xbfb8aa3b, v69
	v_exp_f32_e32 v72, v72
	v_mul_f32_e32 v73, v77, v81
	v_mul_f32_e32 v76, v76, v73
	v_mov_b32_e32 v73, v74
	v_add_f32_e32 v72, 1.0, v72
	v_rcp_f32_e32 v77, v72
	v_mov_b32_e32 v72, v70
	v_pk_mul_f32 v[72:73], v[90:91], v[72:73] op_sel_hi:[0,1]
	v_mul_f32_e32 v79, v79, v83
	v_mul_f32_e32 v70, 0xbfb8aa3b, v73
	v_mov_b32_e32 v74, v71
	v_mul_f32_e32 v78, v78, v79
	v_exp_f32_e32 v79, v70
	v_pk_mul_f32 v[70:71], v[90:91], v[74:75] op_sel_hi:[0,1]
	v_mul_f32_e32 v74, 0xbfb8aa3b, v71
	v_exp_f32_e32 v74, v74
	v_add_f32_e32 v75, 1.0, v79
	v_rcp_f32_e32 v75, v75
	v_mul_f32_e32 v69, v69, v77
	v_add_f32_e32 v74, 1.0, v74
	v_rcp_f32_e32 v74, v74
	v_mul_f32_e32 v77, v68, v69
	v_mul_f32_e32 v68, v73, v75
	v_mul_f32_e32 v72, v72, v68
	v_mul_f32_e32 v68, v71, v74
	v_mul_f32_e32 v71, v70, v68
	v_or_b32_e32 v73, 48, v1
	v_cvt_pk_bf16_f32 v68, v84, v85
	v_cvt_pk_bf16_f32 v69, v80, v78
	v_cvt_pk_bf16_f32 v70, v76, v77
	v_cvt_pk_bf16_f32 v71, v72, v71
	v_mad_i64_i32 v[72:73], s[12:13], v73, s55, v[116:117]
	s_cmp_eq_u32 s22, 64
	v_lshl_add_u64 v[72:73], v[72:73], 0, v[2:3]
	global_store_dwordx4 v[72:73], v[68:71], off
	s_cbranch_scc1 .LBB0_2903
	s_nop 0
	v_fmamk_f32 v68, v229, 0x3a800000, v226
	v_mul_f32_e32 v69, 0x4b800000, v68
	v_cmp_gt_f32_e32 vcc, s47, v68
	v_readlane_b32 s12, v255, 18
	v_readlane_b32 s13, v255, 19
	v_cndmask_b32_e32 v68, v68, v69, vcc
	v_rsq_f32_e32 v70, v68
	v_mov_b32_e32 v69, v60
	v_mov_b32_e32 v68, v64
	v_add_u32_e32 v71, 0x80, v1
	v_mul_f32_e32 v60, 0x45800000, v70
	v_cndmask_b32_e32 v64, v70, v60, vcc
	v_pk_mul_f32 v[68:69], v[64:65], v[68:69] op_sel_hi:[0,1]
	v_mul_f32_e32 v60, 0xbfb8aa3b, v69
	v_exp_f32_e32 v70, v60
	v_mov_b32_e32 v60, v65
	v_pk_mul_f32 v[60:61], v[64:65], v[60:61] op_sel_hi:[0,1]
	v_mul_f32_e32 v65, 0xbfb8aa3b, v61
	v_exp_f32_e32 v65, v65
	v_add_f32_e32 v70, 1.0, v70
	v_rcp_f32_e32 v70, v70
	v_add_f32_e32 v65, 1.0, v65
	v_rcp_f32_e32 v65, v65
	v_mul_f32_e32 v69, v69, v70
	v_mul_f32_e32 v70, v68, v69
	v_mov_b32_e32 v68, v66
	v_mov_b32_e32 v69, v62
	v_pk_mul_f32 v[68:69], v[64:65], v[68:69] op_sel_hi:[0,1]
	v_mul_f32_e32 v62, 0xbfb8aa3b, v69
	v_mul_f32_e32 v61, v61, v65
	v_exp_f32_e32 v65, v62
	v_mov_b32_e32 v62, v67
	v_mul_f32_e32 v67, v60, v61
	v_mov_b32_e32 v61, v52
	v_pk_mul_f32 v[62:63], v[64:65], v[62:63] op_sel_hi:[0,1]
	v_mul_f32_e32 v66, 0xbfb8aa3b, v63
	v_exp_f32_e32 v66, v66
	v_add_f32_e32 v60, 1.0, v65
	v_rcp_f32_e32 v65, v60
	v_add_f32_e32 v60, 1.0, v66
	v_rcp_f32_e32 v66, v60
	v_mov_b32_e32 v60, v56
	v_pk_mul_f32 v[60:61], v[64:65], v[60:61] op_sel_hi:[0,1]
	v_mul_f32_e32 v52, 0xbfb8aa3b, v61
	v_exp_f32_e32 v52, v52
	v_mul_f32_e32 v56, v69, v65
	v_mul_f32_e32 v65, v68, v56
	v_mul_f32_e32 v56, v63, v66
	v_add_f32_e32 v52, 1.0, v52
	v_rcp_f32_e32 v63, v52
	v_mov_b32_e32 v52, v57
	v_pk_mul_f32 v[52:53], v[64:65], v[52:53] op_sel_hi:[0,1]
	v_mul_f32_e32 v57, 0xbfb8aa3b, v53
	v_exp_f32_e32 v57, v57
	v_mul_f32_e32 v62, v62, v56
	v_mul_f32_e32 v56, v61, v63
	v_mul_f32_e32 v60, v60, v56
	v_add_f32_e32 v56, 1.0, v57
	v_rcp_f32_e32 v61, v56
	v_mov_b32_e32 v56, v58
	v_mov_b32_e32 v57, v54
	v_pk_mul_f32 v[56:57], v[64:65], v[56:57] op_sel_hi:[0,1]
	v_mul_f32_e32 v54, 0xbfb8aa3b, v57
	v_exp_f32_e32 v58, v54
	v_mov_b32_e32 v54, v59
	v_pk_mul_f32 v[54:55], v[64:65], v[54:55] op_sel_hi:[0,1]
	v_mul_f32_e32 v59, 0xbfb8aa3b, v55
	v_exp_f32_e32 v59, v59
	v_add_f32_e32 v58, 1.0, v58
	v_rcp_f32_e32 v58, v58
	v_mul_f32_e32 v53, v53, v61
	v_add_f32_e32 v59, 1.0, v59
	v_rcp_f32_e32 v59, v59
	v_mul_f32_e32 v52, v52, v53
	v_mul_f32_e32 v53, v57, v58
	v_mul_f32_e32 v53, v56, v53
	v_mul_f32_e32 v55, v55, v59
	v_mul_f32_e32 v57, v54, v55
	v_cvt_pk_bf16_f32 v54, v70, v67
	v_cvt_pk_bf16_f32 v55, v65, v62
	v_cvt_pk_bf16_f32 v56, v60, v52
	v_fmamk_f32 v52, v228, 0x3a800000, v226
	v_cvt_pk_bf16_f32 v57, v53, v57
	v_mul_f32_e32 v53, 0x4b800000, v52
	v_cmp_gt_f32_e32 vcc, s47, v52
	v_mov_b32_e32 v62, v48
	v_mov_b32_e32 v63, v44
	v_cndmask_b32_e32 v52, v52, v53, vcc
	v_rsq_f32_e32 v60, v52
	v_mov_b64_e32 v[52:53], s[12:13]
	v_mad_i64_i32 v[58:59], s[12:13], v71, s55, v[52:53]
	v_mul_f32_e32 v61, 0x45800000, v60
	v_cndmask_b32_e32 v60, v60, v61, vcc
	v_pk_mul_f32 v[62:63], v[60:61], v[62:63] op_sel_hi:[0,1]
	v_mul_f32_e32 v44, 0xbfb8aa3b, v63
	v_exp_f32_e32 v61, v44
	v_mov_b32_e32 v44, v49
	v_pk_mul_f32 v[44:45], v[60:61], v[44:45] op_sel_hi:[0,1]
	v_mul_f32_e32 v48, 0xbfb8aa3b, v45
	v_exp_f32_e32 v64, v48
	v_lshl_add_u64 v[48:49], v[58:59], 0, v[2:3]
	v_add_f32_e32 v58, 1.0, v61
	v_rcp_f32_e32 v58, v58
	global_store_dwordx4 v[48:49], v[54:57], off
	v_mov_b32_e32 v49, v46
	v_add_f32_e32 v59, 1.0, v64
	v_mul_f32_e32 v48, v63, v58
	v_mul_f32_e32 v54, v62, v48
	v_mov_b32_e32 v48, v50
	v_pk_mul_f32 v[48:49], v[60:61], v[48:49] op_sel_hi:[0,1]
	v_mul_f32_e32 v46, 0xbfb8aa3b, v49
	v_exp_f32_e32 v50, v46
	v_mov_b32_e32 v46, v51
	v_rcp_f32_e32 v59, v59
	v_pk_mul_f32 v[46:47], v[60:61], v[46:47] op_sel_hi:[0,1]
	v_mul_f32_e32 v51, 0xbfb8aa3b, v47
	v_exp_f32_e32 v51, v51
	v_mul_f32_e32 v45, v45, v59
	v_mul_f32_e32 v55, v44, v45
	v_add_f32_e32 v44, 1.0, v50
	v_rcp_f32_e32 v50, v44
	v_add_f32_e32 v44, 1.0, v51
	v_rcp_f32_e32 v51, v44
	v_mov_b32_e32 v44, v40
	v_mov_b32_e32 v45, v36
	v_pk_mul_f32 v[44:45], v[60:61], v[44:45] op_sel_hi:[0,1]
	v_mul_f32_e32 v36, 0xbfb8aa3b, v45
	v_exp_f32_e32 v36, v36
	v_mul_f32_e32 v40, v49, v50
	v_mul_f32_e32 v48, v48, v40
	v_mul_f32_e32 v40, v47, v51
	v_add_f32_e32 v36, 1.0, v36
	v_rcp_f32_e32 v47, v36
	v_mov_b32_e32 v36, v41
	v_pk_mul_f32 v[36:37], v[60:61], v[36:37] op_sel_hi:[0,1]
	v_mul_f32_e32 v41, 0xbfb8aa3b, v37
	v_exp_f32_e32 v41, v41
	v_mul_f32_e32 v46, v46, v40
	v_mul_f32_e32 v40, v45, v47
	v_mul_f32_e32 v44, v44, v40
	v_add_f32_e32 v40, 1.0, v41
	v_rcp_f32_e32 v45, v40
	v_mov_b32_e32 v40, v42
	v_mov_b32_e32 v41, v38
	v_pk_mul_f32 v[40:41], v[60:61], v[40:41] op_sel_hi:[0,1]
	v_mul_f32_e32 v38, 0xbfb8aa3b, v41
	v_exp_f32_e32 v42, v38
	v_mov_b32_e32 v38, v43
	v_pk_mul_f32 v[38:39], v[60:61], v[38:39] op_sel_hi:[0,1]
	v_mul_f32_e32 v43, 0xbfb8aa3b, v39
	v_exp_f32_e32 v43, v43
	v_add_f32_e32 v42, 1.0, v42
	v_rcp_f32_e32 v42, v42
	v_mul_f32_e32 v37, v37, v45
	v_add_f32_e32 v43, 1.0, v43
	v_rcp_f32_e32 v43, v43
	v_mul_f32_e32 v45, v36, v37
	v_mul_f32_e32 v36, v41, v42
	v_fmamk_f32 v42, v227, 0x3a800000, v226
	v_mul_f32_e32 v40, v40, v36
	v_mul_f32_e32 v36, v39, v43
	v_mul_f32_e32 v43, 0x4b800000, v42
	v_cmp_gt_f32_e32 vcc, s47, v42
	v_mul_f32_e32 v39, v38, v36
	v_cvt_pk_bf16_f32 v36, v54, v55
	v_cvt_pk_bf16_f32 v37, v48, v46
	v_cvt_pk_bf16_f32 v38, v44, v45
	v_mov_b32_e32 v44, v32
	v_cndmask_b32_e32 v42, v42, v43, vcc
	v_rsq_f32_e32 v42, v42
	v_mov_b32_e32 v45, v28
	v_add_u32_e32 v41, 0x90, v1
	v_cvt_pk_bf16_f32 v39, v40, v39
	v_mul_f32_e32 v43, 0x45800000, v42
	v_cndmask_b32_e32 v42, v42, v43, vcc
	v_pk_mul_f32 v[44:45], v[42:43], v[44:45] op_sel_hi:[0,1]
	v_mul_f32_e32 v28, 0xbfb8aa3b, v45
	v_exp_f32_e32 v43, v28
	v_mov_b32_e32 v28, v33
	v_mad_i64_i32 v[40:41], s[12:13], v41, s55, v[52:53]
	v_pk_mul_f32 v[28:29], v[42:43], v[28:29] op_sel_hi:[0,1]
	v_mul_f32_e32 v32, 0xbfb8aa3b, v29
	v_exp_f32_e32 v46, v32
	v_lshl_add_u64 v[32:33], v[40:41], 0, v[2:3]
	v_add_f32_e32 v40, 1.0, v43
	v_rcp_f32_e32 v40, v40
	global_store_dwordx4 v[32:33], v[36:39], off
	v_mov_b32_e32 v33, v30
	v_add_f32_e32 v41, 1.0, v46
	v_mul_f32_e32 v32, v45, v40
	v_mul_f32_e32 v36, v44, v32
	v_mov_b32_e32 v32, v34
	v_pk_mul_f32 v[32:33], v[42:43], v[32:33] op_sel_hi:[0,1]
	v_mul_f32_e32 v30, 0xbfb8aa3b, v33
	v_exp_f32_e32 v34, v30
	v_mov_b32_e32 v30, v35
	v_rcp_f32_e32 v41, v41
	v_pk_mul_f32 v[30:31], v[42:43], v[30:31] op_sel_hi:[0,1]
	v_mul_f32_e32 v35, 0xbfb8aa3b, v31
	v_exp_f32_e32 v35, v35
	v_mul_f32_e32 v29, v29, v41
	v_mul_f32_e32 v37, v28, v29
	v_add_f32_e32 v28, 1.0, v34
	v_rcp_f32_e32 v34, v28
	v_add_f32_e32 v28, 1.0, v35
	v_rcp_f32_e32 v35, v28
	v_mov_b32_e32 v28, v24
	v_mov_b32_e32 v29, v20
	v_pk_mul_f32 v[28:29], v[42:43], v[28:29] op_sel_hi:[0,1]
	v_mul_f32_e32 v20, 0xbfb8aa3b, v29
	v_exp_f32_e32 v20, v20
	v_mul_f32_e32 v24, v33, v34
	v_mul_f32_e32 v32, v32, v24
	v_mul_f32_e32 v24, v31, v35
	v_add_f32_e32 v20, 1.0, v20
	v_rcp_f32_e32 v31, v20
	v_mov_b32_e32 v20, v25
	v_pk_mul_f32 v[20:21], v[42:43], v[20:21] op_sel_hi:[0,1]
	v_mul_f32_e32 v25, 0xbfb8aa3b, v21
	v_exp_f32_e32 v25, v25
	v_mul_f32_e32 v30, v30, v24
	v_mul_f32_e32 v24, v29, v31
	v_mul_f32_e32 v28, v28, v24
	v_add_f32_e32 v24, 1.0, v25
	v_rcp_f32_e32 v29, v24
	v_mov_b32_e32 v24, v26
	v_mov_b32_e32 v25, v22
	v_pk_mul_f32 v[24:25], v[42:43], v[24:25] op_sel_hi:[0,1]
	v_mul_f32_e32 v22, 0xbfb8aa3b, v25
	v_exp_f32_e32 v26, v22
	v_mov_b32_e32 v22, v27
	v_pk_mul_f32 v[22:23], v[42:43], v[22:23] op_sel_hi:[0,1]
	v_mul_f32_e32 v27, 0xbfb8aa3b, v23
	v_exp_f32_e32 v27, v27
	v_add_f32_e32 v26, 1.0, v26
	v_rcp_f32_e32 v26, v26
	v_mul_f32_e32 v21, v21, v29
	v_add_f32_e32 v27, 1.0, v27
	v_rcp_f32_e32 v27, v27
	v_mul_f32_e32 v29, v20, v21
	v_mul_f32_e32 v20, v25, v26
	v_fmamk_f32 v26, v218, 0x3a800000, v226
	v_mul_f32_e32 v24, v24, v20
	v_mul_f32_e32 v20, v23, v27
	v_mul_f32_e32 v27, 0x4b800000, v26
	v_cmp_gt_f32_e32 vcc, s47, v26
	v_mul_f32_e32 v23, v22, v20
	v_cvt_pk_bf16_f32 v20, v36, v37
	v_cvt_pk_bf16_f32 v21, v32, v30
	v_cvt_pk_bf16_f32 v22, v28, v29
	v_mov_b32_e32 v28, v16
	v_cndmask_b32_e32 v26, v26, v27, vcc
	v_rsq_f32_e32 v26, v26
	v_mov_b32_e32 v29, v12
	v_add_u32_e32 v25, 0xa0, v1
	v_cvt_pk_bf16_f32 v23, v24, v23
	v_mul_f32_e32 v27, 0x45800000, v26
	v_cndmask_b32_e32 v26, v26, v27, vcc
	v_pk_mul_f32 v[28:29], v[26:27], v[28:29] op_sel_hi:[0,1]
	v_mul_f32_e32 v12, 0xbfb8aa3b, v29
	v_exp_f32_e32 v27, v12
	v_mov_b32_e32 v12, v17
	v_mad_i64_i32 v[24:25], s[12:13], v25, s55, v[52:53]
	v_pk_mul_f32 v[12:13], v[26:27], v[12:13] op_sel_hi:[0,1]
	v_mul_f32_e32 v16, 0xbfb8aa3b, v13
	v_exp_f32_e32 v30, v16
	v_lshl_add_u64 v[16:17], v[24:25], 0, v[2:3]
	v_add_f32_e32 v24, 1.0, v27
	v_rcp_f32_e32 v24, v24
	global_store_dwordx4 v[16:17], v[20:23], off
	v_mov_b32_e32 v17, v14
	v_add_f32_e32 v25, 1.0, v30
	v_mul_f32_e32 v16, v29, v24
	v_mul_f32_e32 v20, v28, v16
	v_mov_b32_e32 v16, v18
	v_pk_mul_f32 v[16:17], v[26:27], v[16:17] op_sel_hi:[0,1]
	v_mul_f32_e32 v14, 0xbfb8aa3b, v17
	v_exp_f32_e32 v18, v14
	v_mov_b32_e32 v14, v19
	v_rcp_f32_e32 v25, v25
	v_pk_mul_f32 v[14:15], v[26:27], v[14:15] op_sel_hi:[0,1]
	v_mul_f32_e32 v19, 0xbfb8aa3b, v15
	v_exp_f32_e32 v19, v19
	v_mul_f32_e32 v13, v13, v25
	v_mul_f32_e32 v21, v12, v13
	v_add_f32_e32 v12, 1.0, v18
	v_rcp_f32_e32 v18, v12
	v_add_f32_e32 v12, 1.0, v19
	v_rcp_f32_e32 v19, v12
	v_mov_b32_e32 v12, v8
	v_mov_b32_e32 v13, v4
	v_pk_mul_f32 v[12:13], v[26:27], v[12:13] op_sel_hi:[0,1]
	v_mul_f32_e32 v4, 0xbfb8aa3b, v13
	v_exp_f32_e32 v4, v4
	v_mul_f32_e32 v8, v17, v18
	v_mul_f32_e32 v16, v16, v8
	v_mul_f32_e32 v8, v15, v19
	v_add_f32_e32 v4, 1.0, v4
	v_rcp_f32_e32 v15, v4
	v_mov_b32_e32 v4, v9
	v_pk_mul_f32 v[4:5], v[26:27], v[4:5] op_sel_hi:[0,1]
	v_mul_f32_e32 v9, 0xbfb8aa3b, v5
	v_exp_f32_e32 v9, v9
	v_mul_f32_e32 v14, v14, v8
	v_mul_f32_e32 v8, v13, v15
	v_mul_f32_e32 v12, v12, v8
	v_add_f32_e32 v8, 1.0, v9
	v_rcp_f32_e32 v13, v8
	v_mov_b32_e32 v8, v10
	v_mov_b32_e32 v9, v6
	v_pk_mul_f32 v[8:9], v[26:27], v[8:9] op_sel_hi:[0,1]
	v_mul_f32_e32 v6, 0xbfb8aa3b, v9
	v_exp_f32_e32 v10, v6
	v_mov_b32_e32 v6, v11
	v_pk_mul_f32 v[6:7], v[26:27], v[6:7] op_sel_hi:[0,1]
	v_mul_f32_e32 v11, 0xbfb8aa3b, v7
	v_exp_f32_e32 v11, v11
	v_add_f32_e32 v10, 1.0, v10
	v_rcp_f32_e32 v10, v10
	v_mul_f32_e32 v5, v5, v13
	v_add_f32_e32 v11, 1.0, v11
	v_rcp_f32_e32 v11, v11
	v_mul_f32_e32 v13, v4, v5
	v_mul_f32_e32 v4, v9, v10
	v_mul_f32_e32 v8, v8, v4
	v_mul_f32_e32 v4, v7, v11
	v_mul_f32_e32 v7, v6, v4
	v_add_u32_e32 v1, 0xb0, v1
	v_cvt_pk_bf16_f32 v4, v20, v21
	v_cvt_pk_bf16_f32 v5, v16, v14
	v_cvt_pk_bf16_f32 v6, v12, v13
	v_cvt_pk_bf16_f32 v7, v8, v7
	v_mad_i64_i32 v[8:9], s[12:13], v1, s55, v[52:53]
	v_lshl_add_u64 v[2:3], v[8:9], 0, v[2:3]
	global_store_dwordx4 v[2:3], v[4:7], off

.LBB0_3193:
	s_waitcnt vmcnt(6)
	v_fmamk_f32 v1, v235, 0x3a800000, v227
	v_mul_f32_e32 v2, 0x4b800000, v1
	v_cmp_gt_f32_e32 vcc, s66, v1
	s_lshl_b32 s27, s18, 8
	s_cmp_lt_i32 s18, 0
	v_cndmask_b32_e32 v1, v1, v2, vcc
	v_rsq_f32_e32 v1, v1
	v_lshl_add_u32 v132, s4, 8, v218
	s_cselect_b64 s[16:17], -1, 0
	s_cmp_gt_i32 s18, -1
	v_mul_f32_e32 v3, 0x45800000, v1
	s_cselect_b64 s[14:15], -1, 0
	v_cndmask_b32_e32 v136, v1, v3, vcc
	v_mad_i64_i32 v[134:135], s[12:13], v132, s67, 0
	v_or_b32_e32 v2, s27, v220
	v_pk_mul_f32 v[130:131], v[136:137], v[130:131] op_sel_hi:[0,1]
	v_pk_mul_f32 v[128:129], v[136:137], v[128:129] op_sel_hi:[0,1]
	v_pk_mul_f32 v[126:127], v[136:137], v[126:127] op_sel_hi:[0,1]
	v_pk_mul_f32 v[124:125], v[136:137], v[124:125] op_sel_hi:[0,1]
	s_mov_b64 s[12:13], -1
	s_and_b64 vcc, exec, s[14:15]
	s_cbranch_vccz .LBB0_3197
	s_cmpk_gt_u32 s27, 0x17f
	v_mov_b32_e32 v140, 0
	s_cbranch_scc1 .LBB0_3196
	v_mov_b32_e32 v140, v125
	v_mov_b32_e32 v141, v129
	v_mov_b32_e32 v138, v124
	v_mov_b32_e32 v139, v128
	v_pk_mul_f32 v[140:141], v[140:141], v[140:141]
	v_mov_b32_e32 v142, v127
	v_mov_b32_e32 v143, v131
	v_pk_fma_f32 v[138:139], v[138:139], v[138:139], v[140:141]
	v_mov_b32_e32 v140, v126
	v_mov_b32_e32 v141, v130
	v_pk_mul_f32 v[142:143], v[142:143], v[142:143]
	v_mov_b32_e32 v3, v0
	v_pk_fma_f32 v[140:141], v[140:141], v[140:141], v[142:143]
	v_cvt_pk_bf16_f32 v142, v128, v129
	v_cvt_pk_bf16_f32 v143, v130, v131
	v_cvt_pk_bf16_f32 v144, v124, v125
	v_cvt_pk_bf16_f32 v145, v126, v127
	s_nop 0
	v_pk_add_f32 v[138:139], v[138:139], v[140:141]
	s_nop 0
	v_add_f32_e32 v140, v138, v139
	v_lshl_add_u64 v[138:139], s[78:79], 0, v[134:135]
	v_lshl_add_u64 v[138:139], v[2:3], 1, v[138:139]
	global_store_dwordx4 v[138:139], v[142:145], off

.LBB0_4161:
	s_waitcnt vmcnt(6)
	v_fmamk_f32 v1, v233, 0x3a800000, v226
	v_mul_f32_e32 v2, 0x4b800000, v1
	v_cmp_gt_f32_e32 vcc, s50, v1
	v_mov_b32_e32 v134, v128
	v_mov_b32_e32 v135, v124
	v_cndmask_b32_e32 v1, v1, v2, vcc
	v_rsq_f32_e32 v3, v1
	v_mov_b32_e32 v124, v129
	v_readlane_b32 s8, v255, 18
	v_lshl_or_b32 v2, s22, 7, v221
	v_mul_f32_e32 v132, 0x45800000, v3
	v_cndmask_b32_e32 v132, v3, v132, vcc
	v_pk_mul_f32 v[134:135], v[132:133], v[134:135] op_sel_hi:[0,1]
	v_mul_f32_e32 v3, 0xbfb8aa3b, v135
	v_pk_mul_f32 v[124:125], v[132:133], v[124:125] op_sel_hi:[0,1]
	v_exp_f32_e32 v3, v3
	v_mul_f32_e32 v128, 0xbfb8aa3b, v125
	v_exp_f32_e32 v128, v128
	v_readlane_b32 s9, v255, 19
	v_add_f32_e32 v3, 1.0, v3
	v_rcp_f32_e32 v129, v3
	v_add_f32_e32 v3, 1.0, v128
	v_rcp_f32_e32 v128, v3
	v_lshl_add_u32 v1, s20, 8, v219
	v_mul_f32_e32 v129, v135, v129
	v_mul_f32_e32 v133, v134, v129
	v_mul_f32_e32 v125, v125, v128
	v_mov_b32_e32 v128, v130
	v_mov_b32_e32 v129, v126
	v_pk_mul_f32 v[128:129], v[132:133], v[128:129] op_sel_hi:[0,1]
	v_mul_f32_e32 v126, 0xbfb8aa3b, v129
	v_exp_f32_e32 v130, v126
	v_mov_b32_e32 v126, v131
	v_pk_mul_f32 v[126:127], v[132:133], v[126:127] op_sel_hi:[0,1]
	v_mul_f32_e32 v131, 0xbfb8aa3b, v127
	v_exp_f32_e32 v131, v131
	v_mul_f32_e32 v134, v124, v125
	v_add_f32_e32 v124, 1.0, v130
	v_rcp_f32_e32 v130, v124
	v_add_f32_e32 v124, 1.0, v131
	v_rcp_f32_e32 v131, v124
	v_mov_b32_e32 v124, v120
	v_mov_b32_e32 v125, v116
	v_pk_mul_f32 v[124:125], v[132:133], v[124:125] op_sel_hi:[0,1]
	v_mul_f32_e32 v116, 0xbfb8aa3b, v125
	v_exp_f32_e32 v116, v116
	v_mul_f32_e32 v120, v129, v130
	v_mul_f32_e32 v128, v128, v120
	v_mul_f32_e32 v120, v127, v131
	v_add_f32_e32 v116, 1.0, v116
	v_rcp_f32_e32 v127, v116
	v_mov_b32_e32 v116, v121
	v_pk_mul_f32 v[116:117], v[132:133], v[116:117] op_sel_hi:[0,1]
	v_mul_f32_e32 v121, 0xbfb8aa3b, v117
	v_exp_f32_e32 v121, v121
	v_mul_f32_e32 v126, v126, v120
	v_mul_f32_e32 v120, v125, v127
	v_mul_f32_e32 v124, v124, v120
	v_add_f32_e32 v120, 1.0, v121
	v_rcp_f32_e32 v125, v120
	v_mov_b32_e32 v120, v122
	v_mov_b32_e32 v121, v118
	v_pk_mul_f32 v[120:121], v[132:133], v[120:121] op_sel_hi:[0,1]
	v_mul_f32_e32 v118, 0xbfb8aa3b, v121
	v_exp_f32_e32 v122, v118
	v_mov_b32_e32 v118, v123
	v_pk_mul_f32 v[118:119], v[132:133], v[118:119] op_sel_hi:[0,1]
	v_mul_f32_e32 v123, 0xbfb8aa3b, v119
	v_exp_f32_e32 v123, v123
	v_add_f32_e32 v122, 1.0, v122
	v_rcp_f32_e32 v122, v122
	v_mul_f32_e32 v117, v117, v125
	v_add_f32_e32 v123, 1.0, v123
	v_rcp_f32_e32 v123, v123
	v_mul_f32_e32 v116, v116, v117
	v_mul_f32_e32 v117, v121, v122
	v_fmamk_f32 v122, v232, 0x3a800000, v226
	v_mul_f32_e32 v119, v119, v123
	v_mul_f32_e32 v123, 0x4b800000, v122
	v_cmp_gt_f32_e32 vcc, s50, v122
	v_mul_f32_e32 v117, v120, v117
	v_mul_f32_e32 v121, v118, v119
	v_cndmask_b32_e32 v122, v122, v123, vcc
	v_cvt_pk_bf16_f32 v118, v133, v134
	v_cvt_pk_bf16_f32 v119, v128, v126
	v_cvt_pk_bf16_f32 v120, v124, v116
	v_rsq_f32_e32 v124, v122
	v_mov_b32_e32 v126, v112
	v_mov_b32_e32 v127, v108
	v_ashrrev_i32_e32 v3, 31, v2
	v_mul_f32_e32 v125, 0x45800000, v124
	v_cndmask_b32_e32 v124, v124, v125, vcc
	v_pk_mul_f32 v[126:127], v[124:125], v[126:127] op_sel_hi:[0,1]
	v_mul_f32_e32 v108, 0xbfb8aa3b, v127
	v_exp_f32_e32 v125, v108
	v_mov_b32_e32 v108, v113
	v_cvt_pk_bf16_f32 v121, v117, v121
	v_mov_b64_e32 v[116:117], s[8:9]
	v_pk_mul_f32 v[108:109], v[124:125], v[108:109] op_sel_hi:[0,1]
	v_mad_i64_i32 v[122:123], s[8:9], v1, s51, v[116:117]
	v_lshlrev_b64 v[2:3], 1, v[2:3]
	v_mul_f32_e32 v112, 0xbfb8aa3b, v109
	v_exp_f32_e32 v128, v112
	v_lshl_add_u64 v[112:113], v[122:123], 0, v[2:3]
	v_add_f32_e32 v122, 1.0, v125
	v_rcp_f32_e32 v122, v122
	global_store_dwordx4 v[112:113], v[118:121], off
	v_mov_b32_e32 v113, v110
	v_add_f32_e32 v123, 1.0, v128
	v_mul_f32_e32 v112, v127, v122
	v_mul_f32_e32 v118, v126, v112
	v_mov_b32_e32 v112, v114
	v_pk_mul_f32 v[112:113], v[124:125], v[112:113] op_sel_hi:[0,1]
	v_mul_f32_e32 v110, 0xbfb8aa3b, v113
	v_exp_f32_e32 v114, v110
	v_mov_b32_e32 v110, v115
	v_rcp_f32_e32 v123, v123
	v_pk_mul_f32 v[110:111], v[124:125], v[110:111] op_sel_hi:[0,1]
	v_mul_f32_e32 v115, 0xbfb8aa3b, v111
	v_exp_f32_e32 v115, v115
	v_mul_f32_e32 v109, v109, v123
	v_mul_f32_e32 v119, v108, v109
	v_add_f32_e32 v108, 1.0, v114
	v_rcp_f32_e32 v114, v108
	v_add_f32_e32 v108, 1.0, v115
	v_rcp_f32_e32 v115, v108
	v_mov_b32_e32 v108, v104
	v_mov_b32_e32 v109, v100
	v_pk_mul_f32 v[108:109], v[124:125], v[108:109] op_sel_hi:[0,1]
	v_mul_f32_e32 v100, 0xbfb8aa3b, v109
	v_exp_f32_e32 v100, v100
	v_mul_f32_e32 v104, v113, v114
	v_mul_f32_e32 v112, v112, v104
	v_mul_f32_e32 v104, v111, v115
	v_add_f32_e32 v100, 1.0, v100
	v_rcp_f32_e32 v111, v100
	v_mov_b32_e32 v100, v105
	v_pk_mul_f32 v[100:101], v[124:125], v[100:101] op_sel_hi:[0,1]
	v_mul_f32_e32 v105, 0xbfb8aa3b, v101
	v_exp_f32_e32 v105, v105
	v_mul_f32_e32 v110, v110, v104
	v_mul_f32_e32 v104, v109, v111
	v_mul_f32_e32 v108, v108, v104
	v_add_f32_e32 v104, 1.0, v105
	v_rcp_f32_e32 v109, v104
	v_mov_b32_e32 v104, v106
	v_mov_b32_e32 v105, v102
	v_pk_mul_f32 v[104:105], v[124:125], v[104:105] op_sel_hi:[0,1]
	v_mul_f32_e32 v102, 0xbfb8aa3b, v105
	v_exp_f32_e32 v106, v102
	v_mov_b32_e32 v102, v107
	v_pk_mul_f32 v[102:103], v[124:125], v[102:103] op_sel_hi:[0,1]
	v_mul_f32_e32 v107, 0xbfb8aa3b, v103
	v_exp_f32_e32 v107, v107
	v_add_f32_e32 v106, 1.0, v106
	v_rcp_f32_e32 v106, v106
	v_mul_f32_e32 v101, v101, v109
	v_add_f32_e32 v107, 1.0, v107
	v_rcp_f32_e32 v107, v107
	v_mul_f32_e32 v109, v100, v101
	v_mul_f32_e32 v100, v105, v106
	v_fmamk_f32 v106, v231, 0x3a800000, v226
	v_mul_f32_e32 v104, v104, v100
	v_mul_f32_e32 v100, v103, v107
	v_mul_f32_e32 v107, 0x4b800000, v106
	v_cmp_gt_f32_e32 vcc, s50, v106
	v_mul_f32_e32 v103, v102, v100
	v_cvt_pk_bf16_f32 v100, v118, v119
	v_cvt_pk_bf16_f32 v101, v112, v110
	v_cvt_pk_bf16_f32 v102, v108, v109
	v_mov_b32_e32 v108, v96
	v_cndmask_b32_e32 v106, v106, v107, vcc
	v_rsq_f32_e32 v106, v106
	v_mov_b32_e32 v109, v92
	v_or_b32_e32 v105, 16, v1
	v_cvt_pk_bf16_f32 v103, v104, v103
	v_mul_f32_e32 v107, 0x45800000, v106
	v_cndmask_b32_e32 v106, v106, v107, vcc
	v_pk_mul_f32 v[108:109], v[106:107], v[108:109] op_sel_hi:[0,1]
	v_mul_f32_e32 v92, 0xbfb8aa3b, v109
	v_exp_f32_e32 v107, v92
	v_mov_b32_e32 v92, v97
	v_mad_i64_i32 v[104:105], s[8:9], v105, s51, v[116:117]
	v_pk_mul_f32 v[92:93], v[106:107], v[92:93] op_sel_hi:[0,1]
	v_mul_f32_e32 v96, 0xbfb8aa3b, v93
	v_exp_f32_e32 v110, v96
	v_lshl_add_u64 v[96:97], v[104:105], 0, v[2:3]
	v_add_f32_e32 v104, 1.0, v107
	v_rcp_f32_e32 v104, v104
	global_store_dwordx4 v[96:97], v[100:103], off
	v_mov_b32_e32 v97, v94
	v_add_f32_e32 v105, 1.0, v110
	v_mul_f32_e32 v96, v109, v104
	v_mul_f32_e32 v100, v108, v96
	v_mov_b32_e32 v96, v98
	v_pk_mul_f32 v[96:97], v[106:107], v[96:97] op_sel_hi:[0,1]
	v_mul_f32_e32 v94, 0xbfb8aa3b, v97
	v_exp_f32_e32 v98, v94
	v_mov_b32_e32 v94, v99
	v_rcp_f32_e32 v105, v105
	v_pk_mul_f32 v[94:95], v[106:107], v[94:95] op_sel_hi:[0,1]
	v_mul_f32_e32 v99, 0xbfb8aa3b, v95
	v_exp_f32_e32 v99, v99
	v_mul_f32_e32 v93, v93, v105
	v_mul_f32_e32 v101, v92, v93
	v_add_f32_e32 v92, 1.0, v98
	v_rcp_f32_e32 v98, v92
	v_add_f32_e32 v92, 1.0, v99
	v_rcp_f32_e32 v99, v92
	v_mov_b32_e32 v92, v88
	v_mov_b32_e32 v93, v84
	v_pk_mul_f32 v[92:93], v[106:107], v[92:93] op_sel_hi:[0,1]
	v_mul_f32_e32 v84, 0xbfb8aa3b, v93
	v_exp_f32_e32 v84, v84
	v_mul_f32_e32 v88, v97, v98
	v_mul_f32_e32 v96, v96, v88
	v_mul_f32_e32 v88, v95, v99
	v_add_f32_e32 v84, 1.0, v84
	v_rcp_f32_e32 v95, v84
	v_mov_b32_e32 v84, v89
	v_pk_mul_f32 v[84:85], v[106:107], v[84:85] op_sel_hi:[0,1]
	v_mul_f32_e32 v89, 0xbfb8aa3b, v85
	v_exp_f32_e32 v89, v89
	v_mul_f32_e32 v94, v94, v88
	v_mul_f32_e32 v88, v93, v95
	v_mul_f32_e32 v92, v92, v88
	v_add_f32_e32 v88, 1.0, v89
	v_rcp_f32_e32 v93, v88
	v_mov_b32_e32 v88, v90
	v_mov_b32_e32 v89, v86
	v_pk_mul_f32 v[88:89], v[106:107], v[88:89] op_sel_hi:[0,1]
	v_mul_f32_e32 v86, 0xbfb8aa3b, v89
	v_exp_f32_e32 v90, v86
	v_mov_b32_e32 v86, v91
	v_pk_mul_f32 v[86:87], v[106:107], v[86:87] op_sel_hi:[0,1]
	v_mul_f32_e32 v91, 0xbfb8aa3b, v87
	v_exp_f32_e32 v91, v91
	v_add_f32_e32 v90, 1.0, v90
	v_rcp_f32_e32 v90, v90
	v_mul_f32_e32 v85, v85, v93
	v_add_f32_e32 v91, 1.0, v91
	v_rcp_f32_e32 v91, v91
	v_mul_f32_e32 v93, v84, v85
	v_mul_f32_e32 v84, v89, v90
	v_fmamk_f32 v90, v230, 0x3a800000, v226
	v_mul_f32_e32 v88, v88, v84
	v_mul_f32_e32 v84, v87, v91
	v_mul_f32_e32 v91, 0x4b800000, v90
	v_cmp_gt_f32_e32 vcc, s50, v90
	v_mul_f32_e32 v87, v86, v84
	v_cvt_pk_bf16_f32 v84, v100, v101
	v_cvt_pk_bf16_f32 v85, v96, v94
	v_cvt_pk_bf16_f32 v86, v92, v93
	v_mov_b32_e32 v92, v80
	v_cndmask_b32_e32 v90, v90, v91, vcc
	v_rsq_f32_e32 v90, v90
	v_mov_b32_e32 v93, v76
	v_or_b32_e32 v89, 32, v1
	v_cvt_pk_bf16_f32 v87, v88, v87
	v_mul_f32_e32 v91, 0x45800000, v90
	v_cndmask_b32_e32 v90, v90, v91, vcc
	v_pk_mul_f32 v[92:93], v[90:91], v[92:93] op_sel_hi:[0,1]
	v_mul_f32_e32 v76, 0xbfb8aa3b, v93
	v_exp_f32_e32 v91, v76
	v_mov_b32_e32 v76, v81
	v_mad_i64_i32 v[88:89], s[8:9], v89, s51, v[116:117]
	v_pk_mul_f32 v[76:77], v[90:91], v[76:77] op_sel_hi:[0,1]
	v_mul_f32_e32 v80, 0xbfb8aa3b, v77
	v_exp_f32_e32 v94, v80
	v_lshl_add_u64 v[80:81], v[88:89], 0, v[2:3]
	v_add_f32_e32 v88, 1.0, v91
	v_rcp_f32_e32 v88, v88
	global_store_dwordx4 v[80:81], v[84:87], off
	v_mov_b32_e32 v81, v78
	v_add_f32_e32 v89, 1.0, v94
	v_mul_f32_e32 v80, v93, v88
	v_mul_f32_e32 v84, v92, v80
	v_mov_b32_e32 v80, v82
	v_pk_mul_f32 v[80:81], v[90:91], v[80:81] op_sel_hi:[0,1]
	v_mul_f32_e32 v78, 0xbfb8aa3b, v81
	v_exp_f32_e32 v82, v78
	v_mov_b32_e32 v78, v83
	v_rcp_f32_e32 v89, v89
	v_pk_mul_f32 v[78:79], v[90:91], v[78:79] op_sel_hi:[0,1]
	v_mul_f32_e32 v83, 0xbfb8aa3b, v79
	v_exp_f32_e32 v83, v83
	v_mul_f32_e32 v77, v77, v89
	v_mul_f32_e32 v85, v76, v77
	v_add_f32_e32 v76, 1.0, v82
	v_rcp_f32_e32 v82, v76
	v_add_f32_e32 v76, 1.0, v83
	v_rcp_f32_e32 v83, v76
	v_mov_b32_e32 v76, v68
	v_mov_b32_e32 v77, v72
	v_pk_mul_f32 v[76:77], v[90:91], v[76:77] op_sel_hi:[0,1]
	v_mul_f32_e32 v68, 0xbfb8aa3b, v77
	v_exp_f32_e32 v68, v68
	v_mul_f32_e32 v72, v81, v82
	v_mul_f32_e32 v80, v80, v72
	v_mov_b32_e32 v72, v69
	v_add_f32_e32 v68, 1.0, v68
	v_rcp_f32_e32 v81, v68
	v_pk_mul_f32 v[68:69], v[90:91], v[72:73] op_sel_hi:[0,1]
	v_mul_f32_e32 v72, 0xbfb8aa3b, v69
	v_exp_f32_e32 v72, v72
	v_mul_f32_e32 v73, v77, v81
	v_mul_f32_e32 v76, v76, v73
	v_mov_b32_e32 v73, v74
	v_add_f32_e32 v72, 1.0, v72
	v_rcp_f32_e32 v77, v72
	v_mov_b32_e32 v72, v70
	v_pk_mul_f32 v[72:73], v[90:91], v[72:73] op_sel_hi:[0,1]
	v_mul_f32_e32 v79, v79, v83
	v_mul_f32_e32 v70, 0xbfb8aa3b, v73
	v_mov_b32_e32 v74, v71
	v_mul_f32_e32 v78, v78, v79
	v_exp_f32_e32 v79, v70
	v_pk_mul_f32 v[70:71], v[90:91], v[74:75] op_sel_hi:[0,1]
	v_mul_f32_e32 v74, 0xbfb8aa3b, v71
	v_exp_f32_e32 v74, v74
	v_add_f32_e32 v75, 1.0, v79
	v_rcp_f32_e32 v75, v75
	v_mul_f32_e32 v69, v69, v77
	v_add_f32_e32 v74, 1.0, v74
	v_rcp_f32_e32 v74, v74
	v_mul_f32_e32 v77, v68, v69
	v_mul_f32_e32 v68, v73, v75
	v_mul_f32_e32 v72, v72, v68
	v_mul_f32_e32 v68, v71, v74
	v_mul_f32_e32 v71, v70, v68
	v_or_b32_e32 v73, 48, v1
	v_cvt_pk_bf16_f32 v68, v84, v85
	v_cvt_pk_bf16_f32 v69, v80, v78
	v_cvt_pk_bf16_f32 v70, v76, v77
	v_cvt_pk_bf16_f32 v71, v72, v71
	v_mad_i64_i32 v[72:73], s[8:9], v73, s51, v[116:117]
	s_cmp_eq_u32 s20, 64
	v_lshl_add_u64 v[72:73], v[72:73], 0, v[2:3]
	global_store_dwordx4 v[72:73], v[68:71], off
	s_cbranch_scc1 .LBB0_4163
	s_nop 0
	v_fmamk_f32 v68, v229, 0x3a800000, v226
	v_mul_f32_e32 v69, 0x4b800000, v68
	v_cmp_gt_f32_e32 vcc, s50, v68
	v_readlane_b32 s8, v255, 18
	v_readlane_b32 s9, v255, 19
	v_cndmask_b32_e32 v68, v68, v69, vcc
	v_rsq_f32_e32 v70, v68
	v_mov_b32_e32 v69, v60
	v_mov_b32_e32 v68, v64
	v_add_u32_e32 v71, 0x80, v1
	v_mul_f32_e32 v60, 0x45800000, v70
	v_cndmask_b32_e32 v64, v70, v60, vcc
	v_pk_mul_f32 v[68:69], v[64:65], v[68:69] op_sel_hi:[0,1]
	v_mul_f32_e32 v60, 0xbfb8aa3b, v69
	v_exp_f32_e32 v70, v60
	v_mov_b32_e32 v60, v65
	v_pk_mul_f32 v[60:61], v[64:65], v[60:61] op_sel_hi:[0,1]
	v_mul_f32_e32 v65, 0xbfb8aa3b, v61
	v_exp_f32_e32 v65, v65
	v_add_f32_e32 v70, 1.0, v70
	v_rcp_f32_e32 v70, v70
	v_add_f32_e32 v65, 1.0, v65
	v_rcp_f32_e32 v65, v65
	v_mul_f32_e32 v69, v69, v70
	v_mul_f32_e32 v70, v68, v69
	v_mov_b32_e32 v68, v66
	v_mov_b32_e32 v69, v62
	v_pk_mul_f32 v[68:69], v[64:65], v[68:69] op_sel_hi:[0,1]
	v_mul_f32_e32 v62, 0xbfb8aa3b, v69
	v_mul_f32_e32 v61, v61, v65
	v_exp_f32_e32 v65, v62
	v_mov_b32_e32 v62, v67
	v_mul_f32_e32 v67, v60, v61
	v_mov_b32_e32 v61, v52
	v_pk_mul_f32 v[62:63], v[64:65], v[62:63] op_sel_hi:[0,1]
	v_mul_f32_e32 v66, 0xbfb8aa3b, v63
	v_exp_f32_e32 v66, v66
	v_add_f32_e32 v60, 1.0, v65
	v_rcp_f32_e32 v65, v60
	v_add_f32_e32 v60, 1.0, v66
	v_rcp_f32_e32 v66, v60
	v_mov_b32_e32 v60, v56
	v_pk_mul_f32 v[60:61], v[64:65], v[60:61] op_sel_hi:[0,1]
	v_mul_f32_e32 v52, 0xbfb8aa3b, v61
	v_exp_f32_e32 v52, v52
	v_mul_f32_e32 v56, v69, v65
	v_mul_f32_e32 v65, v68, v56
	v_mul_f32_e32 v56, v63, v66
	v_add_f32_e32 v52, 1.0, v52
	v_rcp_f32_e32 v63, v52
	v_mov_b32_e32 v52, v57
	v_pk_mul_f32 v[52:53], v[64:65], v[52:53] op_sel_hi:[0,1]
	v_mul_f32_e32 v57, 0xbfb8aa3b, v53
	v_exp_f32_e32 v57, v57
	v_mul_f32_e32 v62, v62, v56
	v_mul_f32_e32 v56, v61, v63
	v_mul_f32_e32 v60, v60, v56
	v_add_f32_e32 v56, 1.0, v57
	v_rcp_f32_e32 v61, v56
	v_mov_b32_e32 v56, v58
	v_mov_b32_e32 v57, v54
	v_pk_mul_f32 v[56:57], v[64:65], v[56:57] op_sel_hi:[0,1]
	v_mul_f32_e32 v54, 0xbfb8aa3b, v57
	v_exp_f32_e32 v58, v54
	v_mov_b32_e32 v54, v59
	v_pk_mul_f32 v[54:55], v[64:65], v[54:55] op_sel_hi:[0,1]
	v_mul_f32_e32 v59, 0xbfb8aa3b, v55
	v_exp_f32_e32 v59, v59
	v_add_f32_e32 v58, 1.0, v58
	v_rcp_f32_e32 v58, v58
	v_mul_f32_e32 v53, v53, v61
	v_add_f32_e32 v59, 1.0, v59
	v_rcp_f32_e32 v59, v59
	v_mul_f32_e32 v52, v52, v53
	v_mul_f32_e32 v53, v57, v58
	v_mul_f32_e32 v53, v56, v53
	v_mul_f32_e32 v55, v55, v59
	v_mul_f32_e32 v57, v54, v55
	v_cvt_pk_bf16_f32 v54, v70, v67
	v_cvt_pk_bf16_f32 v55, v65, v62
	v_cvt_pk_bf16_f32 v56, v60, v52
	v_fmamk_f32 v52, v228, 0x3a800000, v226
	v_cvt_pk_bf16_f32 v57, v53, v57
	v_mul_f32_e32 v53, 0x4b800000, v52
	v_cmp_gt_f32_e32 vcc, s50, v52
	v_mov_b32_e32 v62, v48
	v_mov_b32_e32 v63, v44
	v_cndmask_b32_e32 v52, v52, v53, vcc
	v_rsq_f32_e32 v60, v52
	v_mov_b64_e32 v[52:53], s[8:9]
	v_mad_i64_i32 v[58:59], s[8:9], v71, s51, v[52:53]
	v_mul_f32_e32 v61, 0x45800000, v60
	v_cndmask_b32_e32 v60, v60, v61, vcc
	v_pk_mul_f32 v[62:63], v[60:61], v[62:63] op_sel_hi:[0,1]
	v_mul_f32_e32 v44, 0xbfb8aa3b, v63
	v_exp_f32_e32 v61, v44
	v_mov_b32_e32 v44, v49
	v_pk_mul_f32 v[44:45], v[60:61], v[44:45] op_sel_hi:[0,1]
	v_mul_f32_e32 v48, 0xbfb8aa3b, v45
	v_exp_f32_e32 v64, v48
	v_lshl_add_u64 v[48:49], v[58:59], 0, v[2:3]
	v_add_f32_e32 v58, 1.0, v61
	v_rcp_f32_e32 v58, v58
	global_store_dwordx4 v[48:49], v[54:57], off
	v_mov_b32_e32 v49, v46
	v_add_f32_e32 v59, 1.0, v64
	v_mul_f32_e32 v48, v63, v58
	v_mul_f32_e32 v54, v62, v48
	v_mov_b32_e32 v48, v50
	v_pk_mul_f32 v[48:49], v[60:61], v[48:49] op_sel_hi:[0,1]
	v_mul_f32_e32 v46, 0xbfb8aa3b, v49
	v_exp_f32_e32 v50, v46
	v_mov_b32_e32 v46, v51
	v_rcp_f32_e32 v59, v59
	v_pk_mul_f32 v[46:47], v[60:61], v[46:47] op_sel_hi:[0,1]
	v_mul_f32_e32 v51, 0xbfb8aa3b, v47
	v_exp_f32_e32 v51, v51
	v_mul_f32_e32 v45, v45, v59
	v_mul_f32_e32 v55, v44, v45
	v_add_f32_e32 v44, 1.0, v50
	v_rcp_f32_e32 v50, v44
	v_add_f32_e32 v44, 1.0, v51
	v_rcp_f32_e32 v51, v44
	v_mov_b32_e32 v44, v40
	v_mov_b32_e32 v45, v36
	v_pk_mul_f32 v[44:45], v[60:61], v[44:45] op_sel_hi:[0,1]
	v_mul_f32_e32 v36, 0xbfb8aa3b, v45
	v_exp_f32_e32 v36, v36
	v_mul_f32_e32 v40, v49, v50
	v_mul_f32_e32 v48, v48, v40
	v_mul_f32_e32 v40, v47, v51
	v_add_f32_e32 v36, 1.0, v36
	v_rcp_f32_e32 v47, v36
	v_mov_b32_e32 v36, v41
	v_pk_mul_f32 v[36:37], v[60:61], v[36:37] op_sel_hi:[0,1]
	v_mul_f32_e32 v41, 0xbfb8aa3b, v37
	v_exp_f32_e32 v41, v41
	v_mul_f32_e32 v46, v46, v40
	v_mul_f32_e32 v40, v45, v47
	v_mul_f32_e32 v44, v44, v40
	v_add_f32_e32 v40, 1.0, v41
	v_rcp_f32_e32 v45, v40
	v_mov_b32_e32 v40, v42
	v_mov_b32_e32 v41, v38
	v_pk_mul_f32 v[40:41], v[60:61], v[40:41] op_sel_hi:[0,1]
	v_mul_f32_e32 v38, 0xbfb8aa3b, v41
	v_exp_f32_e32 v42, v38
	v_mov_b32_e32 v38, v43
	v_pk_mul_f32 v[38:39], v[60:61], v[38:39] op_sel_hi:[0,1]
	v_mul_f32_e32 v43, 0xbfb8aa3b, v39
	v_exp_f32_e32 v43, v43
	v_add_f32_e32 v42, 1.0, v42
	v_rcp_f32_e32 v42, v42
	v_mul_f32_e32 v37, v37, v45
	v_add_f32_e32 v43, 1.0, v43
	v_rcp_f32_e32 v43, v43
	v_mul_f32_e32 v45, v36, v37
	v_mul_f32_e32 v36, v41, v42
	v_fmamk_f32 v42, v227, 0x3a800000, v226
	v_mul_f32_e32 v40, v40, v36
	v_mul_f32_e32 v36, v39, v43
	v_mul_f32_e32 v43, 0x4b800000, v42
	v_cmp_gt_f32_e32 vcc, s50, v42
	v_mul_f32_e32 v39, v38, v36
	v_cvt_pk_bf16_f32 v36, v54, v55
	v_cvt_pk_bf16_f32 v37, v48, v46
	v_cvt_pk_bf16_f32 v38, v44, v45
	v_mov_b32_e32 v44, v32
	v_cndmask_b32_e32 v42, v42, v43, vcc
	v_rsq_f32_e32 v42, v42
	v_mov_b32_e32 v45, v28
	v_add_u32_e32 v41, 0x90, v1
	v_cvt_pk_bf16_f32 v39, v40, v39
	v_mul_f32_e32 v43, 0x45800000, v42
	v_cndmask_b32_e32 v42, v42, v43, vcc
	v_pk_mul_f32 v[44:45], v[42:43], v[44:45] op_sel_hi:[0,1]
	v_mul_f32_e32 v28, 0xbfb8aa3b, v45
	v_exp_f32_e32 v43, v28
	v_mov_b32_e32 v28, v33
	v_mad_i64_i32 v[40:41], s[8:9], v41, s51, v[52:53]
	v_pk_mul_f32 v[28:29], v[42:43], v[28:29] op_sel_hi:[0,1]
	v_mul_f32_e32 v32, 0xbfb8aa3b, v29
	v_exp_f32_e32 v46, v32
	v_lshl_add_u64 v[32:33], v[40:41], 0, v[2:3]
	v_add_f32_e32 v40, 1.0, v43
	v_rcp_f32_e32 v40, v40
	global_store_dwordx4 v[32:33], v[36:39], off
	v_mov_b32_e32 v33, v30
	v_add_f32_e32 v41, 1.0, v46
	v_mul_f32_e32 v32, v45, v40
	v_mul_f32_e32 v36, v44, v32
	v_mov_b32_e32 v32, v34
	v_pk_mul_f32 v[32:33], v[42:43], v[32:33] op_sel_hi:[0,1]
	v_mul_f32_e32 v30, 0xbfb8aa3b, v33
	v_exp_f32_e32 v34, v30
	v_mov_b32_e32 v30, v35
	v_rcp_f32_e32 v41, v41
	v_pk_mul_f32 v[30:31], v[42:43], v[30:31] op_sel_hi:[0,1]
	v_mul_f32_e32 v35, 0xbfb8aa3b, v31
	v_exp_f32_e32 v35, v35
	v_mul_f32_e32 v29, v29, v41
	v_mul_f32_e32 v37, v28, v29
	v_add_f32_e32 v28, 1.0, v34
	v_rcp_f32_e32 v34, v28
	v_add_f32_e32 v28, 1.0, v35
	v_rcp_f32_e32 v35, v28
	v_mov_b32_e32 v28, v24
	v_mov_b32_e32 v29, v20
	v_pk_mul_f32 v[28:29], v[42:43], v[28:29] op_sel_hi:[0,1]
	v_mul_f32_e32 v20, 0xbfb8aa3b, v29
	v_exp_f32_e32 v20, v20
	v_mul_f32_e32 v24, v33, v34
	v_mul_f32_e32 v32, v32, v24
	v_mul_f32_e32 v24, v31, v35
	v_add_f32_e32 v20, 1.0, v20
	v_rcp_f32_e32 v31, v20
	v_mov_b32_e32 v20, v25
	v_pk_mul_f32 v[20:21], v[42:43], v[20:21] op_sel_hi:[0,1]
	v_mul_f32_e32 v25, 0xbfb8aa3b, v21
	v_exp_f32_e32 v25, v25
	v_mul_f32_e32 v30, v30, v24
	v_mul_f32_e32 v24, v29, v31
	v_mul_f32_e32 v28, v28, v24
	v_add_f32_e32 v24, 1.0, v25
	v_rcp_f32_e32 v29, v24
	v_mov_b32_e32 v24, v26
	v_mov_b32_e32 v25, v22
	v_pk_mul_f32 v[24:25], v[42:43], v[24:25] op_sel_hi:[0,1]
	v_mul_f32_e32 v22, 0xbfb8aa3b, v25
	v_exp_f32_e32 v26, v22
	v_mov_b32_e32 v22, v27
	v_pk_mul_f32 v[22:23], v[42:43], v[22:23] op_sel_hi:[0,1]
	v_mul_f32_e32 v27, 0xbfb8aa3b, v23
	v_exp_f32_e32 v27, v27
	v_add_f32_e32 v26, 1.0, v26
	v_rcp_f32_e32 v26, v26
	v_mul_f32_e32 v21, v21, v29
	v_add_f32_e32 v27, 1.0, v27
	v_rcp_f32_e32 v27, v27
	v_mul_f32_e32 v29, v20, v21
	v_mul_f32_e32 v20, v25, v26
	v_fmamk_f32 v26, v218, 0x3a800000, v226
	v_mul_f32_e32 v24, v24, v20
	v_mul_f32_e32 v20, v23, v27
	v_mul_f32_e32 v27, 0x4b800000, v26
	v_cmp_gt_f32_e32 vcc, s50, v26
	v_mul_f32_e32 v23, v22, v20
	v_cvt_pk_bf16_f32 v20, v36, v37
	v_cvt_pk_bf16_f32 v21, v32, v30
	v_cvt_pk_bf16_f32 v22, v28, v29
	v_mov_b32_e32 v28, v16
	v_cndmask_b32_e32 v26, v26, v27, vcc
	v_rsq_f32_e32 v26, v26
	v_mov_b32_e32 v29, v12
	v_add_u32_e32 v25, 0xa0, v1
	v_cvt_pk_bf16_f32 v23, v24, v23
	v_mul_f32_e32 v27, 0x45800000, v26
	v_cndmask_b32_e32 v26, v26, v27, vcc
	v_pk_mul_f32 v[28:29], v[26:27], v[28:29] op_sel_hi:[0,1]
	v_mul_f32_e32 v12, 0xbfb8aa3b, v29
	v_exp_f32_e32 v27, v12
	v_mov_b32_e32 v12, v17
	v_mad_i64_i32 v[24:25], s[8:9], v25, s51, v[52:53]
	v_pk_mul_f32 v[12:13], v[26:27], v[12:13] op_sel_hi:[0,1]
	v_mul_f32_e32 v16, 0xbfb8aa3b, v13
	v_exp_f32_e32 v30, v16
	v_lshl_add_u64 v[16:17], v[24:25], 0, v[2:3]
	v_add_f32_e32 v24, 1.0, v27
	v_rcp_f32_e32 v24, v24
	global_store_dwordx4 v[16:17], v[20:23], off
	v_mov_b32_e32 v17, v14
	v_add_f32_e32 v25, 1.0, v30
	v_mul_f32_e32 v16, v29, v24
	v_mul_f32_e32 v20, v28, v16
	v_mov_b32_e32 v16, v18
	v_pk_mul_f32 v[16:17], v[26:27], v[16:17] op_sel_hi:[0,1]
	v_mul_f32_e32 v14, 0xbfb8aa3b, v17
	v_exp_f32_e32 v18, v14
	v_mov_b32_e32 v14, v19
	v_rcp_f32_e32 v25, v25
	v_pk_mul_f32 v[14:15], v[26:27], v[14:15] op_sel_hi:[0,1]
	v_mul_f32_e32 v19, 0xbfb8aa3b, v15
	v_exp_f32_e32 v19, v19
	v_mul_f32_e32 v13, v13, v25
	v_mul_f32_e32 v21, v12, v13
	v_add_f32_e32 v12, 1.0, v18
	v_rcp_f32_e32 v18, v12
	v_add_f32_e32 v12, 1.0, v19
	v_rcp_f32_e32 v19, v12
	v_mov_b32_e32 v12, v8
	v_mov_b32_e32 v13, v4
	v_pk_mul_f32 v[12:13], v[26:27], v[12:13] op_sel_hi:[0,1]
	v_mul_f32_e32 v4, 0xbfb8aa3b, v13
	v_exp_f32_e32 v4, v4
	v_mul_f32_e32 v8, v17, v18
	v_mul_f32_e32 v16, v16, v8
	v_mul_f32_e32 v8, v15, v19
	v_add_f32_e32 v4, 1.0, v4
	v_rcp_f32_e32 v15, v4
	v_mov_b32_e32 v4, v9
	v_pk_mul_f32 v[4:5], v[26:27], v[4:5] op_sel_hi:[0,1]
	v_mul_f32_e32 v9, 0xbfb8aa3b, v5
	v_exp_f32_e32 v9, v9
	v_mul_f32_e32 v14, v14, v8
	v_mul_f32_e32 v8, v13, v15
	v_mul_f32_e32 v12, v12, v8
	v_add_f32_e32 v8, 1.0, v9
	v_rcp_f32_e32 v13, v8
	v_mov_b32_e32 v8, v10
	v_mov_b32_e32 v9, v6
	v_pk_mul_f32 v[8:9], v[26:27], v[8:9] op_sel_hi:[0,1]
	v_mul_f32_e32 v6, 0xbfb8aa3b, v9
	v_exp_f32_e32 v10, v6
	v_mov_b32_e32 v6, v11
	v_pk_mul_f32 v[6:7], v[26:27], v[6:7] op_sel_hi:[0,1]
	v_mul_f32_e32 v11, 0xbfb8aa3b, v7
	v_exp_f32_e32 v11, v11
	v_add_f32_e32 v10, 1.0, v10
	v_rcp_f32_e32 v10, v10
	v_mul_f32_e32 v5, v5, v13
	v_add_f32_e32 v11, 1.0, v11
	v_rcp_f32_e32 v11, v11
	v_mul_f32_e32 v13, v4, v5
	v_mul_f32_e32 v4, v9, v10
	v_mul_f32_e32 v8, v8, v4
	v_mul_f32_e32 v4, v7, v11
	v_mul_f32_e32 v7, v6, v4
	v_add_u32_e32 v1, 0xb0, v1
	v_cvt_pk_bf16_f32 v4, v20, v21
	v_cvt_pk_bf16_f32 v5, v16, v14
	v_cvt_pk_bf16_f32 v6, v12, v13
	v_cvt_pk_bf16_f32 v7, v8, v7
	v_mad_i64_i32 v[8:9], s[8:9], v1, s51, v[52:53]
	v_lshl_add_u64 v[2:3], v[8:9], 0, v[2:3]
	global_store_dwordx4 v[2:3], v[4:7], off
